# GEMM loops: per-phase s_setprio flips deleted, one static s_setprio 1 for the second-dispatched half (waves 4-7) before the K-loop, reset after
# speedup vs baseline: 1.0451x; 1.0043x over previous
; __device__ __forceinline__ f32x4 zero4() { float z = 0.f; asm volatile("" : "+v"(z)); return (f32x4){z, z, z, z}; }
; #define G_STAGE(bufoff, gbase) do { _Pragma("unroll") for (int _i = 0; _i < 2; ++_i) \
;     __builtin_amdgcn_global_load_lds((const unsigned*)((const char*)(gbase) + voff[_i]), (GLAS unsigned*)(lds + (bufoff) + ldsw + _i * 8192), 16, 0, 0); } while (0)
; #define G_WAIT_V(n) asm volatile("s_waitcnt vmcnt(" #n ")" ::: "memory")
; __device__ __forceinline__ void gemm_phase(const Params& p, int l, const bf16_t* __restrict__ A, const bf16_t* __restrict__ Bt, int M, int N, int K,
;                            int epi, bf16_t* __restrict__ outp, char* smem, int wvi) {
;     ...
;   for (int i = 0; i < 2; ++i) { int R, C; stage_rc(tidx * 16 + i * 8192, R, C); voff[i] = (unsigned)(R * K + C) * 2u; }
;   const size_t kstep = (size_t)(GBK * 2), hstep = (size_t)GHALF * K * 2, tstep = 2 * hstep;
;   const unsigned ldsw = (unsigned)wid * 1024u;
;   const int aoff = lds_byte(wr * 64 + fr, fq * 8), boff = lds_byte(wc * 32 + fr, fq * 8);
;   constexpr int HTB = GHT * 2;
;     ...
;   const int nM = M / GBM, nN = N / GBM, nwg = nM * nN;
;   auto tile_of = [&](int Lw, int& pm_, int& pn_) {
;     int wgid = Lw;
;     { const int q = nwg / GNXCD, r = nwg % GNXCD, xcd = wgid % GNXCD, off = wgid / GNXCD; wgid = (xcd < r ? xcd * (q + 1) : r * (q + 1) + (xcd - r) * q) + off; }
;     const int nig = GWGM * nN, gid = wgid / nig, fm = gid * GWGM, gsz = min(nM - fm, GWGM);
;     pm_ = fm + ((wgid % nig) % gsz); pn_ = (wgid % nig) / gsz;
;   };
;   int Lw = blockIdx.x;
;   if (Lw < nwg) {
;     int pm, pn; tile_of(Lw, pm, pn);
;     const char* cA = (const char*)A + (size_t)pm * tstep;
;     const char* cB = (const char*)Bt + (size_t)pn * tstep;
;     f32x4 acc[2][2][4][2];
; #pragma unroll
;     for (int a = 0; a < 2; ++a)
; #pragma unroll
;       for (int b = 0; b < 2; ++b)
; #pragma unroll
;         for (int m = 0; m < 4; ++m)
; #pragma unroll
;           for (int n = 0; n < 2; ++n) acc[a][b][m][n] = zero4();
;     bf16x8 At[4][2], B0[2][2], B1[2][2];
;     G_STAGE(G_SB(0, 0), cB); G_STAGE(G_SA(0, 0), cA); G_STAGE(G_SB(0, 1), cB + hstep); G_STAGE(G_SA(0, 1), cA + hstep);
;     if (wr == 1) G_BAR;
;     G_WAIT_V(4); G_BAR;
;     G_STAGE(G_SB(1, 0), cB + kstep); G_STAGE(G_SA(1, 0), cA + kstep); G_STAGE(G_SB(1, 1), cB + hstep + kstep);
;     G_WAIT_V(6); G_BAR;
.LBB0_112:
	s_andn2_b64 vcc, exec, s[2:3]
	s_cbranch_vccnz .LBB0_309
	v_readlane_b32 s0, v244, 21
	v_readlane_b32 s1, v244, 22
	s_and_b64 s[0:1], s[0:1], exec
	s_movk_i32 s0, 0x110
	s_cselect_b32 s16, s0, 0x100
	v_readlane_b32 s0, v248, 9
	s_waitcnt vmcnt(1)
	v_mbcnt_lo_u32_b32 v0, -1, 0
	v_mbcnt_hi_u32_b32 v0, -1, v0
	s_lshl_b32 s17, s16, 2
	v_add_u32_e32 v130, s0, v0
	v_readlane_b32 s0, v248, 0
	s_cmp_ge_i32 s0, s17
	s_cbranch_scc1 .LBB0_127
	v_lshlrev_b32_e32 v0, 4, v130
	v_add_u32_e32 v1, 0x2000, v0
	v_ashrrev_i32_e32 v2, 31, v1
	v_lshrrev_b32_e32 v2, 22, v2
	v_add_u32_e32 v2, v1, v2
	v_ashrrev_i32_e32 v134, 10, v2
	v_mul_i32_i24_e32 v2, 0x400, v134
	v_sub_u32_e32 v1, v1, v2
	v_lshrrev_b32_e32 v2, 4, v1
	v_bitop3_b32 v1, v2, v1, 32 bitop3:0x6c
	v_ashrrev_i32_e32 v2, 31, v1
	v_lshrrev_b32_e32 v2, 26, v2
	v_add_u32_e32 v2, v1, v2
	v_ashrrev_i32_e32 v135, 6, v2
	v_and_b32_e32 v2, 0xc0, v2
	v_sub_u32_e32 v1, v1, v2
	v_ashrrev_i16_sdwa v1, v199, sext(v1) dst_sel:DWORD dst_unused:UNUSED_PAD src0_sel:DWORD src1_sel:BYTE_0
	v_bfe_i32 v139, v1, 0, 16
	v_bfe_i32 v1, v130, 27, 1
	v_lshrrev_b32_e32 v1, 22, v1
	v_add_u32_e32 v1, v0, v1
	v_and_b32_e32 v1, 0xfffffc00, v1
	v_sub_u32_e32 v0, v0, v1
	v_lshrrev_b32_e32 v1, 4, v0
	v_ashrrev_i32_e32 v2, 31, v130
	v_bitop3_b32 v0, v1, v0, 32 bitop3:0x6c
	v_lshrrev_b32_e32 v2, 26, v2
	v_ashrrev_i32_e32 v1, 31, v0
	v_add_u32_e32 v2, v130, v2
	v_lshrrev_b32_e32 v1, 26, v1
	v_ashrrev_i32_e32 v133, 6, v2
	v_lshlrev_b32_e32 v3, 3, v134
	v_add_u32_e32 v1, v0, v1
	v_lshlrev_b32_e32 v2, 3, v133
	v_and_b32_e32 v3, 0xfffff0, v3
	v_ashrrev_i32_e32 v132, 6, v1
	v_and_b32_e32 v2, 0xfffff0, v2
	v_add_u32_e32 v3, v135, v3
	s_movk_i32 s0, 0xb00
	v_add_u32_e32 v2, v132, v2
	v_mul_lo_u32 v3, v3, s0
	v_mul_lo_u32 v2, v2, s0
	s_lshr_b32 s20, s16, 1
	v_readlane_b32 s0, v248, 35
	s_or_b32 s21, s20, 1
	v_readlane_b32 s1, v248, 36
	s_and_b64 s[0:1], s[0:1], exec
	s_cselect_b32 s0, s21, s20
	v_readlane_b32 s1, v247, 6
	s_mul_i32 s0, s0, s1
	v_readlane_b32 s1, v247, 9
	s_add_i32 s0, s0, s1
	s_ashr_i32 s1, s0, 31
	s_lshr_b32 s1, s1, 27
	s_add_i32 s1, s0, s1
	s_ashr_i32 s2, s1, 5
	v_and_b32_e32 v1, 0xc0, v1
	s_lshl_b32 s2, s2, 3
	s_waitcnt vmcnt(0)
	v_lshlrev_b32_e32 v4, 5, v134
	v_sub_u32_e32 v0, v0, v1
	s_sub_i32 s3, s16, s2
	v_and_b32_e32 v138, 32, v4
	v_ashrrev_i16_sdwa v0, v199, sext(v0) dst_sel:DWORD dst_unused:UNUSED_PAD src0_sel:DWORD src1_sel:BYTE_0
	s_min_i32 s3, s3, 8
	v_or_b32_e32 v3, v3, v138
	v_bfe_i32 v141, v0, 0, 16
	v_cvt_f32_i32_e32 v0, s3
	v_add_lshl_u32 v128, v3, v139, 1
	v_lshlrev_b32_e32 v3, 5, v133
	v_and_b32_e32 v140, 32, v3
	s_andn2_b32 s1, s1, 31
	v_or_b32_e32 v2, v2, v140
	s_sub_i32 s5, s0, s1
	v_add_lshl_u32 v176, v2, v141, 1
	v_cvt_f32_i32_e32 v1, s5
	v_rcp_iflag_f32_e32 v2, v0
	s_xor_b32 s0, s5, s3
	s_ashr_i32 s0, s0, 30
	s_or_b32 s4, s0, 1
	v_mul_f32_e32 v2, v1, v2
	v_trunc_f32_e32 v2, v2
	v_fma_f32 v1, -v2, v0, v1
	v_cvt_i32_f32_e32 v2, v2
	v_cmp_ge_f32_e64 s[0:1], |v1|, |v0|
	s_and_b64 s[0:1], s[0:1], exec
	s_cselect_b32 s0, s4, 0
	v_readfirstlane_b32 s1, v2
	s_add_i32 s4, s1, s0
	s_mul_i32 s0, s4, s3
	s_sub_i32 s0, s5, s0
	s_sext_i32_i8 s0, s0
	s_add_i32 s29, s2, s0
	s_mul_hi_i32 s5, s29, 0x160000
	s_bfe_i64 s[0:1], s[4:5], 0x80000
	v_readlane_b32 s36, v246, 63
	s_mul_i32 s12, s0, 0x160000
	v_readlane_b32 s38, v245, 1
	s_mul_hi_i32 s13, s0, 0x160000
	v_readlane_b32 s39, v245, 2
	s_add_u32 s2, s38, s12
	s_addc_u32 s3, s39, s13
	s_add_i32 s22, s58, 0
	v_mov_b32_e32 v20, v177
	v_mov_b32_e32 v28, v177
	v_mov_b32_e32 v12, v177
	v_mov_b32_e32 v24, v177
	v_mov_b32_e32 v4, v177
	v_mov_b32_e32 v16, v177
	v_mov_b32_e32 v0, v177
	v_mov_b32_e32 v8, v177
	v_mov_b32_e32 v80, v177
	v_mov_b32_e32 v92, v177
	v_mov_b32_e32 v64, v177
	v_mov_b32_e32 v84, v177
	v_mov_b32_e32 v52, v177
	v_mov_b32_e32 v76, v177
	v_mov_b32_e32 v40, v177
	v_mov_b32_e32 v60, v177
	v_mov_b32_e32 v68, v177
	v_mov_b32_e32 v88, v177
	v_mov_b32_e32 v48, v177
	v_mov_b32_e32 v72, v177
	v_mov_b32_e32 v36, v177
	v_mov_b32_e32 v56, v177
	v_mov_b32_e32 v32, v177
	v_mov_b32_e32 v44, v177
	v_mov_b32_e32 v120, v177
	v_mov_b32_e32 v124, v177
	v_mov_b32_e32 v112, v177
	v_mov_b32_e32 v116, v177
	v_mov_b32_e32 v104, v177
	v_mov_b32_e32 v108, v177
	v_mov_b32_e32 v96, v177
	v_mov_b32_e32 v100, v177
	s_add_i32 m0, s22, 0x10000
	s_mul_i32 s6, s29, 0x160000
	v_readlane_b32 s48, v245, 11
	global_load_lds_dwordx4 v176, s[2:3]
	s_add_i32 m0, s22, 0x12000
	v_readlane_b32 s49, v245, 12
	s_add_u32 s10, s48, s6
	global_load_lds_dwordx4 v128, s[2:3]
	s_addc_u32 s11, s49, s5
	s_mov_b32 m0, s22
	s_add_i32 s23, s22, 0x2000
	global_load_lds_dwordx4 v176, s[10:11]
	s_mov_b32 m0, s23
	s_add_u32 s0, s2, 0xb0000
	global_load_lds_dwordx4 v128, s[10:11]
	s_addc_u32 s1, s3, 0
	s_add_i32 m0, s22, 0x14000
	v_readlane_b32 s37, v245, 0
	global_load_lds_dwordx4 v176, s[0:1]
	s_add_i32 m0, s22, 0x16000
	v_readlane_b32 s40, v245, 3
	global_load_lds_dwordx4 v128, s[0:1]
	s_add_u32 s0, s10, 0xb0000
	s_addc_u32 s1, s11, 0
	s_add_i32 s24, s22, 0x4000
	s_mov_b32 m0, s24
	s_add_i32 s25, s22, 0x6000
	global_load_lds_dwordx4 v176, s[0:1]
	s_mov_b32 m0, s25
	v_readlane_b32 s41, v245, 4
	global_load_lds_dwordx4 v128, s[0:1]
	v_readlane_b32 s0, v248, 13
	v_readlane_b32 s1, v248, 14
	s_andn2_b64 vcc, exec, s[0:1]
	v_readlane_b32 s42, v245, 5
	v_readlane_b32 s43, v245, 6
	v_readlane_b32 s44, v245, 7
	v_readlane_b32 s45, v245, 8
	v_readlane_b32 s46, v245, 9
	v_readlane_b32 s47, v245, 10
	v_readlane_b32 s50, v245, 13
	v_readlane_b32 s51, v245, 14
	s_cbranch_vccnz .LBB0_116
	s_barrier
	s_setprio 1

; #define G_STAGE(bufoff, gbase) do { _Pragma("unroll") for (int _i = 0; _i < 2; ++_i) \
;     __builtin_amdgcn_global_load_lds((const unsigned*)((const char*)(gbase) + voff[_i]), (GLAS unsigned*)(lds + (bufoff) + ldsw + _i * 8192), 16, 0, 0); } while (0)
; #define G_LDA(dst, b, h) do { _Pragma("unroll") for (int m = 0; m < 4; ++m) _Pragma("unroll") for (int k = 0; k < 2; ++k) \
;     dst[m][k] = *(const GLAS bf16x8*)(lds + G_SA(b, h) + aoff + m * 2048 + k * 1024); } while (0)
; #define G_LDB(dst, b, h) do { _Pragma("unroll") for (int n = 0; n < 2; ++n) _Pragma("unroll") for (int k = 0; k < 2; ++k) \
;     dst[n][k] = *(const GLAS bf16x8*)(lds + G_SB(b, h) + boff + n * 2048 + k * 1024); } while (0)
; #define G_MMA(ai, bj, At_, Bt_) do { __builtin_amdgcn_s_setprio(1); \
;     _Pragma("unroll") for (int m = 0; m < 4; ++m) _Pragma("unroll") for (int n = 0; n < 2; ++n) _Pragma("unroll") for (int k = 0; k < 2; ++k) \
;       acc[ai][bj][m][n] = __builtin_amdgcn_mfma_f32_16x16x32_bf16(Bt_[n][k], At_[m][k], acc[ai][bj][m][n], 0, 0, 0); \
;     __builtin_amdgcn_s_setprio(0); } while (0)
; #define G_WAIT_V(n) asm volatile("s_waitcnt vmcnt(" #n ")" ::: "memory")
; #define G_WAIT_L(n) asm volatile("s_waitcnt lgkmcnt(" #n ")" ::: "memory")
; #define G_BAR __builtin_amdgcn_s_barrier()
; __device__ __forceinline__ void gemm_phase(const Params& p, int l, const bf16_t* __restrict__ A, const bf16_t* __restrict__ Bt, int M, int N, int K,
;                            int epi, bf16_t* __restrict__ outp, char* smem, int wvi) {
;     ...
;       for (int t = 0; t < nt; t += 2) {
;         const bool lastt = (t == nt - 2);
;         const char* a1 = cA + (size_t)(t + 1) * kstep;
;         const char* a2 = lastt ? nA : cA + (size_t)(t + 2) * kstep; const char* b2 = lastt ? nB : cB + (size_t)(t + 2) * kstep;
;         const char* a3 = a2 + kstep; const char* b3 = b2 + kstep;
;         G_LDB(B0, 0, 0); G_SCHED; G_LDA(At, 0, 0); G_STAGE(G_SA(1, 1), a1 + hstep);
;         G_WAIT_L(8); G_BAR; G_WAIT_L(0); G_MMA(0, 0, At, B0); G_BAR; G_SCHED;
;         G_LDB(B1, 0, 1); G_STAGE(G_SB(0, 0), b2);
;         G_BAR; G_WAIT_L(0); G_MMA(0, 1, At, B1); G_BAR;
;         G_LDA(At, 0, 1); G_STAGE(G_SA(0, 0), a2);
;         G_BAR; G_WAIT_L(0); G_MMA(1, 0, At, B0); G_BAR; G_SCHED;
;         G_STAGE(G_SB(0, 1), b2 + hstep);
;         G_WAIT_V(6); G_BAR; G_MMA(1, 1, At, B1); G_BAR;
.LBB0_121:
	s_add_u32 s2, s10, 0x100
	s_addc_u32 s3, s11, 0
	s_add_i32 s34, 0, 0x10000
	v_add_u32_e32 v139, s34, v137
	ds_read_b128 v[140:143], v139
	ds_read_b128 v[144:147], v139 offset:1024
	ds_read_b128 v[148:151], v139 offset:2048
	ds_read_b128 v[152:155], v139 offset:3072
	s_cmp_eq_u32 s67, 40
	s_cselect_b32 s15, s5, s3
	s_cselect_b32 s14, s4, s2
	s_cselect_b32 s13, s53, s63
	s_cselect_b32 s12, s31, s55
	v_lshl_add_u64 v[190:191], s[10:11], 0, v[132:133]
	s_add_i32 m0, s22, 0xc000
	ds_read_b128 v[156:159], v138
	ds_read_b128 v[160:163], v138 offset:1024
	ds_read_b128 v[164:167], v138 offset:2048
	ds_read_b128 v[168:171], v138 offset:3072
	ds_read_b128 v[172:175], v138 offset:4096
	ds_read_b128 v[182:185], v138 offset:5120
	ds_read_b128 v[186:189], v138 offset:6144
	ds_read_b128 v[214:217], v138 offset:7168
	global_load_lds_dwordx4 v[190:191], off
	v_lshl_add_u64 v[190:191], s[10:11], 0, v[134:135]
	s_add_i32 m0, s22, 0xe000
	s_nop 0
	global_load_lds_dwordx4 v[190:191], off
	s_waitcnt lgkmcnt(8)
	s_barrier
	s_waitcnt lgkmcnt(0)
	s_waitcnt lgkmcnt(0)
	v_mfma_f32_16x16x32_bf16 v[20:23], v[140:143], v[156:159], v[20:23]
	v_mfma_f32_16x16x32_bf16 v[28:31], v[148:151], v[156:159], v[28:31]
	v_mfma_f32_16x16x32_bf16 v[12:15], v[140:143], v[164:167], v[12:15]
	v_mfma_f32_16x16x32_bf16 v[24:27], v[148:151], v[164:167], v[24:27]
	v_mfma_f32_16x16x32_bf16 v[4:7], v[140:143], v[172:175], v[4:7]
	v_mfma_f32_16x16x32_bf16 v[16:19], v[148:151], v[172:175], v[16:19]
	v_mfma_f32_16x16x32_bf16 v[0:3], v[140:143], v[186:189], v[0:3]
	v_mfma_f32_16x16x32_bf16 v[8:11], v[148:151], v[186:189], v[8:11]
	v_mfma_f32_16x16x32_bf16 v[20:23], v[144:147], v[160:163], v[20:23]
	v_mfma_f32_16x16x32_bf16 v[28:31], v[152:155], v[160:163], v[28:31]
	v_mfma_f32_16x16x32_bf16 v[12:15], v[144:147], v[168:171], v[12:15]
	v_mfma_f32_16x16x32_bf16 v[24:27], v[152:155], v[168:171], v[24:27]
	v_mfma_f32_16x16x32_bf16 v[4:7], v[144:147], v[182:185], v[4:7]
	v_mfma_f32_16x16x32_bf16 v[16:19], v[152:155], v[182:185], v[16:19]
	v_mfma_f32_16x16x32_bf16 v[0:3], v[144:147], v[214:217], v[0:3]
	v_mfma_f32_16x16x32_bf16 v[8:11], v[152:155], v[214:217], v[8:11]
	s_barrier
	s_add_i32 s35, 0, 0x14000
	s_add_i32 s10, s34, s58
	v_add_u32_e32 v139, s35, v137
	v_lshl_add_u64 v[190:191], s[12:13], 0, v[176:177]
	s_mov_b32 m0, s10
	ds_read_b128 v[218:221], v139
	ds_read_b128 v[222:225], v139 offset:1024
	ds_read_b128 v[226:229], v139 offset:2048
	ds_read_b128 v[230:233], v139 offset:3072
	global_load_lds_dwordx4 v[190:191], off
	v_lshl_add_u64 v[234:235], s[12:13], 0, v[128:129]
	s_add_i32 m0, s10, 0x2000
	s_nop 0
	global_load_lds_dwordx4 v[234:235], off
	s_barrier
	s_waitcnt lgkmcnt(0)
	s_waitcnt lgkmcnt(0)
	v_mfma_f32_16x16x32_bf16 v[80:83], v[218:221], v[156:159], v[80:83]
	v_mfma_f32_16x16x32_bf16 v[92:95], v[226:229], v[156:159], v[92:95]
	v_mfma_f32_16x16x32_bf16 v[64:67], v[218:221], v[164:167], v[64:67]
	v_mfma_f32_16x16x32_bf16 v[84:87], v[226:229], v[164:167], v[84:87]
	v_mfma_f32_16x16x32_bf16 v[52:55], v[218:221], v[172:175], v[52:55]
	v_mfma_f32_16x16x32_bf16 v[76:79], v[226:229], v[172:175], v[76:79]
	v_mfma_f32_16x16x32_bf16 v[40:43], v[218:221], v[186:189], v[40:43]
	v_mfma_f32_16x16x32_bf16 v[60:63], v[226:229], v[186:189], v[60:63]
	v_mfma_f32_16x16x32_bf16 v[80:83], v[222:225], v[160:163], v[80:83]
	v_mfma_f32_16x16x32_bf16 v[92:95], v[230:233], v[160:163], v[92:95]
	v_mfma_f32_16x16x32_bf16 v[64:67], v[222:225], v[168:171], v[64:67]
	v_mfma_f32_16x16x32_bf16 v[84:87], v[230:233], v[168:171], v[84:87]
	v_mfma_f32_16x16x32_bf16 v[52:55], v[222:225], v[182:185], v[52:55]
	v_mfma_f32_16x16x32_bf16 v[76:79], v[230:233], v[182:185], v[76:79]
	v_mfma_f32_16x16x32_bf16 v[40:43], v[222:225], v[214:217], v[40:43]
	v_mfma_f32_16x16x32_bf16 v[60:63], v[230:233], v[214:217], v[60:63]
	s_mov_b32 m0, s22
	v_lshl_add_u64 v[236:237], s[14:15], 0, v[176:177]
	s_barrier
	ds_read_b128 v[156:159], v138 offset:16384
	ds_read_b128 v[160:163], v138 offset:17408
	ds_read_b128 v[164:167], v138 offset:18432
	ds_read_b128 v[168:171], v138 offset:19456
	ds_read_b128 v[172:175], v138 offset:20480
	ds_read_b128 v[182:185], v138 offset:21504
	ds_read_b128 v[186:189], v138 offset:22528
	ds_read_b128 v[214:217], v138 offset:23552
	global_load_lds_dwordx4 v[236:237], off
	v_lshl_add_u64 v[238:239], s[14:15], 0, v[128:129]
	s_mov_b32 m0, s23
	s_nop 0
	global_load_lds_dwordx4 v[238:239], off
	s_barrier
	s_waitcnt lgkmcnt(0)
	s_waitcnt lgkmcnt(0)
	v_mfma_f32_16x16x32_bf16 v[68:71], v[140:143], v[156:159], v[68:71]
	v_mfma_f32_16x16x32_bf16 v[88:91], v[148:151], v[156:159], v[88:91]
	v_mfma_f32_16x16x32_bf16 v[48:51], v[140:143], v[164:167], v[48:51]
	v_mfma_f32_16x16x32_bf16 v[72:75], v[148:151], v[164:167], v[72:75]
	v_mfma_f32_16x16x32_bf16 v[36:39], v[140:143], v[172:175], v[36:39]
	v_mfma_f32_16x16x32_bf16 v[56:59], v[148:151], v[172:175], v[56:59]
	v_mfma_f32_16x16x32_bf16 v[32:35], v[140:143], v[186:189], v[32:35]
	v_mfma_f32_16x16x32_bf16 v[44:47], v[148:151], v[186:189], v[44:47]
	v_mfma_f32_16x16x32_bf16 v[68:71], v[144:147], v[160:163], v[68:71]
	v_mfma_f32_16x16x32_bf16 v[88:91], v[152:155], v[160:163], v[88:91]
	v_mfma_f32_16x16x32_bf16 v[48:51], v[144:147], v[168:171], v[48:51]
	v_mfma_f32_16x16x32_bf16 v[72:75], v[152:155], v[168:171], v[72:75]
	v_mfma_f32_16x16x32_bf16 v[36:39], v[144:147], v[182:185], v[36:39]
	v_mfma_f32_16x16x32_bf16 v[56:59], v[152:155], v[182:185], v[56:59]
	v_mfma_f32_16x16x32_bf16 v[32:35], v[144:147], v[214:217], v[32:35]
	v_mfma_f32_16x16x32_bf16 v[44:47], v[152:155], v[214:217], v[44:47]
	s_barrier
; #define G_STAGE(bufoff, gbase) do { _Pragma("unroll") for (int _i = 0; _i < 2; ++_i) \
;     __builtin_amdgcn_global_load_lds((const unsigned*)((const char*)(gbase) + voff[_i]), (GLAS unsigned*)(lds + (bufoff) + ldsw + _i * 8192), 16, 0, 0); } while (0)
; #define G_LDA(dst, b, h) do { _Pragma("unroll") for (int m = 0; m < 4; ++m) _Pragma("unroll") for (int k = 0; k < 2; ++k) \
;     dst[m][k] = *(const GLAS bf16x8*)(lds + G_SA(b, h) + aoff + m * 2048 + k * 1024); } while (0)
; #define G_LDB(dst, b, h) do { _Pragma("unroll") for (int n = 0; n < 2; ++n) _Pragma("unroll") for (int k = 0; k < 2; ++k) \
;     dst[n][k] = *(const GLAS bf16x8*)(lds + G_SB(b, h) + boff + n * 2048 + k * 1024); } while (0)
; #define G_MMA(ai, bj, At_, Bt_) do { __builtin_amdgcn_s_setprio(1); \
;     _Pragma("unroll") for (int m = 0; m < 4; ++m) _Pragma("unroll") for (int n = 0; n < 2; ++n) _Pragma("unroll") for (int k = 0; k < 2; ++k) \
;       acc[ai][bj][m][n] = __builtin_amdgcn_mfma_f32_16x16x32_bf16(Bt_[n][k], At_[m][k], acc[ai][bj][m][n], 0, 0, 0); \
;     __builtin_amdgcn_s_setprio(0); } while (0)
; #define G_WAIT_V(n) asm volatile("s_waitcnt vmcnt(" #n ")" ::: "memory")
; #define G_WAIT_L(n) asm volatile("s_waitcnt lgkmcnt(" #n ")" ::: "memory")
; #define G_BAR __builtin_amdgcn_s_barrier()
; #define G_SCHED __builtin_amdgcn_sched_barrier(0)
; __device__ __forceinline__ void gemm_phase(const Params& p, int l, const bf16_t* __restrict__ A, const bf16_t* __restrict__ Bt, int M, int N, int K,
;                            int epi, bf16_t* __restrict__ outp, char* smem, int wvi) {
;     ...
;         G_WAIT_V(6); G_BAR; G_MMA(1, 1, At, B1); G_BAR;
;         G_LDB(B0, 1, 0); G_SCHED; G_LDA(At, 1, 0); G_STAGE(G_SA(0, 1), a2 + hstep);
;         G_WAIT_L(8); G_BAR; G_WAIT_L(0); G_MMA(0, 0, At, B0); G_BAR; G_SCHED;
;         G_LDB(B1, 1, 1); G_STAGE(G_SB(1, 0), b3);
;         G_BAR; G_WAIT_L(0); G_MMA(0, 1, At, B1); G_BAR;
;         G_LDA(At, 1, 1); G_STAGE(G_SA(1, 0), a3);
;         G_BAR; G_WAIT_L(0); G_MMA(1, 0, At, B0); G_BAR; G_SCHED;
;         G_STAGE(G_SB(1, 1), b3 + hstep);
	s_add_u32 s10, s12, 0xb0000
	s_addc_u32 s11, s13, 0
	s_add_i32 s34, s35, s58
	v_lshl_add_u64 v[140:141], s[10:11], 0, v[176:177]
	s_mov_b32 m0, s34
	s_nop 0
	global_load_lds_dwordx4 v[140:141], off
	v_lshl_add_u64 v[140:141], s[10:11], 0, v[128:129]
	s_add_i32 m0, s34, 0x2000
	s_nop 0
	global_load_lds_dwordx4 v[140:141], off
	s_waitcnt vmcnt(6)
	s_barrier
	v_mfma_f32_16x16x32_bf16 v[120:123], v[218:221], v[156:159], v[120:123]
	v_mfma_f32_16x16x32_bf16 v[124:127], v[226:229], v[156:159], v[124:127]
	v_mfma_f32_16x16x32_bf16 v[112:115], v[218:221], v[164:167], v[112:115]
	v_mfma_f32_16x16x32_bf16 v[116:119], v[226:229], v[164:167], v[116:119]
	v_mfma_f32_16x16x32_bf16 v[104:107], v[218:221], v[172:175], v[104:107]
	v_mfma_f32_16x16x32_bf16 v[108:111], v[226:229], v[172:175], v[108:111]
	v_mfma_f32_16x16x32_bf16 v[96:99], v[218:221], v[186:189], v[96:99]
	v_mfma_f32_16x16x32_bf16 v[100:103], v[226:229], v[186:189], v[100:103]
	v_mfma_f32_16x16x32_bf16 v[120:123], v[222:225], v[160:163], v[120:123]
	v_mfma_f32_16x16x32_bf16 v[124:127], v[230:233], v[160:163], v[124:127]
	v_mfma_f32_16x16x32_bf16 v[112:115], v[222:225], v[168:171], v[112:115]
	v_mfma_f32_16x16x32_bf16 v[116:119], v[230:233], v[168:171], v[116:119]
	v_mfma_f32_16x16x32_bf16 v[104:107], v[222:225], v[182:185], v[104:107]
	v_mfma_f32_16x16x32_bf16 v[108:111], v[230:233], v[182:185], v[108:111]
	v_mfma_f32_16x16x32_bf16 v[96:99], v[222:225], v[214:217], v[96:99]
	v_mfma_f32_16x16x32_bf16 v[100:103], v[230:233], v[214:217], v[100:103]
	s_add_i32 s34, 0, 0x18000
	v_add_u32_e32 v139, s34, v137
	s_barrier
	ds_read_b128 v[140:143], v139
	ds_read_b128 v[144:147], v139 offset:1024
	ds_read_b128 v[148:151], v139 offset:2048
	ds_read_b128 v[152:155], v139 offset:3072
	s_add_u32 s10, s14, 0xb0000
	s_addc_u32 s11, s15, 0
	s_mov_b32 m0, s24
	v_lshl_add_u64 v[218:219], s[10:11], 0, v[176:177]
	ds_read_b128 v[156:159], v138 offset:32768
	ds_read_b128 v[160:163], v138 offset:33792
	ds_read_b128 v[164:167], v138 offset:34816
	ds_read_b128 v[168:171], v138 offset:35840
	ds_read_b128 v[172:175], v138 offset:36864
	ds_read_b128 v[182:185], v138 offset:37888
	ds_read_b128 v[186:189], v138 offset:38912
	ds_read_b128 v[214:217], v138 offset:39936
	global_load_lds_dwordx4 v[218:219], off
	v_lshl_add_u64 v[218:219], s[10:11], 0, v[128:129]
	s_mov_b32 m0, s25
	s_nop 0
	global_load_lds_dwordx4 v[218:219], off
	s_waitcnt lgkmcnt(8)
	s_barrier
	s_waitcnt lgkmcnt(0)
	s_waitcnt lgkmcnt(0)
	v_mfma_f32_16x16x32_bf16 v[20:23], v[140:143], v[156:159], v[20:23]
	v_mfma_f32_16x16x32_bf16 v[28:31], v[148:151], v[156:159], v[28:31]
	v_mfma_f32_16x16x32_bf16 v[12:15], v[140:143], v[164:167], v[12:15]
	v_mfma_f32_16x16x32_bf16 v[24:27], v[148:151], v[164:167], v[24:27]
	v_mfma_f32_16x16x32_bf16 v[4:7], v[140:143], v[172:175], v[4:7]
	v_mfma_f32_16x16x32_bf16 v[16:19], v[148:151], v[172:175], v[16:19]
	v_mfma_f32_16x16x32_bf16 v[0:3], v[140:143], v[186:189], v[0:3]
	v_mfma_f32_16x16x32_bf16 v[8:11], v[148:151], v[186:189], v[8:11]
	v_mfma_f32_16x16x32_bf16 v[20:23], v[144:147], v[160:163], v[20:23]
	v_mfma_f32_16x16x32_bf16 v[28:31], v[152:155], v[160:163], v[28:31]
	v_mfma_f32_16x16x32_bf16 v[12:15], v[144:147], v[168:171], v[12:15]
	v_mfma_f32_16x16x32_bf16 v[24:27], v[152:155], v[168:171], v[24:27]
	v_mfma_f32_16x16x32_bf16 v[4:7], v[144:147], v[182:185], v[4:7]
	v_mfma_f32_16x16x32_bf16 v[16:19], v[152:155], v[182:185], v[16:19]
	v_mfma_f32_16x16x32_bf16 v[0:3], v[144:147], v[214:217], v[0:3]
	v_mfma_f32_16x16x32_bf16 v[8:11], v[152:155], v[214:217], v[8:11]
	s_barrier
	s_add_i32 s14, 0, 0x1c000
	s_add_i32 s10, s34, s58
	v_add_u32_e32 v139, s14, v137
	v_lshl_add_u64 v[190:191], v[190:191], 0, s[64:65]
	s_mov_b32 m0, s10
	ds_read_b128 v[218:221], v139
	ds_read_b128 v[222:225], v139 offset:1024
	ds_read_b128 v[226:229], v139 offset:2048
	ds_read_b128 v[230:233], v139 offset:3072
	global_load_lds_dwordx4 v[190:191], off
	v_lshl_add_u64 v[190:191], v[234:235], 0, s[64:65]
	s_add_i32 m0, s10, 0x2000
	s_nop 0
	global_load_lds_dwordx4 v[190:191], off
	s_barrier
	s_waitcnt lgkmcnt(0)
	s_waitcnt lgkmcnt(0)
	v_mfma_f32_16x16x32_bf16 v[80:83], v[218:221], v[156:159], v[80:83]
	v_mfma_f32_16x16x32_bf16 v[92:95], v[226:229], v[156:159], v[92:95]
	v_mfma_f32_16x16x32_bf16 v[64:67], v[218:221], v[164:167], v[64:67]
	v_mfma_f32_16x16x32_bf16 v[84:87], v[226:229], v[164:167], v[84:87]
	v_mfma_f32_16x16x32_bf16 v[52:55], v[218:221], v[172:175], v[52:55]
	v_mfma_f32_16x16x32_bf16 v[76:79], v[226:229], v[172:175], v[76:79]
	v_mfma_f32_16x16x32_bf16 v[40:43], v[218:221], v[186:189], v[40:43]
	v_mfma_f32_16x16x32_bf16 v[60:63], v[226:229], v[186:189], v[60:63]
	v_mfma_f32_16x16x32_bf16 v[80:83], v[222:225], v[160:163], v[80:83]
	v_mfma_f32_16x16x32_bf16 v[92:95], v[230:233], v[160:163], v[92:95]
	v_mfma_f32_16x16x32_bf16 v[64:67], v[222:225], v[168:171], v[64:67]
	v_mfma_f32_16x16x32_bf16 v[84:87], v[230:233], v[168:171], v[84:87]
	v_mfma_f32_16x16x32_bf16 v[52:55], v[222:225], v[182:185], v[52:55]
	v_mfma_f32_16x16x32_bf16 v[76:79], v[230:233], v[182:185], v[76:79]
	v_mfma_f32_16x16x32_bf16 v[40:43], v[222:225], v[214:217], v[40:43]
	v_mfma_f32_16x16x32_bf16 v[60:63], v[230:233], v[214:217], v[60:63]
	s_mov_b32 m0, s0
	v_lshl_add_u64 v[190:191], v[236:237], 0, s[64:65]
	s_barrier
	ds_read_b128 v[156:159], v138 offset:49152
	ds_read_b128 v[160:163], v138 offset:50176
	ds_read_b128 v[164:167], v138 offset:51200
	ds_read_b128 v[168:171], v138 offset:52224
	ds_read_b128 v[172:175], v138 offset:53248
	ds_read_b128 v[182:185], v138 offset:54272
	ds_read_b128 v[186:189], v138 offset:55296
	ds_read_b128 v[214:217], v138 offset:56320
	global_load_lds_dwordx4 v[190:191], off
	v_lshl_add_u64 v[190:191], v[238:239], 0, s[64:65]
	s_mov_b32 m0, s1
	s_nop 0
	global_load_lds_dwordx4 v[190:191], off
	s_barrier
; __device__ __forceinline__ u32x4 mk4(unsigned a, unsigned b, unsigned c, unsigned d) { return (u32x4){a, b, c, d}; }
; #define G_STAGE(bufoff, gbase) do { _Pragma("unroll") for (int _i = 0; _i < 2; ++_i) \
;     __builtin_amdgcn_global_load_lds((const unsigned*)((const char*)(gbase) + voff[_i]), (GLAS unsigned*)(lds + (bufoff) + ldsw + _i * 8192), 16, 0, 0); } while (0)
; #define G_LDA(dst, b, h) do { _Pragma("unroll") for (int m = 0; m < 4; ++m) _Pragma("unroll") for (int k = 0; k < 2; ++k) \
;     dst[m][k] = *(const GLAS bf16x8*)(lds + G_SA(b, h) + aoff + m * 2048 + k * 1024); } while (0)
; #define G_MMA(ai, bj, At_, Bt_) do { __builtin_amdgcn_s_setprio(1); \
;     _Pragma("unroll") for (int m = 0; m < 4; ++m) _Pragma("unroll") for (int n = 0; n < 2; ++n) _Pragma("unroll") for (int k = 0; k < 2; ++k) \
;       acc[ai][bj][m][n] = __builtin_amdgcn_mfma_f32_16x16x32_bf16(Bt_[n][k], At_[m][k], acc[ai][bj][m][n], 0, 0, 0); \
;     __builtin_amdgcn_s_setprio(0); } while (0)
; #define G_WAIT_V(n) asm volatile("s_waitcnt vmcnt(" #n ")" ::: "memory")
; #define G_WAIT_L(n) asm volatile("s_waitcnt lgkmcnt(" #n ")" ::: "memory")
; #define G_BAR __builtin_amdgcn_s_barrier()
; #define G_SCHED __builtin_amdgcn_sched_barrier(0)
; __device__ __forceinline__ void gemm_phase(const Params& p, int l, const bf16_t* __restrict__ A, const bf16_t* __restrict__ Bt, int M, int N, int K,
;                            int epi, bf16_t* __restrict__ outp, char* smem, int wvi) {
;     ...
;         G_BAR; G_WAIT_L(0); G_MMA(0, 1, At, B1); G_BAR;
;         G_LDA(At, 1, 1); G_STAGE(G_SA(1, 0), a3);
;         G_BAR; G_WAIT_L(0); G_MMA(1, 0, At, B0); G_BAR; G_SCHED;
;         G_STAGE(G_SB(1, 1), b3 + hstep);
;         G_WAIT_V(6); G_BAR; G_MMA(1, 1, At, B1); G_BAR;
;       }
;       const int brow = pm * GBM, bcol = pn * GBM;
;     const int r0 = brow + wr * 64 + fr;
;     if (epi == EPI_PLAIN) {
; #pragma unroll
;       for (int ai = 0; ai < 2; ++ai)
; #pragma unroll
;         for (int m = 0; m < 4; ++m) {
;           bf16_t* rp = outp + (size_t)(r0 + ai * GHALF + m * 16) * N + bcol + wc * 32 + fq * 8;
; #pragma unroll
;           for (int bj = 0; bj < 2; ++bj) {
;             const f32x4 v0 = acc[ai][bj][m][0], v1 = acc[ai][bj][m][1];
;             *reinterpret_cast<u32x4*>(rp + bj * GHALF) = mk4(pk2(v0[0], v0[1]), pk2(v0[2], v0[3]), pk2(v1[0], v1[1]), pk2(v1[2], v1[3]));
	s_waitcnt lgkmcnt(0)
	s_waitcnt lgkmcnt(0)
	v_mfma_f32_16x16x32_bf16 v[68:71], v[140:143], v[156:159], v[68:71]
	v_mfma_f32_16x16x32_bf16 v[88:91], v[148:151], v[156:159], v[88:91]
	v_mfma_f32_16x16x32_bf16 v[48:51], v[140:143], v[164:167], v[48:51]
	v_mfma_f32_16x16x32_bf16 v[72:75], v[148:151], v[164:167], v[72:75]
	v_mfma_f32_16x16x32_bf16 v[36:39], v[140:143], v[172:175], v[36:39]
	v_mfma_f32_16x16x32_bf16 v[56:59], v[148:151], v[172:175], v[56:59]
	v_mfma_f32_16x16x32_bf16 v[32:35], v[140:143], v[186:189], v[32:35]
	v_mfma_f32_16x16x32_bf16 v[44:47], v[148:151], v[186:189], v[44:47]
	v_mfma_f32_16x16x32_bf16 v[68:71], v[144:147], v[160:163], v[68:71]
	v_mfma_f32_16x16x32_bf16 v[88:91], v[152:155], v[160:163], v[88:91]
	v_mfma_f32_16x16x32_bf16 v[48:51], v[144:147], v[168:171], v[48:51]
	v_mfma_f32_16x16x32_bf16 v[72:75], v[152:155], v[168:171], v[72:75]
	v_mfma_f32_16x16x32_bf16 v[36:39], v[144:147], v[182:185], v[36:39]
	v_mfma_f32_16x16x32_bf16 v[56:59], v[152:155], v[182:185], v[56:59]
	v_mfma_f32_16x16x32_bf16 v[32:35], v[144:147], v[214:217], v[32:35]
	v_mfma_f32_16x16x32_bf16 v[44:47], v[152:155], v[214:217], v[44:47]
	s_barrier
	s_add_u32 s10, s12, 0xb0080
	s_addc_u32 s11, s13, 0
	s_add_i32 s12, s14, s58
	v_lshl_add_u64 v[140:141], s[10:11], 0, v[176:177]
	s_mov_b32 m0, s12
	s_nop 0
	global_load_lds_dwordx4 v[140:141], off
	v_lshl_add_u64 v[140:141], s[10:11], 0, v[128:129]
	s_add_i32 m0, s12, 0x2000
	s_nop 0
	global_load_lds_dwordx4 v[140:141], off
	s_waitcnt vmcnt(6)
	s_barrier
	v_mfma_f32_16x16x32_bf16 v[120:123], v[218:221], v[156:159], v[120:123]
	v_mfma_f32_16x16x32_bf16 v[124:127], v[226:229], v[156:159], v[124:127]
	v_mfma_f32_16x16x32_bf16 v[112:115], v[218:221], v[164:167], v[112:115]
	v_mfma_f32_16x16x32_bf16 v[116:119], v[226:229], v[164:167], v[116:119]
	v_mfma_f32_16x16x32_bf16 v[104:107], v[218:221], v[172:175], v[104:107]
	v_mfma_f32_16x16x32_bf16 v[108:111], v[226:229], v[172:175], v[108:111]
	v_mfma_f32_16x16x32_bf16 v[96:99], v[218:221], v[186:189], v[96:99]
	v_mfma_f32_16x16x32_bf16 v[100:103], v[226:229], v[186:189], v[100:103]
	v_mfma_f32_16x16x32_bf16 v[120:123], v[222:225], v[160:163], v[120:123]
	v_mfma_f32_16x16x32_bf16 v[124:127], v[230:233], v[160:163], v[124:127]
	v_mfma_f32_16x16x32_bf16 v[112:115], v[222:225], v[168:171], v[112:115]
	v_mfma_f32_16x16x32_bf16 v[116:119], v[230:233], v[168:171], v[116:119]
	v_mfma_f32_16x16x32_bf16 v[104:107], v[222:225], v[182:185], v[104:107]
	v_mfma_f32_16x16x32_bf16 v[108:111], v[230:233], v[182:185], v[108:111]
	v_mfma_f32_16x16x32_bf16 v[96:99], v[222:225], v[214:217], v[96:99]
	v_mfma_f32_16x16x32_bf16 v[100:103], v[230:233], v[214:217], v[100:103]
	s_add_i32 s67, s67, 2
	s_add_u32 s55, s55, 0x100
	s_addc_u32 s63, s63, 0
	s_cmp_gt_u32 s67, 41
	s_mov_b64 s[10:11], s[2:3]
	s_barrier
	s_cbranch_scc0 .LBB0_121
	s_lshl_b32 s2, s30, 8
	v_lshl_add_u32 v140, s29, 8, v136
	s_ashr_i32 s3, s2, 31
	v_ashrrev_i32_e32 v141, 31, v140
	v_lshl_add_u64 v[142:143], s[2:3], 1, v[130:131]
	v_lshlrev_b64 v[144:145], 11, v[140:141]
	v_lshl_add_u64 v[144:145], v[142:143], 0, v[144:145]
	v_cvt_pk_bf16_f32 v20, v20, v21
	v_cvt_pk_bf16_f32 v21, v22, v23
	v_cvt_pk_bf16_f32 v22, v28, v29
	v_cvt_pk_bf16_f32 v23, v30, v31
	global_store_dwordx4 v[144:145], v[20:23], off
	v_cvt_pk_bf16_f32 v12, v12, v13
	v_cvt_pk_bf16_f32 v13, v14, v15
	v_cvt_pk_bf16_f32 v20, v80, v81
	v_cvt_pk_bf16_f32 v21, v82, v83
	v_cvt_pk_bf16_f32 v22, v92, v93
	v_cvt_pk_bf16_f32 v23, v94, v95
	global_store_dwordx4 v[144:145], v[20:23], off offset:256
	v_cvt_pk_bf16_f32 v14, v24, v25
	v_cvt_pk_bf16_f32 v15, v26, v27
	v_or_b32_e32 v20, 16, v140
	v_ashrrev_i32_e32 v21, 31, v20
	v_lshlrev_b64 v[20:21], 11, v[20:21]
	v_lshl_add_u64 v[20:21], v[142:143], 0, v[20:21]
	global_store_dwordx4 v[20:21], v[12:15], off
	v_cvt_pk_bf16_f32 v4, v4, v5
	v_cvt_pk_bf16_f32 v5, v6, v7
	v_cvt_pk_bf16_f32 v12, v64, v65
	v_cvt_pk_bf16_f32 v13, v66, v67
	v_cvt_pk_bf16_f32 v14, v84, v85
	v_cvt_pk_bf16_f32 v15, v86, v87
	global_store_dwordx4 v[20:21], v[12:15], off offset:256
	v_cvt_pk_bf16_f32 v6, v16, v17
	v_cvt_pk_bf16_f32 v7, v18, v19
	v_or_b32_e32 v12, 32, v140
	v_ashrrev_i32_e32 v13, 31, v12
	v_lshlrev_b64 v[12:13], 11, v[12:13]
	v_lshl_add_u64 v[12:13], v[142:143], 0, v[12:13]
	global_store_dwordx4 v[12:13], v[4:7], off
	v_cvt_pk_bf16_f32 v0, v0, v1
	v_cvt_pk_bf16_f32 v1, v2, v3
	v_cvt_pk_bf16_f32 v4, v52, v53
	v_cvt_pk_bf16_f32 v5, v54, v55
	v_cvt_pk_bf16_f32 v6, v76, v77
	v_cvt_pk_bf16_f32 v7, v78, v79
	global_store_dwordx4 v[12:13], v[4:7], off offset:256
	v_cvt_pk_bf16_f32 v2, v8, v9
	v_cvt_pk_bf16_f32 v3, v10, v11
	v_or_b32_e32 v4, 48, v140
	v_ashrrev_i32_e32 v5, 31, v4
	v_lshlrev_b64 v[4:5], 11, v[4:5]
	v_lshl_add_u64 v[4:5], v[142:143], 0, v[4:5]
	global_store_dwordx4 v[4:5], v[0:3], off
	s_mov_b64 s[2:3], 0x40000
	v_readlane_b32 s63, v244, 19
	v_cvt_pk_bf16_f32 v0, v40, v41
	v_cvt_pk_bf16_f32 v1, v42, v43
	v_cvt_pk_bf16_f32 v2, v60, v61
	v_cvt_pk_bf16_f32 v3, v62, v63
	global_store_dwordx4 v[4:5], v[0:3], off offset:256
	v_lshl_add_u64 v[4:5], v[144:145], 0, s[2:3]
	s_mov_b32 s2, 0x40000
	v_add_co_u32_e32 v6, vcc, s2, v144
	v_cvt_pk_bf16_f32 v0, v68, v69
	v_cvt_pk_bf16_f32 v1, v70, v71
	v_cvt_pk_bf16_f32 v2, v88, v89
	v_cvt_pk_bf16_f32 v3, v90, v91
	v_addc_co_u32_e32 v7, vcc, 0, v145, vcc
	global_store_dwordx4 v[6:7], v[0:3], off
; __device__ __forceinline__ u32x4 mk4(unsigned a, unsigned b, unsigned c, unsigned d) { return (u32x4){a, b, c, d}; }
; __device__ __forceinline__ f32x4 zero4() { float z = 0.f; asm volatile("" : "+v"(z)); return (f32x4){z, z, z, z}; }
; #define G_WAIT_V(n) asm volatile("s_waitcnt vmcnt(" #n ")" ::: "memory")
; #define G_BAR __builtin_amdgcn_s_barrier()
; __device__ __forceinline__ void gemm_phase(const Params& p, int l, const bf16_t* __restrict__ A, const bf16_t* __restrict__ Bt, int M, int N, int K,
;                            int epi, bf16_t* __restrict__ outp, char* smem, int wvi) {
;     ...
;           bf16_t* rp = outp + (size_t)(r0 + ai * GHALF + m * 16) * N + bcol + wc * 32 + fq * 8;
; #pragma unroll
;           for (int bj = 0; bj < 2; ++bj) {
;             const f32x4 v0 = acc[ai][bj][m][0], v1 = acc[ai][bj][m][1];
;             *reinterpret_cast<u32x4*>(rp + bj * GHALF) = mk4(pk2(v0[0], v0[1]), pk2(v0[2], v0[3]), pk2(v1[0], v1[1]), pk2(v1[2], v1[3]));
;           }
;         }
;     ...
;       if (!has_next) break;
; #pragma unroll
;       for (int a = 0; a < 2; ++a)
; #pragma unroll
;         for (int b = 0; b < 2; ++b)
; #pragma unroll
;           for (int m = 0; m < 4; ++m)
; #pragma unroll
;             for (int n = 0; n < 2; ++n) acc[a][b][m][n] = zero4();
;       Lw = Ln; pm = npm; pn = npn; cA = nA; cB = nB;
;     }
;     G_WAIT_V(0);
;     if (wr == 0) G_BAR;
;     G_BAR;
	s_mov_b64 s[2:3], 0x48000
	v_readlane_b32 s67, v244, 20
	v_cvt_pk_bf16_f32 v0, v120, v121
	v_cvt_pk_bf16_f32 v1, v122, v123
	v_cvt_pk_bf16_f32 v2, v124, v125
	v_cvt_pk_bf16_f32 v3, v126, v127
	global_store_dwordx4 v[4:5], v[0:3], off offset:256
	v_lshl_add_u64 v[4:5], v[144:145], 0, s[2:3]
	s_mov_b32 s2, 0x48000
	v_add_co_u32_e32 v6, vcc, s2, v144
	v_cvt_pk_bf16_f32 v0, v48, v49
	v_cvt_pk_bf16_f32 v1, v50, v51
	v_cvt_pk_bf16_f32 v2, v72, v73
	v_cvt_pk_bf16_f32 v3, v74, v75
	v_addc_co_u32_e32 v7, vcc, 0, v145, vcc
	global_store_dwordx4 v[6:7], v[0:3], off
	s_mov_b64 s[2:3], 0x50000
	s_movk_i32 s53, 0x440
	v_cvt_pk_bf16_f32 v0, v112, v113
	v_cvt_pk_bf16_f32 v1, v114, v115
	v_cvt_pk_bf16_f32 v2, v116, v117
	v_cvt_pk_bf16_f32 v3, v118, v119
	global_store_dwordx4 v[4:5], v[0:3], off offset:256
	v_lshl_add_u64 v[4:5], v[144:145], 0, s[2:3]
	s_mov_b32 s2, 0x50000
	v_add_co_u32_e32 v6, vcc, s2, v144
	v_cvt_pk_bf16_f32 v0, v36, v37
	v_cvt_pk_bf16_f32 v1, v38, v39
	v_cvt_pk_bf16_f32 v2, v56, v57
	v_cvt_pk_bf16_f32 v3, v58, v59
	v_addc_co_u32_e32 v7, vcc, 0, v145, vcc
	global_store_dwordx4 v[6:7], v[0:3], off
	s_mov_b64 s[2:3], 0x58000
	v_readlane_b32 s55, v244, 31
	v_cvt_pk_bf16_f32 v0, v104, v105
	v_cvt_pk_bf16_f32 v1, v106, v107
	v_cvt_pk_bf16_f32 v2, v108, v109
	v_cvt_pk_bf16_f32 v3, v110, v111
	global_store_dwordx4 v[4:5], v[0:3], off offset:256
	v_lshl_add_u64 v[4:5], v[144:145], 0, s[2:3]
	s_mov_b32 s2, 0x58000
	v_add_co_u32_e32 v6, vcc, s2, v144
	v_cvt_pk_bf16_f32 v0, v32, v33
	v_cvt_pk_bf16_f32 v1, v34, v35
	v_cvt_pk_bf16_f32 v2, v44, v45
	v_cvt_pk_bf16_f32 v3, v46, v47
	v_addc_co_u32_e32 v7, vcc, 0, v145, vcc
	global_store_dwordx4 v[6:7], v[0:3], off
	s_mov_b64 s[2:3], -1
	s_and_b64 vcc, exec, s[8:9]
	v_cvt_pk_bf16_f32 v0, v96, v97
	v_cvt_pk_bf16_f32 v1, v98, v99
	v_cvt_pk_bf16_f32 v2, v100, v101
	v_cvt_pk_bf16_f32 v3, v102, v103
	global_store_dwordx4 v[4:5], v[0:3], off offset:256
	s_cbranch_vccz .LBB0_117
	v_mov_b32_e32 v20, v177
	v_mov_b32_e32 v28, v177
	v_mov_b32_e32 v12, v177
	v_mov_b32_e32 v24, v177
	v_mov_b32_e32 v4, v177
	v_mov_b32_e32 v16, v177
	v_mov_b32_e32 v0, v177
	v_mov_b32_e32 v8, v177
	v_mov_b32_e32 v80, v177
	v_mov_b32_e32 v92, v177
	v_mov_b32_e32 v64, v177
	v_mov_b32_e32 v84, v177
	v_mov_b32_e32 v52, v177
	v_mov_b32_e32 v76, v177
	v_mov_b32_e32 v40, v177
	v_mov_b32_e32 v60, v177
	v_mov_b32_e32 v68, v177
	v_mov_b32_e32 v88, v177
	v_mov_b32_e32 v48, v177
	v_mov_b32_e32 v72, v177
	v_mov_b32_e32 v36, v177
	v_mov_b32_e32 v56, v177
	v_mov_b32_e32 v32, v177
	v_mov_b32_e32 v44, v177
	v_mov_b32_e32 v120, v177
	v_mov_b32_e32 v124, v177
	v_mov_b32_e32 v112, v177
	v_mov_b32_e32 v116, v177
	v_mov_b32_e32 v104, v177
	v_mov_b32_e32 v108, v177
	v_mov_b32_e32 v96, v177
	v_mov_b32_e32 v100, v177
	s_nop 0
	v_mov_b32_e32 v21, v20
	v_mov_b32_e32 v22, v20
	v_mov_b32_e32 v23, v20
	v_mov_b32_e32 v29, v28
	v_mov_b32_e32 v30, v28
	v_mov_b32_e32 v31, v28
	v_mov_b32_e32 v13, v12
	v_mov_b32_e32 v14, v12
	v_mov_b32_e32 v15, v12
	v_mov_b32_e32 v25, v24
	v_mov_b32_e32 v26, v24
	v_mov_b32_e32 v27, v24
	v_mov_b32_e32 v5, v4
	v_mov_b32_e32 v6, v4
	v_mov_b32_e32 v7, v4
	v_mov_b32_e32 v17, v16
	v_mov_b32_e32 v18, v16
	v_mov_b32_e32 v19, v16
	s_nop 0
	v_mov_b32_e32 v1, v0
	v_mov_b32_e32 v2, v0
	v_mov_b32_e32 v3, v0
	v_mov_b32_e32 v9, v8
	v_mov_b32_e32 v10, v8
	v_mov_b32_e32 v11, v8
	v_mov_b32_e32 v81, v80
	v_mov_b32_e32 v82, v80
	v_mov_b32_e32 v83, v80
	v_mov_b32_e32 v93, v92
	v_mov_b32_e32 v94, v92
	v_mov_b32_e32 v95, v92
	v_mov_b32_e32 v65, v64
	v_mov_b32_e32 v66, v64
	v_mov_b32_e32 v67, v64
	v_mov_b32_e32 v85, v84
	v_mov_b32_e32 v86, v84
	v_mov_b32_e32 v87, v84
	s_nop 0
	v_mov_b32_e32 v53, v52
	v_mov_b32_e32 v54, v52
	v_mov_b32_e32 v55, v52
	v_mov_b32_e32 v77, v76
	v_mov_b32_e32 v78, v76
	v_mov_b32_e32 v79, v76
	v_mov_b32_e32 v41, v40
	v_mov_b32_e32 v42, v40
	v_mov_b32_e32 v43, v40
	v_mov_b32_e32 v61, v60
	v_mov_b32_e32 v62, v60
	v_mov_b32_e32 v63, v60
	v_mov_b32_e32 v69, v68
	v_mov_b32_e32 v70, v68
	v_mov_b32_e32 v71, v68
	v_mov_b32_e32 v89, v88
	v_mov_b32_e32 v90, v88
	v_mov_b32_e32 v91, v88
	s_nop 0
	v_mov_b32_e32 v49, v48
	v_mov_b32_e32 v50, v48
	v_mov_b32_e32 v51, v48
	v_mov_b32_e32 v73, v72
	v_mov_b32_e32 v74, v72
	v_mov_b32_e32 v75, v72
	v_mov_b32_e32 v37, v36
	v_mov_b32_e32 v38, v36
	v_mov_b32_e32 v39, v36
	v_mov_b32_e32 v57, v56
	v_mov_b32_e32 v58, v56
	v_mov_b32_e32 v59, v56
	v_mov_b32_e32 v33, v32
	v_mov_b32_e32 v34, v32
	v_mov_b32_e32 v35, v32
	v_mov_b32_e32 v45, v44
	v_mov_b32_e32 v46, v44
	v_mov_b32_e32 v47, v44
	s_nop 0
	v_mov_b32_e32 v121, v120
	v_mov_b32_e32 v122, v120
	v_mov_b32_e32 v123, v120
	v_mov_b32_e32 v125, v124
	v_mov_b32_e32 v126, v124
	v_mov_b32_e32 v127, v124
	v_mov_b32_e32 v113, v112
	v_mov_b32_e32 v114, v112
	v_mov_b32_e32 v115, v112
	v_mov_b32_e32 v117, v116
	v_mov_b32_e32 v118, v116
	v_mov_b32_e32 v119, v116
	v_mov_b32_e32 v105, v104
	v_mov_b32_e32 v106, v104
	v_mov_b32_e32 v107, v104
	v_mov_b32_e32 v109, v108
	v_mov_b32_e32 v110, v108
	v_mov_b32_e32 v111, v108
	s_mov_b64 s[2:3], 0
	v_mov_b32_e32 v97, v96
	v_mov_b32_e32 v98, v96
	v_mov_b32_e32 v99, v96
	v_mov_b32_e32 v101, v100
	v_mov_b32_e32 v102, v100
	v_mov_b32_e32 v103, v100
	s_branch .LBB0_117
.LBB0_124:
	v_readlane_b32 s0, v248, 17
	s_setprio 0
	s_waitcnt vmcnt(0)
	v_readlane_b32 s1, v248, 18
	s_andn2_b64 vcc, exec, s[0:1]
	s_cbranch_vccnz .LBB0_126
	s_barrier

; __device__ __forceinline__ f32x4 zero4() { float z = 0.f; asm volatile("" : "+v"(z)); return (f32x4){z, z, z, z}; }
; #define G_STAGE(bufoff, gbase) do { _Pragma("unroll") for (int _i = 0; _i < 2; ++_i) \
;     __builtin_amdgcn_global_load_lds((const unsigned*)((const char*)(gbase) + voff[_i]), (GLAS unsigned*)(lds + (bufoff) + ldsw + _i * 8192), 16, 0, 0); } while (0)
; #define G_WAIT_V(n) asm volatile("s_waitcnt vmcnt(" #n ")" ::: "memory")
; __device__ __forceinline__ void gemm_phase(const Params& p, int l, const bf16_t* __restrict__ A, const bf16_t* __restrict__ Bt, int M, int N, int K,
;                            int epi, bf16_t* __restrict__ outp, char* smem, int wvi) {
;     ...
;   for (int i = 0; i < 2; ++i) { int R, C; stage_rc(tidx * 16 + i * 8192, R, C); voff[i] = (unsigned)(R * K + C) * 2u; }
;   const size_t kstep = (size_t)(GBK * 2), hstep = (size_t)GHALF * K * 2, tstep = 2 * hstep;
;   const unsigned ldsw = (unsigned)wid * 1024u;
;   const int aoff = lds_byte(wr * 64 + fr, fq * 8), boff = lds_byte(wc * 32 + fr, fq * 8);
;   constexpr int HTB = GHT * 2;
;     ...
;   const int nM = M / GBM, nN = N / GBM, nwg = nM * nN;
;   auto tile_of = [&](int Lw, int& pm_, int& pn_) {
;     int wgid = Lw;
;     { const int q = nwg / GNXCD, r = nwg % GNXCD, xcd = wgid % GNXCD, off = wgid / GNXCD; wgid = (xcd < r ? xcd * (q + 1) : r * (q + 1) + (xcd - r) * q) + off; }
;     const int nig = GWGM * nN, gid = wgid / nig, fm = gid * GWGM, gsz = min(nM - fm, GWGM);
;     pm_ = fm + ((wgid % nig) % gsz); pn_ = (wgid % nig) / gsz;
;   };
;   int Lw = blockIdx.x;
;   if (Lw < nwg) {
;     int pm, pn; tile_of(Lw, pm, pn);
;     const char* cA = (const char*)A + (size_t)pm * tstep;
;     const char* cB = (const char*)Bt + (size_t)pn * tstep;
;     f32x4 acc[2][2][4][2];
; #pragma unroll
;     for (int a = 0; a < 2; ++a)
; #pragma unroll
;       for (int b = 0; b < 2; ++b)
; #pragma unroll
;         for (int m = 0; m < 4; ++m)
; #pragma unroll
;           for (int n = 0; n < 2; ++n) acc[a][b][m][n] = zero4();
;     bf16x8 At[4][2], B0[2][2], B1[2][2];
;     G_STAGE(G_SB(0, 0), cB); G_STAGE(G_SA(0, 0), cA); G_STAGE(G_SB(0, 1), cB + hstep); G_STAGE(G_SA(0, 1), cA + hstep);
;     if (wr == 1) G_BAR;
;     G_WAIT_V(4); G_BAR;
;     G_STAGE(G_SB(1, 0), cB + kstep); G_STAGE(G_SA(1, 0), cA + kstep); G_STAGE(G_SB(1, 1), cB + hstep + kstep);
;     G_WAIT_V(6); G_BAR;
.LBB0_310:
	s_andn2_b64 vcc, exec, s[2:3]
	s_mov_b64 s[30:31], 0
	s_cbranch_vccnz .LBB0_362
	s_cmp_gt_i32 s55, 9
	s_cbranch_scc0 .LBB0_323
	v_readlane_b32 s0, v244, 21
	v_readlane_b32 s1, v244, 22
	s_and_b64 s[0:1], s[0:1], exec
	s_movk_i32 s0, 0x110
	s_cselect_b32 s18, s0, 0x100
	v_readlane_b32 s0, v248, 9
	s_waitcnt vmcnt(1)
	v_mbcnt_lo_u32_b32 v0, -1, 0
	v_mbcnt_hi_u32_b32 v0, -1, v0
	s_mul_i32 s19, s18, 22
	v_add_u32_e32 v130, s0, v0
	v_readlane_b32 s0, v248, 0
	s_cmp_ge_i32 s0, s19
	s_cbranch_scc1 .LBB0_327
	v_lshlrev_b32_e32 v0, 4, v130
	v_add_u32_e32 v1, 0x2000, v0
	v_ashrrev_i32_e32 v2, 31, v1
	v_lshrrev_b32_e32 v2, 22, v2
	v_add_u32_e32 v2, v1, v2
	v_ashrrev_i32_e32 v134, 10, v2
	v_mul_i32_i24_e32 v2, 0x400, v134
	v_sub_u32_e32 v1, v1, v2
	v_lshrrev_b32_e32 v2, 4, v1
	v_bitop3_b32 v1, v2, v1, 32 bitop3:0x6c
	v_ashrrev_i32_e32 v2, 31, v1
	v_lshrrev_b32_e32 v2, 26, v2
	v_add_u32_e32 v2, v1, v2
	v_ashrrev_i32_e32 v135, 6, v2
	v_and_b32_e32 v2, 0xc0, v2
	v_sub_u32_e32 v1, v1, v2
	v_ashrrev_i16_sdwa v1, v199, sext(v1) dst_sel:DWORD dst_unused:UNUSED_PAD src0_sel:DWORD src1_sel:BYTE_0
	v_bfe_i32 v137, v1, 0, 16
	v_bfe_i32 v1, v130, 27, 1
	v_lshrrev_b32_e32 v1, 22, v1
	s_lshr_b32 s25, s19, 3
	v_readlane_b32 s0, v248, 35
	v_add_u32_e32 v1, v0, v1
	s_or_b32 s26, s25, 1
	v_readlane_b32 s1, v248, 36
	v_and_b32_e32 v1, 0xfffffc00, v1
	s_and_b64 s[0:1], s[0:1], exec
	v_sub_u32_e32 v0, v0, v1
	s_cselect_b32 s0, s26, s25
	v_readlane_b32 s1, v247, 6
	v_lshrrev_b32_e32 v1, 4, v0
	s_mul_i32 s0, s0, s1
	v_readlane_b32 s1, v247, 9
	v_bitop3_b32 v0, v1, v0, 32 bitop3:0x6c
	s_add_i32 s0, s0, s1
	v_ashrrev_i32_e32 v1, 31, v0
	s_mul_hi_i32 s1, s0, 0x2e8ba2e9
	v_lshrrev_b32_e32 v1, 26, v1
	s_lshr_b32 s2, s1, 31
	s_ashr_i32 s1, s1, 5
	v_add_u32_e32 v1, v0, v1
	v_ashrrev_i32_e32 v2, 31, v130
	s_add_i32 s1, s1, s2
	v_lshlrev_b32_e32 v3, 3, v134
	v_ashrrev_i32_e32 v132, 6, v1
	v_lshrrev_b32_e32 v2, 26, v2
	v_and_b32_e32 v1, 0xc0, v1
	s_lshl_b32 s2, s1, 3
	v_and_b32_e32 v3, 0x1ffff0, v3
	s_waitcnt vmcnt(0)
	v_lshlrev_b32_e32 v4, 5, v134
	v_add_u32_e32 v2, v130, v2
	v_sub_u32_e32 v0, v0, v1
	s_sub_i32 s3, s18, s2
	v_add_u32_e32 v3, v135, v3
	v_and_b32_e32 v136, 32, v4
	v_ashrrev_i32_e32 v133, 6, v2
	v_ashrrev_i16_sdwa v0, v199, sext(v0) dst_sel:DWORD dst_unused:UNUSED_PAD src0_sel:DWORD src1_sel:BYTE_0
	s_min_i32 s3, s3, 8
	v_lshl_or_b32 v3, v3, 10, v136
	v_lshlrev_b32_e32 v2, 3, v133
	v_bfe_i32 v141, v0, 0, 16
	v_cvt_f32_i32_e32 v0, s3
	v_add_lshl_u32 v128, v3, v137, 1
	v_and_b32_e32 v2, 0x1ffff0, v2
	v_lshlrev_b32_e32 v3, 5, v133
	v_add_u32_e32 v2, v132, v2
	v_and_b32_e32 v140, 32, v3
	s_mulk_i32 s1, 0xb0
	v_lshl_or_b32 v2, v2, 10, v140
	s_sub_i32 s5, s0, s1
	v_add_lshl_u32 v176, v2, v141, 1
	v_cvt_f32_i32_e32 v1, s5
	v_rcp_iflag_f32_e32 v2, v0
	s_xor_b32 s0, s5, s3
	s_ashr_i32 s0, s0, 30
	s_or_b32 s4, s0, 1
	v_mul_f32_e32 v2, v1, v2
	v_trunc_f32_e32 v2, v2
	v_fma_f32 v1, -v2, v0, v1
	v_cvt_i32_f32_e32 v2, v2
	v_cmp_ge_f32_e64 s[0:1], |v1|, |v0|
	s_and_b64 s[0:1], s[0:1], exec
	s_cselect_b32 s0, s4, 0
	v_readfirstlane_b32 s1, v2
	s_add_i32 s4, s1, s0
	s_mul_i32 s0, s4, s3
	s_sub_i32 s0, s5, s0
	s_sext_i32_i16 s0, s0
	s_add_i32 s16, s2, s0
	s_ashr_i32 s17, s16, 31
	s_bfe_i64 s[2:3], s[4:5], 0x100000
	v_readlane_b32 s36, v245, 17
	s_lshl_b64 s[0:1], s[16:17], 19
	s_lshl_b64 s[92:93], s[2:3], 19
	v_readlane_b32 s50, v245, 31
	v_readlane_b32 s51, v245, 32
	s_add_u32 s2, s50, s92
	v_readlane_b32 s37, v245, 18
	v_readlane_b32 s38, v245, 19
	v_readlane_b32 s39, v245, 20
	v_readlane_b32 s40, v245, 21
	v_readlane_b32 s41, v245, 22
	v_readlane_b32 s42, v245, 23
	v_readlane_b32 s43, v245, 24
	v_readlane_b32 s44, v245, 25
	v_readlane_b32 s45, v245, 26
	v_readlane_b32 s46, v245, 27
	v_readlane_b32 s47, v245, 28
	v_readlane_b32 s48, v245, 29
	v_readlane_b32 s49, v245, 30
	s_addc_u32 s3, s51, s93
	s_add_i32 s17, s58, 0
	v_mov_b32_e32 v120, v177
	v_mov_b32_e32 v124, v177
	v_mov_b32_e32 v104, v177
	v_mov_b32_e32 v108, v177
	v_mov_b32_e32 v88, v177
	v_mov_b32_e32 v92, v177
	v_mov_b32_e32 v72, v177
	v_mov_b32_e32 v76, v177
	v_mov_b32_e32 v112, v177
	v_mov_b32_e32 v116, v177
	v_mov_b32_e32 v96, v177
	v_mov_b32_e32 v100, v177
	v_mov_b32_e32 v80, v177
	v_mov_b32_e32 v84, v177
	v_mov_b32_e32 v64, v177
	v_mov_b32_e32 v68, v177
	v_mov_b32_e32 v56, v177
	v_mov_b32_e32 v60, v177
	v_mov_b32_e32 v40, v177
	v_mov_b32_e32 v44, v177
	v_mov_b32_e32 v24, v177
	v_mov_b32_e32 v28, v177
	v_mov_b32_e32 v8, v177
	v_mov_b32_e32 v12, v177
	v_mov_b32_e32 v48, v177
	v_mov_b32_e32 v52, v177
	v_mov_b32_e32 v32, v177
	v_mov_b32_e32 v36, v177
	v_mov_b32_e32 v16, v177
	v_mov_b32_e32 v20, v177
	v_mov_b32_e32 v0, v177
	v_mov_b32_e32 v4, v177
	s_add_i32 m0, s17, 0x10000
	v_readlane_b32 s36, v246, 63
	global_load_lds_dwordx4 v176, s[2:3]
	s_add_i32 m0, s17, 0x12000
	v_readlane_b32 s44, v245, 7
	v_readlane_b32 s45, v245, 8
	s_add_u32 s10, s44, s0
	global_load_lds_dwordx4 v128, s[2:3]
	s_addc_u32 s11, s45, s1
	s_mov_b32 m0, s17
	s_add_i32 s89, s17, 0x2000
	global_load_lds_dwordx4 v176, s[10:11]
	s_mov_b32 m0, s89
	s_add_u32 s0, s2, 0x40000
	global_load_lds_dwordx4 v128, s[10:11]
	s_addc_u32 s1, s3, 0
	s_add_i32 m0, s17, 0x14000
	v_readlane_b32 s37, v245, 0
	global_load_lds_dwordx4 v176, s[0:1]
	s_add_i32 m0, s17, 0x16000
	v_readlane_b32 s38, v245, 1
	global_load_lds_dwordx4 v128, s[0:1]
	s_add_u32 s0, s10, 0x40000
	s_addc_u32 s1, s11, 0
	s_add_i32 s88, s17, 0x4000
	s_mov_b32 m0, s88
	s_add_i32 s55, s17, 0x6000
	global_load_lds_dwordx4 v176, s[0:1]
	s_mov_b32 m0, s55
	v_readlane_b32 s39, v245, 2
	global_load_lds_dwordx4 v128, s[0:1]
	v_readlane_b32 s0, v248, 13
	v_readlane_b32 s1, v248, 14
	s_andn2_b64 vcc, exec, s[0:1]
	v_readlane_b32 s40, v245, 3
	v_readlane_b32 s41, v245, 4
	v_readlane_b32 s42, v245, 5
	v_readlane_b32 s43, v245, 6
	v_readlane_b32 s46, v245, 9
	v_readlane_b32 s47, v245, 10
	v_readlane_b32 s48, v245, 11
	v_readlane_b32 s49, v245, 12
	v_readlane_b32 s50, v245, 13
	v_readlane_b32 s51, v245, 14
	s_cbranch_vccnz .LBB0_315
	s_barrier
	s_setprio 1

; #define G_STAGE(bufoff, gbase) do { _Pragma("unroll") for (int _i = 0; _i < 2; ++_i) \
;     __builtin_amdgcn_global_load_lds((const unsigned*)((const char*)(gbase) + voff[_i]), (GLAS unsigned*)(lds + (bufoff) + ldsw + _i * 8192), 16, 0, 0); } while (0)
; #define G_LDA(dst, b, h) do { _Pragma("unroll") for (int m = 0; m < 4; ++m) _Pragma("unroll") for (int k = 0; k < 2; ++k) \
;     dst[m][k] = *(const GLAS bf16x8*)(lds + G_SA(b, h) + aoff + m * 2048 + k * 1024); } while (0)
; #define G_LDB(dst, b, h) do { _Pragma("unroll") for (int n = 0; n < 2; ++n) _Pragma("unroll") for (int k = 0; k < 2; ++k) \
;     dst[n][k] = *(const GLAS bf16x8*)(lds + G_SB(b, h) + boff + n * 2048 + k * 1024); } while (0)
; #define G_MMA(ai, bj, At_, Bt_) do { __builtin_amdgcn_s_setprio(1); \
;     _Pragma("unroll") for (int m = 0; m < 4; ++m) _Pragma("unroll") for (int n = 0; n < 2; ++n) _Pragma("unroll") for (int k = 0; k < 2; ++k) \
;       acc[ai][bj][m][n] = __builtin_amdgcn_mfma_f32_16x16x32_bf16(Bt_[n][k], At_[m][k], acc[ai][bj][m][n], 0, 0, 0); \
;     __builtin_amdgcn_s_setprio(0); } while (0)
; #define G_WAIT_V(n) asm volatile("s_waitcnt vmcnt(" #n ")" ::: "memory")
; #define G_WAIT_L(n) asm volatile("s_waitcnt lgkmcnt(" #n ")" ::: "memory")
; #define G_BAR __builtin_amdgcn_s_barrier()
; __device__ __forceinline__ void gemm_phase(const Params& p, int l, const bf16_t* __restrict__ A, const bf16_t* __restrict__ Bt, int M, int N, int K,
;                            int epi, bf16_t* __restrict__ outp, char* smem, int wvi) {
;     ...
;       for (int t = 0; t < nt; t += 2) {
;         const bool lastt = (t == nt - 2);
;         const char* a1 = cA + (size_t)(t + 1) * kstep;
;         const char* a2 = lastt ? nA : cA + (size_t)(t + 2) * kstep; const char* b2 = lastt ? nB : cB + (size_t)(t + 2) * kstep;
;         const char* a3 = a2 + kstep; const char* b3 = b2 + kstep;
;         G_LDB(B0, 0, 0); G_SCHED; G_LDA(At, 0, 0); G_STAGE(G_SA(1, 1), a1 + hstep);
;         G_WAIT_L(8); G_BAR; G_WAIT_L(0); G_MMA(0, 0, At, B0); G_BAR; G_SCHED;
;         G_LDB(B1, 0, 1); G_STAGE(G_SB(0, 0), b2);
;         G_BAR; G_WAIT_L(0); G_MMA(0, 1, At, B1); G_BAR;
;         G_LDA(At, 0, 1); G_STAGE(G_SA(0, 0), a2);
;         G_BAR; G_WAIT_L(0); G_MMA(1, 0, At, B0); G_BAR; G_SCHED;
;         G_STAGE(G_SB(0, 1), b2 + hstep);
;         G_WAIT_V(6); G_BAR; G_MMA(1, 1, At, B1); G_BAR;
.LBB0_320:
	s_add_u32 s2, s10, 0x100
	s_addc_u32 s3, s11, 0
	s_add_i32 s23, 0, 0x10000
	v_add_u32_e32 v136, s23, v139
	ds_read_b128 v[142:145], v136
	ds_read_b128 v[146:149], v136 offset:1024
	ds_read_b128 v[150:153], v136 offset:2048
	ds_read_b128 v[154:157], v136 offset:3072
	s_cmp_eq_u32 s22, 12
	s_cselect_b32 s29, s9, s3
	s_cselect_b32 s28, s8, s2
	s_cselect_b32 s93, s5, s21
	s_cselect_b32 s92, s1, s7
	v_lshl_add_u64 v[136:137], s[10:11], 0, v[132:133]
	s_add_i32 m0, s17, 0xc000
	ds_read_b128 v[158:161], v140
	ds_read_b128 v[162:165], v140 offset:1024
	ds_read_b128 v[166:169], v140 offset:2048
	ds_read_b128 v[170:173], v140 offset:3072
	ds_read_b128 v[182:185], v140 offset:4096
	ds_read_b128 v[186:189], v140 offset:5120
	ds_read_b128 v[214:217], v140 offset:6144
	ds_read_b128 v[218:221], v140 offset:7168
	global_load_lds_dwordx4 v[136:137], off
	v_lshl_add_u64 v[136:137], s[10:11], 0, v[134:135]
	s_add_i32 m0, s17, 0xe000
	s_nop 0
	global_load_lds_dwordx4 v[136:137], off
	s_waitcnt lgkmcnt(8)
	s_barrier
	s_waitcnt lgkmcnt(0)
	s_waitcnt lgkmcnt(0)
	v_mfma_f32_16x16x32_bf16 v[120:123], v[142:145], v[158:161], v[120:123]
	v_mfma_f32_16x16x32_bf16 v[124:127], v[150:153], v[158:161], v[124:127]
	v_mfma_f32_16x16x32_bf16 v[104:107], v[142:145], v[166:169], v[104:107]
	v_mfma_f32_16x16x32_bf16 v[108:111], v[150:153], v[166:169], v[108:111]
	v_mfma_f32_16x16x32_bf16 v[88:91], v[142:145], v[182:185], v[88:91]
	v_mfma_f32_16x16x32_bf16 v[92:95], v[150:153], v[182:185], v[92:95]
	v_mfma_f32_16x16x32_bf16 v[72:75], v[142:145], v[214:217], v[72:75]
	v_mfma_f32_16x16x32_bf16 v[76:79], v[150:153], v[214:217], v[76:79]
	v_mfma_f32_16x16x32_bf16 v[120:123], v[146:149], v[162:165], v[120:123]
	v_mfma_f32_16x16x32_bf16 v[124:127], v[154:157], v[162:165], v[124:127]
	v_mfma_f32_16x16x32_bf16 v[104:107], v[146:149], v[170:173], v[104:107]
	v_mfma_f32_16x16x32_bf16 v[108:111], v[154:157], v[170:173], v[108:111]
	v_mfma_f32_16x16x32_bf16 v[88:91], v[146:149], v[186:189], v[88:91]
	v_mfma_f32_16x16x32_bf16 v[92:95], v[154:157], v[186:189], v[92:95]
	v_mfma_f32_16x16x32_bf16 v[72:75], v[146:149], v[218:221], v[72:75]
	v_mfma_f32_16x16x32_bf16 v[76:79], v[154:157], v[218:221], v[76:79]
	s_barrier
	s_add_i32 s24, 0, 0x14000
	v_add_u32_e32 v136, s24, v139
	s_add_i32 s10, s23, s58
	ds_read_b128 v[222:225], v136
	ds_read_b128 v[226:229], v136 offset:1024
	ds_read_b128 v[230:233], v136 offset:2048
	ds_read_b128 v[234:237], v136 offset:3072
	v_lshl_add_u64 v[136:137], s[92:93], 0, v[176:177]
	s_mov_b32 m0, s10
	v_lshl_add_u64 v[174:175], s[92:93], 0, v[128:129]
	global_load_lds_dwordx4 v[136:137], off
	s_add_i32 m0, s10, 0x2000
	s_nop 0
	global_load_lds_dwordx4 v[174:175], off
	s_barrier
	s_waitcnt lgkmcnt(0)
	s_waitcnt lgkmcnt(0)
	v_mfma_f32_16x16x32_bf16 v[112:115], v[222:225], v[158:161], v[112:115]
	v_mfma_f32_16x16x32_bf16 v[116:119], v[230:233], v[158:161], v[116:119]
	v_mfma_f32_16x16x32_bf16 v[96:99], v[222:225], v[166:169], v[96:99]
	v_mfma_f32_16x16x32_bf16 v[100:103], v[230:233], v[166:169], v[100:103]
	v_mfma_f32_16x16x32_bf16 v[80:83], v[222:225], v[182:185], v[80:83]
	v_mfma_f32_16x16x32_bf16 v[84:87], v[230:233], v[182:185], v[84:87]
	v_mfma_f32_16x16x32_bf16 v[64:67], v[222:225], v[214:217], v[64:67]
	v_mfma_f32_16x16x32_bf16 v[68:71], v[230:233], v[214:217], v[68:71]
	v_mfma_f32_16x16x32_bf16 v[112:115], v[226:229], v[162:165], v[112:115]
	v_mfma_f32_16x16x32_bf16 v[116:119], v[234:237], v[162:165], v[116:119]
	v_mfma_f32_16x16x32_bf16 v[96:99], v[226:229], v[170:173], v[96:99]
	v_mfma_f32_16x16x32_bf16 v[100:103], v[234:237], v[170:173], v[100:103]
	v_mfma_f32_16x16x32_bf16 v[80:83], v[226:229], v[186:189], v[80:83]
	v_mfma_f32_16x16x32_bf16 v[84:87], v[234:237], v[186:189], v[84:87]
	v_mfma_f32_16x16x32_bf16 v[64:67], v[226:229], v[218:221], v[64:67]
	v_mfma_f32_16x16x32_bf16 v[68:71], v[234:237], v[218:221], v[68:71]
	s_mov_b32 m0, s17
	v_lshl_add_u64 v[190:191], s[28:29], 0, v[176:177]
	s_barrier
	ds_read_b128 v[158:161], v140 offset:16384
	ds_read_b128 v[162:165], v140 offset:17408
	ds_read_b128 v[166:169], v140 offset:18432
	ds_read_b128 v[170:173], v140 offset:19456
	ds_read_b128 v[182:185], v140 offset:20480
	ds_read_b128 v[186:189], v140 offset:21504
	ds_read_b128 v[214:217], v140 offset:22528
	ds_read_b128 v[218:221], v140 offset:23552
	global_load_lds_dwordx4 v[190:191], off
	v_lshl_add_u64 v[238:239], s[28:29], 0, v[128:129]
	s_mov_b32 m0, s89
	s_nop 0
	global_load_lds_dwordx4 v[238:239], off
	s_barrier
	s_waitcnt lgkmcnt(0)
	s_waitcnt lgkmcnt(0)
	v_mfma_f32_16x16x32_bf16 v[56:59], v[142:145], v[158:161], v[56:59]
	v_mfma_f32_16x16x32_bf16 v[60:63], v[150:153], v[158:161], v[60:63]
	v_mfma_f32_16x16x32_bf16 v[40:43], v[142:145], v[166:169], v[40:43]
	v_mfma_f32_16x16x32_bf16 v[44:47], v[150:153], v[166:169], v[44:47]
	v_mfma_f32_16x16x32_bf16 v[24:27], v[142:145], v[182:185], v[24:27]
	v_mfma_f32_16x16x32_bf16 v[28:31], v[150:153], v[182:185], v[28:31]
	v_mfma_f32_16x16x32_bf16 v[8:11], v[142:145], v[214:217], v[8:11]
	v_mfma_f32_16x16x32_bf16 v[12:15], v[150:153], v[214:217], v[12:15]
	v_mfma_f32_16x16x32_bf16 v[56:59], v[146:149], v[162:165], v[56:59]
	v_mfma_f32_16x16x32_bf16 v[60:63], v[154:157], v[162:165], v[60:63]
	v_mfma_f32_16x16x32_bf16 v[40:43], v[146:149], v[170:173], v[40:43]
	v_mfma_f32_16x16x32_bf16 v[44:47], v[154:157], v[170:173], v[44:47]
	v_mfma_f32_16x16x32_bf16 v[24:27], v[146:149], v[186:189], v[24:27]
	v_mfma_f32_16x16x32_bf16 v[28:31], v[154:157], v[186:189], v[28:31]
	v_mfma_f32_16x16x32_bf16 v[8:11], v[146:149], v[218:221], v[8:11]
	v_mfma_f32_16x16x32_bf16 v[12:15], v[154:157], v[218:221], v[12:15]
	s_barrier
; #define G_STAGE(bufoff, gbase) do { _Pragma("unroll") for (int _i = 0; _i < 2; ++_i) \
;     __builtin_amdgcn_global_load_lds((const unsigned*)((const char*)(gbase) + voff[_i]), (GLAS unsigned*)(lds + (bufoff) + ldsw + _i * 8192), 16, 0, 0); } while (0)
; #define G_LDA(dst, b, h) do { _Pragma("unroll") for (int m = 0; m < 4; ++m) _Pragma("unroll") for (int k = 0; k < 2; ++k) \
;     dst[m][k] = *(const GLAS bf16x8*)(lds + G_SA(b, h) + aoff + m * 2048 + k * 1024); } while (0)
; #define G_LDB(dst, b, h) do { _Pragma("unroll") for (int n = 0; n < 2; ++n) _Pragma("unroll") for (int k = 0; k < 2; ++k) \
;     dst[n][k] = *(const GLAS bf16x8*)(lds + G_SB(b, h) + boff + n * 2048 + k * 1024); } while (0)
; #define G_MMA(ai, bj, At_, Bt_) do { __builtin_amdgcn_s_setprio(1); \
;     _Pragma("unroll") for (int m = 0; m < 4; ++m) _Pragma("unroll") for (int n = 0; n < 2; ++n) _Pragma("unroll") for (int k = 0; k < 2; ++k) \
;       acc[ai][bj][m][n] = __builtin_amdgcn_mfma_f32_16x16x32_bf16(Bt_[n][k], At_[m][k], acc[ai][bj][m][n], 0, 0, 0); \
;     __builtin_amdgcn_s_setprio(0); } while (0)
; #define G_WAIT_V(n) asm volatile("s_waitcnt vmcnt(" #n ")" ::: "memory")
; #define G_WAIT_L(n) asm volatile("s_waitcnt lgkmcnt(" #n ")" ::: "memory")
; #define G_BAR __builtin_amdgcn_s_barrier()
; #define G_SCHED __builtin_amdgcn_sched_barrier(0)
; __device__ __forceinline__ void gemm_phase(const Params& p, int l, const bf16_t* __restrict__ A, const bf16_t* __restrict__ Bt, int M, int N, int K,
;                            int epi, bf16_t* __restrict__ outp, char* smem, int wvi) {
;     ...
;         G_STAGE(G_SB(0, 1), b2 + hstep);
;         G_WAIT_V(6); G_BAR; G_MMA(1, 1, At, B1); G_BAR;
;         G_LDB(B0, 1, 0); G_SCHED; G_LDA(At, 1, 0); G_STAGE(G_SA(0, 1), a2 + hstep);
;         G_WAIT_L(8); G_BAR; G_WAIT_L(0); G_MMA(0, 0, At, B0); G_BAR; G_SCHED;
;         G_LDB(B1, 1, 1); G_STAGE(G_SB(1, 0), b3);
;         G_BAR; G_WAIT_L(0); G_MMA(0, 1, At, B1); G_BAR;
;         G_LDA(At, 1, 1); G_STAGE(G_SA(1, 0), a3);
;         G_BAR; G_WAIT_L(0); G_MMA(1, 0, At, B0); G_BAR; G_SCHED;
;         G_STAGE(G_SB(1, 1), b3 + hstep);
	s_add_u32 s10, s92, 0x40000
	s_addc_u32 s11, s93, 0
	s_add_i32 s23, s24, s58
	v_lshl_add_u64 v[142:143], s[10:11], 0, v[176:177]
	s_mov_b32 m0, s23
	s_nop 0
	global_load_lds_dwordx4 v[142:143], off
	v_lshl_add_u64 v[142:143], s[10:11], 0, v[128:129]
	s_add_i32 m0, s23, 0x2000
	s_nop 0
	global_load_lds_dwordx4 v[142:143], off
	s_waitcnt vmcnt(6)
	s_barrier
	v_mfma_f32_16x16x32_bf16 v[48:51], v[222:225], v[158:161], v[48:51]
	v_mfma_f32_16x16x32_bf16 v[52:55], v[230:233], v[158:161], v[52:55]
	v_mfma_f32_16x16x32_bf16 v[32:35], v[222:225], v[166:169], v[32:35]
	v_mfma_f32_16x16x32_bf16 v[36:39], v[230:233], v[166:169], v[36:39]
	v_mfma_f32_16x16x32_bf16 v[16:19], v[222:225], v[182:185], v[16:19]
	v_mfma_f32_16x16x32_bf16 v[20:23], v[230:233], v[182:185], v[20:23]
	v_mfma_f32_16x16x32_bf16 v[0:3], v[222:225], v[214:217], v[0:3]
	v_mfma_f32_16x16x32_bf16 v[4:7], v[230:233], v[214:217], v[4:7]
	v_mfma_f32_16x16x32_bf16 v[48:51], v[226:229], v[162:165], v[48:51]
	v_mfma_f32_16x16x32_bf16 v[52:55], v[234:237], v[162:165], v[52:55]
	v_mfma_f32_16x16x32_bf16 v[32:35], v[226:229], v[170:173], v[32:35]
	v_mfma_f32_16x16x32_bf16 v[36:39], v[234:237], v[170:173], v[36:39]
	v_mfma_f32_16x16x32_bf16 v[16:19], v[226:229], v[186:189], v[16:19]
	v_mfma_f32_16x16x32_bf16 v[20:23], v[234:237], v[186:189], v[20:23]
	v_mfma_f32_16x16x32_bf16 v[0:3], v[226:229], v[218:221], v[0:3]
	v_mfma_f32_16x16x32_bf16 v[4:7], v[234:237], v[218:221], v[4:7]
	s_add_i32 s23, 0, 0x18000
	v_add_u32_e32 v141, s23, v139
	s_barrier
	ds_read_b128 v[142:145], v141
	ds_read_b128 v[146:149], v141 offset:1024
	ds_read_b128 v[150:153], v141 offset:2048
	ds_read_b128 v[154:157], v141 offset:3072
	s_add_u32 s10, s28, 0x40000
	s_addc_u32 s11, s29, 0
	s_mov_b32 m0, s88
	v_lshl_add_u64 v[222:223], s[10:11], 0, v[176:177]
	ds_read_b128 v[158:161], v140 offset:32768
	ds_read_b128 v[162:165], v140 offset:33792
	ds_read_b128 v[166:169], v140 offset:34816
	ds_read_b128 v[170:173], v140 offset:35840
	ds_read_b128 v[182:185], v140 offset:36864
	ds_read_b128 v[186:189], v140 offset:37888
	ds_read_b128 v[214:217], v140 offset:38912
	ds_read_b128 v[218:221], v140 offset:39936
	global_load_lds_dwordx4 v[222:223], off
	v_lshl_add_u64 v[222:223], s[10:11], 0, v[128:129]
	s_mov_b32 m0, s55
	s_nop 0
	global_load_lds_dwordx4 v[222:223], off
	s_waitcnt lgkmcnt(8)
	s_barrier
	s_waitcnt lgkmcnt(0)
	s_waitcnt lgkmcnt(0)
	v_mfma_f32_16x16x32_bf16 v[120:123], v[142:145], v[158:161], v[120:123]
	v_mfma_f32_16x16x32_bf16 v[124:127], v[150:153], v[158:161], v[124:127]
	v_mfma_f32_16x16x32_bf16 v[104:107], v[142:145], v[166:169], v[104:107]
	v_mfma_f32_16x16x32_bf16 v[108:111], v[150:153], v[166:169], v[108:111]
	v_mfma_f32_16x16x32_bf16 v[88:91], v[142:145], v[182:185], v[88:91]
	v_mfma_f32_16x16x32_bf16 v[92:95], v[150:153], v[182:185], v[92:95]
	v_mfma_f32_16x16x32_bf16 v[72:75], v[142:145], v[214:217], v[72:75]
	v_mfma_f32_16x16x32_bf16 v[76:79], v[150:153], v[214:217], v[76:79]
	v_mfma_f32_16x16x32_bf16 v[120:123], v[146:149], v[162:165], v[120:123]
	v_mfma_f32_16x16x32_bf16 v[124:127], v[154:157], v[162:165], v[124:127]
	v_mfma_f32_16x16x32_bf16 v[104:107], v[146:149], v[170:173], v[104:107]
	v_mfma_f32_16x16x32_bf16 v[108:111], v[154:157], v[170:173], v[108:111]
	v_mfma_f32_16x16x32_bf16 v[88:91], v[146:149], v[186:189], v[88:91]
	v_mfma_f32_16x16x32_bf16 v[92:95], v[154:157], v[186:189], v[92:95]
	v_mfma_f32_16x16x32_bf16 v[72:75], v[146:149], v[218:221], v[72:75]
	v_mfma_f32_16x16x32_bf16 v[76:79], v[154:157], v[218:221], v[76:79]
	s_barrier
	s_add_i32 s24, 0, 0x1c000
	s_add_i32 s10, s23, s58
	v_add_u32_e32 v141, s24, v139
	v_lshl_add_u64 v[136:137], v[136:137], 0, s[64:65]
	s_mov_b32 m0, s10
	ds_read_b128 v[222:225], v141
	ds_read_b128 v[226:229], v141 offset:1024
	ds_read_b128 v[230:233], v141 offset:2048
	ds_read_b128 v[234:237], v141 offset:3072
	global_load_lds_dwordx4 v[136:137], off
	v_lshl_add_u64 v[136:137], v[174:175], 0, s[64:65]
	s_add_i32 m0, s10, 0x2000
	s_nop 0
	global_load_lds_dwordx4 v[136:137], off
	s_barrier
	s_waitcnt lgkmcnt(0)
	s_waitcnt lgkmcnt(0)
	v_mfma_f32_16x16x32_bf16 v[112:115], v[222:225], v[158:161], v[112:115]
	v_mfma_f32_16x16x32_bf16 v[116:119], v[230:233], v[158:161], v[116:119]
	v_mfma_f32_16x16x32_bf16 v[96:99], v[222:225], v[166:169], v[96:99]
	v_mfma_f32_16x16x32_bf16 v[100:103], v[230:233], v[166:169], v[100:103]
	v_mfma_f32_16x16x32_bf16 v[80:83], v[222:225], v[182:185], v[80:83]
	v_mfma_f32_16x16x32_bf16 v[84:87], v[230:233], v[182:185], v[84:87]
	v_mfma_f32_16x16x32_bf16 v[64:67], v[222:225], v[214:217], v[64:67]
	v_mfma_f32_16x16x32_bf16 v[68:71], v[230:233], v[214:217], v[68:71]
	v_mfma_f32_16x16x32_bf16 v[112:115], v[226:229], v[162:165], v[112:115]
	v_mfma_f32_16x16x32_bf16 v[116:119], v[234:237], v[162:165], v[116:119]
	v_mfma_f32_16x16x32_bf16 v[96:99], v[226:229], v[170:173], v[96:99]
	v_mfma_f32_16x16x32_bf16 v[100:103], v[234:237], v[170:173], v[100:103]
	v_mfma_f32_16x16x32_bf16 v[80:83], v[226:229], v[186:189], v[80:83]
	v_mfma_f32_16x16x32_bf16 v[84:87], v[234:237], v[186:189], v[84:87]
	v_mfma_f32_16x16x32_bf16 v[64:67], v[226:229], v[218:221], v[64:67]
	v_mfma_f32_16x16x32_bf16 v[68:71], v[234:237], v[218:221], v[68:71]
	s_mov_b32 m0, s30
	v_lshl_add_u64 v[136:137], v[190:191], 0, s[64:65]
	s_barrier
	ds_read_b128 v[158:161], v140 offset:49152
	ds_read_b128 v[162:165], v140 offset:50176
	ds_read_b128 v[166:169], v140 offset:51200
	ds_read_b128 v[170:173], v140 offset:52224
	ds_read_b128 v[182:185], v140 offset:53248
	ds_read_b128 v[186:189], v140 offset:54272
	ds_read_b128 v[214:217], v140 offset:55296
	ds_read_b128 v[218:221], v140 offset:56320
	global_load_lds_dwordx4 v[136:137], off
	v_lshl_add_u64 v[136:137], v[238:239], 0, s[64:65]
	s_mov_b32 m0, s31
	s_nop 0
	global_load_lds_dwordx4 v[136:137], off
	s_barrier
; __device__ __forceinline__ u32x4 mk4(unsigned a, unsigned b, unsigned c, unsigned d) { return (u32x4){a, b, c, d}; }
; __device__ __forceinline__ float silu_f(float x) { return x * __builtin_amdgcn_rcpf(1.f + __expf(-x)); }
; #define G_STAGE(bufoff, gbase) do { _Pragma("unroll") for (int _i = 0; _i < 2; ++_i) \
;     __builtin_amdgcn_global_load_lds((const unsigned*)((const char*)(gbase) + voff[_i]), (GLAS unsigned*)(lds + (bufoff) + ldsw + _i * 8192), 16, 0, 0); } while (0)
; #define G_LDA(dst, b, h) do { _Pragma("unroll") for (int m = 0; m < 4; ++m) _Pragma("unroll") for (int k = 0; k < 2; ++k) \
;     dst[m][k] = *(const GLAS bf16x8*)(lds + G_SA(b, h) + aoff + m * 2048 + k * 1024); } while (0)
; #define G_MMA(ai, bj, At_, Bt_) do { __builtin_amdgcn_s_setprio(1); \
;     _Pragma("unroll") for (int m = 0; m < 4; ++m) _Pragma("unroll") for (int n = 0; n < 2; ++n) _Pragma("unroll") for (int k = 0; k < 2; ++k) \
;       acc[ai][bj][m][n] = __builtin_amdgcn_mfma_f32_16x16x32_bf16(Bt_[n][k], At_[m][k], acc[ai][bj][m][n], 0, 0, 0); \
;     __builtin_amdgcn_s_setprio(0); } while (0)
; #define G_WAIT_V(n) asm volatile("s_waitcnt vmcnt(" #n ")" ::: "memory")
; #define G_BAR __builtin_amdgcn_s_barrier()
; __device__ __forceinline__ void gemm_phase(const Params& p, int l, const bf16_t* __restrict__ A, const bf16_t* __restrict__ Bt, int M, int N, int K,
;                            int epi, bf16_t* __restrict__ outp, char* smem, int wvi) {
;     ...
;         G_BAR; G_WAIT_L(0); G_MMA(0, 1, At, B1); G_BAR;
;         G_LDA(At, 1, 1); G_STAGE(G_SA(1, 0), a3);
;         G_BAR; G_WAIT_L(0); G_MMA(1, 0, At, B0); G_BAR; G_SCHED;
;         G_STAGE(G_SB(1, 1), b3 + hstep);
;         G_WAIT_V(6); G_BAR; G_MMA(1, 1, At, B1); G_BAR;
;     ...
;       for (int ai = 0; ai < 2; ++ai)
; #pragma unroll
;         for (int m = 0; m < 4; ++m) {
;           bf16_t* rp = outp + (size_t)(r0 + ai * GHALF + m * 16) * DFF + pn * 128 + wc * 32 + fq * 8;
;           unsigned pk[4];
; #pragma unroll
;           for (int bj = 0; bj < 2; ++bj) {
;             const f32x4 g = acc[ai][bj][m][0], u = acc[ai][bj][m][1];
;             const float o0 = silu_f(g[0]) * u[0], o1 = silu_f(g[1]) * u[1], o2 = silu_f(g[2]) * u[2], o3 = silu_f(g[3]) * u[3];
;             pk[2 * bj] = pk2(o0, o1); pk[2 * bj + 1] = pk2(o2, o3);
;           }
;           *reinterpret_cast<u32x4*>(rp) = mk4(pk[0], pk[1], pk[2], pk[3]);
;         }
	s_waitcnt lgkmcnt(0)
	s_waitcnt lgkmcnt(0)
	v_mfma_f32_16x16x32_bf16 v[56:59], v[142:145], v[158:161], v[56:59]
	v_mfma_f32_16x16x32_bf16 v[60:63], v[150:153], v[158:161], v[60:63]
	v_mfma_f32_16x16x32_bf16 v[40:43], v[142:145], v[166:169], v[40:43]
	v_mfma_f32_16x16x32_bf16 v[44:47], v[150:153], v[166:169], v[44:47]
	v_mfma_f32_16x16x32_bf16 v[24:27], v[142:145], v[182:185], v[24:27]
	v_mfma_f32_16x16x32_bf16 v[28:31], v[150:153], v[182:185], v[28:31]
	v_mfma_f32_16x16x32_bf16 v[8:11], v[142:145], v[214:217], v[8:11]
	v_mfma_f32_16x16x32_bf16 v[12:15], v[150:153], v[214:217], v[12:15]
	v_mfma_f32_16x16x32_bf16 v[56:59], v[146:149], v[162:165], v[56:59]
	v_mfma_f32_16x16x32_bf16 v[60:63], v[154:157], v[162:165], v[60:63]
	v_mfma_f32_16x16x32_bf16 v[40:43], v[146:149], v[170:173], v[40:43]
	v_mfma_f32_16x16x32_bf16 v[44:47], v[154:157], v[170:173], v[44:47]
	v_mfma_f32_16x16x32_bf16 v[24:27], v[146:149], v[186:189], v[24:27]
	v_mfma_f32_16x16x32_bf16 v[28:31], v[154:157], v[186:189], v[28:31]
	v_mfma_f32_16x16x32_bf16 v[8:11], v[146:149], v[218:221], v[8:11]
	v_mfma_f32_16x16x32_bf16 v[12:15], v[154:157], v[218:221], v[12:15]
	s_barrier
	s_add_u32 s10, s92, 0x40080
	s_addc_u32 s11, s93, 0
	s_add_i32 s23, s24, s58
	v_lshl_add_u64 v[136:137], s[10:11], 0, v[176:177]
	s_mov_b32 m0, s23
	s_nop 0
	global_load_lds_dwordx4 v[136:137], off
	v_lshl_add_u64 v[136:137], s[10:11], 0, v[128:129]
	s_add_i32 m0, s23, 0x2000
	s_nop 0
	global_load_lds_dwordx4 v[136:137], off
	s_waitcnt vmcnt(6)
	s_barrier
	v_mfma_f32_16x16x32_bf16 v[48:51], v[222:225], v[158:161], v[48:51]
	v_mfma_f32_16x16x32_bf16 v[52:55], v[230:233], v[158:161], v[52:55]
	v_mfma_f32_16x16x32_bf16 v[32:35], v[222:225], v[166:169], v[32:35]
	v_mfma_f32_16x16x32_bf16 v[36:39], v[230:233], v[166:169], v[36:39]
	v_mfma_f32_16x16x32_bf16 v[16:19], v[222:225], v[182:185], v[16:19]
	v_mfma_f32_16x16x32_bf16 v[20:23], v[230:233], v[182:185], v[20:23]
	v_mfma_f32_16x16x32_bf16 v[0:3], v[222:225], v[214:217], v[0:3]
	v_mfma_f32_16x16x32_bf16 v[4:7], v[230:233], v[214:217], v[4:7]
	v_mfma_f32_16x16x32_bf16 v[48:51], v[226:229], v[162:165], v[48:51]
	v_mfma_f32_16x16x32_bf16 v[52:55], v[234:237], v[162:165], v[52:55]
	v_mfma_f32_16x16x32_bf16 v[32:35], v[226:229], v[170:173], v[32:35]
	v_mfma_f32_16x16x32_bf16 v[36:39], v[234:237], v[170:173], v[36:39]
	v_mfma_f32_16x16x32_bf16 v[16:19], v[226:229], v[186:189], v[16:19]
	v_mfma_f32_16x16x32_bf16 v[20:23], v[234:237], v[186:189], v[20:23]
	v_mfma_f32_16x16x32_bf16 v[0:3], v[226:229], v[218:221], v[0:3]
	v_mfma_f32_16x16x32_bf16 v[4:7], v[234:237], v[218:221], v[4:7]
	s_add_i32 s22, s22, 2
	s_add_u32 s7, s7, 0x100
	s_addc_u32 s21, s21, 0
	s_cmp_gt_u32 s22, 13
	s_mov_b64 s[10:11], s[2:3]
	s_barrier
	s_cbranch_scc0 .LBB0_320
	v_mul_f32_e32 v142, 0xbfb8aa3b, v120
	v_mul_f32_e32 v143, 0xbfb8aa3b, v121
	v_exp_f32_e32 v142, v142
	v_exp_f32_e32 v143, v143
	s_lshl_b32 s0, s0, 7
	s_ashr_i32 s1, s0, 31
	v_add_f32_e32 v142, 1.0, v142
	v_add_f32_e32 v143, 1.0, v143
	v_rcp_f32_e32 v142, v142
	v_rcp_f32_e32 v143, v143
	v_lshl_add_u32 v141, s16, 8, v138
	v_lshl_add_u64 v[136:137], s[0:1], 1, v[130:131]
	s_movk_i32 s2, 0x1600
	v_pk_mul_f32 v[120:121], v[120:121], v[142:143]
	s_and_b64 vcc, exec, s[14:15]
	v_pk_mul_f32 v[120:121], v[124:125], v[120:121]
	v_mul_f32_e32 v124, 0xbfb8aa3b, v122
	v_mul_f32_e32 v125, 0xbfb8aa3b, v123
	v_exp_f32_e32 v124, v124
	v_exp_f32_e32 v125, v125
	v_cvt_pk_bf16_f32 v120, v120, v121
	v_add_f32_e32 v124, 1.0, v124
	v_add_f32_e32 v125, 1.0, v125
	v_rcp_f32_e32 v124, v124
	v_rcp_f32_e32 v125, v125
	s_nop 0
	v_pk_mul_f32 v[122:123], v[122:123], v[124:125]
	s_nop 0
	v_pk_mul_f32 v[122:123], v[126:127], v[122:123]
	s_nop 0
	v_cvt_pk_bf16_f32 v121, v122, v123
	v_mul_f32_e32 v122, 0xbfb8aa3b, v112
	v_mul_f32_e32 v123, 0xbfb8aa3b, v113
	v_exp_f32_e32 v122, v122
	v_exp_f32_e32 v123, v123
	v_add_f32_e32 v122, 1.0, v122
	v_add_f32_e32 v123, 1.0, v123
	v_rcp_f32_e32 v122, v122
	v_rcp_f32_e32 v123, v123
	s_nop 0
	v_pk_mul_f32 v[112:113], v[112:113], v[122:123]
	s_nop 0
	v_pk_mul_f32 v[112:113], v[116:117], v[112:113]
	v_mul_f32_e32 v116, 0xbfb8aa3b, v114
	v_mul_f32_e32 v117, 0xbfb8aa3b, v115
	v_exp_f32_e32 v116, v116
	v_exp_f32_e32 v117, v117
	v_cvt_pk_bf16_f32 v122, v112, v113
	v_mad_i64_i32 v[112:113], s[0:1], v141, s2, v[136:137]
	v_add_f32_e32 v116, 1.0, v116
	v_add_f32_e32 v117, 1.0, v117
	v_rcp_f32_e32 v116, v116
	v_rcp_f32_e32 v117, v117
	s_nop 0
	v_pk_mul_f32 v[114:115], v[114:115], v[116:117]
	s_nop 0
	v_pk_mul_f32 v[114:115], v[118:119], v[114:115]
	s_nop 0
	v_cvt_pk_bf16_f32 v123, v114, v115
	global_store_dwordx4 v[112:113], v[120:123], off
	v_mul_f32_e32 v112, 0xbfb8aa3b, v104
	v_mul_f32_e32 v113, 0xbfb8aa3b, v105
	v_exp_f32_e32 v112, v112
	v_exp_f32_e32 v113, v113
	v_or_b32_e32 v114, 16, v141
	v_add_f32_e32 v112, 1.0, v112
	v_add_f32_e32 v113, 1.0, v113
	v_rcp_f32_e32 v112, v112
	v_rcp_f32_e32 v113, v113
	s_nop 0
	v_pk_mul_f32 v[104:105], v[104:105], v[112:113]
	s_nop 0
	v_pk_mul_f32 v[104:105], v[108:109], v[104:105]
	v_mul_f32_e32 v108, 0xbfb8aa3b, v106
	v_mul_f32_e32 v109, 0xbfb8aa3b, v107
	v_exp_f32_e32 v108, v108
	v_exp_f32_e32 v109, v109
	v_cvt_pk_bf16_f32 v104, v104, v105
	v_add_f32_e32 v108, 1.0, v108
	v_add_f32_e32 v109, 1.0, v109
	v_rcp_f32_e32 v108, v108
	v_rcp_f32_e32 v109, v109
	s_nop 0
	v_pk_mul_f32 v[106:107], v[106:107], v[108:109]
	s_nop 0
	v_pk_mul_f32 v[106:107], v[110:111], v[106:107]
	s_nop 0
	v_cvt_pk_bf16_f32 v105, v106, v107
	v_mul_f32_e32 v106, 0xbfb8aa3b, v96
	v_mul_f32_e32 v107, 0xbfb8aa3b, v97
	v_exp_f32_e32 v106, v106
	v_exp_f32_e32 v107, v107
	v_add_f32_e32 v106, 1.0, v106
	v_add_f32_e32 v107, 1.0, v107
; __device__ __forceinline__ u32x4 mk4(unsigned a, unsigned b, unsigned c, unsigned d) { return (u32x4){a, b, c, d}; }
; __device__ __forceinline__ float silu_f(float x) { return x * __builtin_amdgcn_rcpf(1.f + __expf(-x)); }
; __device__ __forceinline__ void gemm_phase(const Params& p, int l, const bf16_t* __restrict__ A, const bf16_t* __restrict__ Bt, int M, int N, int K,
;                            int epi, bf16_t* __restrict__ outp, char* smem, int wvi) {
;     ...
;       for (int ai = 0; ai < 2; ++ai)
; #pragma unroll
;         for (int m = 0; m < 4; ++m) {
;           bf16_t* rp = outp + (size_t)(r0 + ai * GHALF + m * 16) * DFF + pn * 128 + wc * 32 + fq * 8;
;           unsigned pk[4];
; #pragma unroll
;           for (int bj = 0; bj < 2; ++bj) {
;             const f32x4 g = acc[ai][bj][m][0], u = acc[ai][bj][m][1];
;             const float o0 = silu_f(g[0]) * u[0], o1 = silu_f(g[1]) * u[1], o2 = silu_f(g[2]) * u[2], o3 = silu_f(g[3]) * u[3];
;             pk[2 * bj] = pk2(o0, o1); pk[2 * bj + 1] = pk2(o2, o3);
;           }
;           *reinterpret_cast<u32x4*>(rp) = mk4(pk[0], pk[1], pk[2], pk[3]);
;         }
	v_rcp_f32_e32 v106, v106
	v_rcp_f32_e32 v107, v107
	s_nop 0
	v_pk_mul_f32 v[96:97], v[96:97], v[106:107]
	s_nop 0
	v_pk_mul_f32 v[96:97], v[100:101], v[96:97]
	v_mul_f32_e32 v100, 0xbfb8aa3b, v98
	v_mul_f32_e32 v101, 0xbfb8aa3b, v99
	v_exp_f32_e32 v100, v100
	v_exp_f32_e32 v101, v101
	v_cvt_pk_bf16_f32 v106, v96, v97
	v_mad_i64_i32 v[96:97], s[0:1], v114, s2, v[136:137]
	v_add_f32_e32 v100, 1.0, v100
	v_add_f32_e32 v101, 1.0, v101
	v_rcp_f32_e32 v100, v100
	v_rcp_f32_e32 v101, v101
	s_nop 0
	v_pk_mul_f32 v[98:99], v[98:99], v[100:101]
	s_nop 0
	v_pk_mul_f32 v[98:99], v[102:103], v[98:99]
	s_nop 0
	v_cvt_pk_bf16_f32 v107, v98, v99
	global_store_dwordx4 v[96:97], v[104:107], off
	v_mul_f32_e32 v96, 0xbfb8aa3b, v88
	v_mul_f32_e32 v97, 0xbfb8aa3b, v89
	v_exp_f32_e32 v96, v96
	v_exp_f32_e32 v97, v97
	v_or_b32_e32 v98, 32, v141
	v_add_f32_e32 v96, 1.0, v96
	v_add_f32_e32 v97, 1.0, v97
	v_rcp_f32_e32 v96, v96
	v_rcp_f32_e32 v97, v97
	s_nop 0
	v_pk_mul_f32 v[88:89], v[88:89], v[96:97]
	s_nop 0
	v_pk_mul_f32 v[88:89], v[92:93], v[88:89]
	v_mul_f32_e32 v92, 0xbfb8aa3b, v90
	v_mul_f32_e32 v93, 0xbfb8aa3b, v91
	v_exp_f32_e32 v92, v92
	v_exp_f32_e32 v93, v93
	v_cvt_pk_bf16_f32 v88, v88, v89
	v_add_f32_e32 v92, 1.0, v92
	v_add_f32_e32 v93, 1.0, v93
	v_rcp_f32_e32 v92, v92
	v_rcp_f32_e32 v93, v93
	s_nop 0
	v_pk_mul_f32 v[90:91], v[90:91], v[92:93]
	s_nop 0
	v_pk_mul_f32 v[90:91], v[94:95], v[90:91]
	s_nop 0
	v_cvt_pk_bf16_f32 v89, v90, v91
	v_mul_f32_e32 v90, 0xbfb8aa3b, v80
	v_mul_f32_e32 v91, 0xbfb8aa3b, v81
	v_exp_f32_e32 v90, v90
	v_exp_f32_e32 v91, v91
	v_add_f32_e32 v90, 1.0, v90
	v_add_f32_e32 v91, 1.0, v91
	v_rcp_f32_e32 v90, v90
	v_rcp_f32_e32 v91, v91
	s_nop 0
	v_pk_mul_f32 v[80:81], v[80:81], v[90:91]
	s_nop 0
	v_pk_mul_f32 v[80:81], v[84:85], v[80:81]
	v_mul_f32_e32 v84, 0xbfb8aa3b, v82
	v_mul_f32_e32 v85, 0xbfb8aa3b, v83
	v_exp_f32_e32 v84, v84
	v_exp_f32_e32 v85, v85
	v_cvt_pk_bf16_f32 v90, v80, v81
	v_mad_i64_i32 v[80:81], s[0:1], v98, s2, v[136:137]
	v_add_f32_e32 v84, 1.0, v84
	v_add_f32_e32 v85, 1.0, v85
	v_rcp_f32_e32 v84, v84
	v_rcp_f32_e32 v85, v85
	s_nop 0
	v_pk_mul_f32 v[82:83], v[82:83], v[84:85]
	s_nop 0
	v_pk_mul_f32 v[82:83], v[86:87], v[82:83]
	s_nop 0
	v_cvt_pk_bf16_f32 v91, v82, v83
	global_store_dwordx4 v[80:81], v[88:91], off
	v_mul_f32_e32 v80, 0xbfb8aa3b, v72
	v_mul_f32_e32 v81, 0xbfb8aa3b, v73
	v_exp_f32_e32 v80, v80
	v_exp_f32_e32 v81, v81
	v_or_b32_e32 v82, 48, v141
	v_add_f32_e32 v80, 1.0, v80
	v_add_f32_e32 v81, 1.0, v81
	v_rcp_f32_e32 v80, v80
	v_rcp_f32_e32 v81, v81
	s_nop 0
	v_pk_mul_f32 v[72:73], v[72:73], v[80:81]
	s_nop 0
	v_pk_mul_f32 v[72:73], v[76:77], v[72:73]
	v_mul_f32_e32 v76, 0xbfb8aa3b, v74
	v_mul_f32_e32 v77, 0xbfb8aa3b, v75
	v_exp_f32_e32 v76, v76
	v_exp_f32_e32 v77, v77
	v_cvt_pk_bf16_f32 v72, v72, v73
	v_add_f32_e32 v76, 1.0, v76
	v_add_f32_e32 v77, 1.0, v77
	v_rcp_f32_e32 v76, v76
	v_rcp_f32_e32 v77, v77
	s_nop 0
	v_pk_mul_f32 v[74:75], v[74:75], v[76:77]
	s_nop 0
	v_pk_mul_f32 v[74:75], v[78:79], v[74:75]
	s_nop 0
	v_cvt_pk_bf16_f32 v73, v74, v75
	v_mul_f32_e32 v74, 0xbfb8aa3b, v64
	v_mul_f32_e32 v75, 0xbfb8aa3b, v65
	v_exp_f32_e32 v74, v74
	v_exp_f32_e32 v75, v75
	v_add_f32_e32 v74, 1.0, v74
	v_add_f32_e32 v75, 1.0, v75
	v_rcp_f32_e32 v74, v74
	v_rcp_f32_e32 v75, v75
	s_nop 0
	v_pk_mul_f32 v[64:65], v[64:65], v[74:75]
	s_nop 0
	v_pk_mul_f32 v[64:65], v[68:69], v[64:65]
	v_mul_f32_e32 v68, 0xbfb8aa3b, v66
	v_mul_f32_e32 v69, 0xbfb8aa3b, v67
	v_exp_f32_e32 v68, v68
	v_exp_f32_e32 v69, v69
	v_cvt_pk_bf16_f32 v74, v64, v65
	v_mad_i64_i32 v[64:65], s[0:1], v82, s2, v[136:137]
	v_add_f32_e32 v68, 1.0, v68
	v_add_f32_e32 v69, 1.0, v69
	v_rcp_f32_e32 v68, v68
	v_rcp_f32_e32 v69, v69
	s_nop 0
	v_pk_mul_f32 v[66:67], v[66:67], v[68:69]
	s_nop 0
	v_pk_mul_f32 v[66:67], v[70:71], v[66:67]
	s_nop 0
	v_cvt_pk_bf16_f32 v75, v66, v67
	global_store_dwordx4 v[64:65], v[72:75], off
	v_mul_f32_e32 v64, 0xbfb8aa3b, v56
	v_mul_f32_e32 v65, 0xbfb8aa3b, v57
	v_exp_f32_e32 v64, v64
	v_exp_f32_e32 v65, v65
	v_add_u32_e32 v66, 0x80, v141
	v_add_f32_e32 v64, 1.0, v64
	v_add_f32_e32 v65, 1.0, v65
	v_rcp_f32_e32 v64, v64
	v_rcp_f32_e32 v65, v65
	s_nop 0
	v_pk_mul_f32 v[56:57], v[56:57], v[64:65]
	s_nop 0
	v_pk_mul_f32 v[56:57], v[60:61], v[56:57]
	v_mul_f32_e32 v60, 0xbfb8aa3b, v58
	v_mul_f32_e32 v61, 0xbfb8aa3b, v59
	v_exp_f32_e32 v60, v60
	v_exp_f32_e32 v61, v61
	v_cvt_pk_bf16_f32 v56, v56, v57
	v_add_f32_e32 v60, 1.0, v60
	v_add_f32_e32 v61, 1.0, v61
	v_rcp_f32_e32 v60, v60
	v_rcp_f32_e32 v61, v61
	s_nop 0
	v_pk_mul_f32 v[58:59], v[58:59], v[60:61]
	s_nop 0
	v_pk_mul_f32 v[58:59], v[62:63], v[58:59]
	s_nop 0
	v_cvt_pk_bf16_f32 v57, v58, v59
	v_mul_f32_e32 v58, 0xbfb8aa3b, v48
	v_mul_f32_e32 v59, 0xbfb8aa3b, v49
	v_exp_f32_e32 v58, v58
	v_exp_f32_e32 v59, v59
	v_add_f32_e32 v58, 1.0, v58
	v_add_f32_e32 v59, 1.0, v59
	v_rcp_f32_e32 v58, v58
	v_rcp_f32_e32 v59, v59
	s_nop 0
	v_pk_mul_f32 v[48:49], v[48:49], v[58:59]
	s_nop 0
	v_pk_mul_f32 v[48:49], v[52:53], v[48:49]
	v_mul_f32_e32 v52, 0xbfb8aa3b, v50
	v_mul_f32_e32 v53, 0xbfb8aa3b, v51
	v_exp_f32_e32 v52, v52
	v_exp_f32_e32 v53, v53
	v_cvt_pk_bf16_f32 v58, v48, v49
	v_mad_i64_i32 v[48:49], s[0:1], v66, s2, v[136:137]
	v_add_f32_e32 v52, 1.0, v52
	v_add_f32_e32 v53, 1.0, v53
	v_rcp_f32_e32 v52, v52
	v_rcp_f32_e32 v53, v53
	s_nop 0
	v_pk_mul_f32 v[50:51], v[50:51], v[52:53]
	s_nop 0
	v_pk_mul_f32 v[50:51], v[54:55], v[50:51]
	s_nop 0
	v_cvt_pk_bf16_f32 v59, v50, v51
	global_store_dwordx4 v[48:49], v[56:59], off
	v_mul_f32_e32 v48, 0xbfb8aa3b, v40
	v_mul_f32_e32 v49, 0xbfb8aa3b, v41
	v_exp_f32_e32 v48, v48
	v_exp_f32_e32 v49, v49
	v_add_u32_e32 v50, 0x90, v141
; __device__ __forceinline__ u32x4 mk4(unsigned a, unsigned b, unsigned c, unsigned d) { return (u32x4){a, b, c, d}; }
; __device__ __forceinline__ float silu_f(float x) { return x * __builtin_amdgcn_rcpf(1.f + __expf(-x)); }
; __device__ __forceinline__ void gemm_phase(const Params& p, int l, const bf16_t* __restrict__ A, const bf16_t* __restrict__ Bt, int M, int N, int K,
;                            int epi, bf16_t* __restrict__ outp, char* smem, int wvi) {
;     ...
;       for (int ai = 0; ai < 2; ++ai)
; #pragma unroll
;         for (int m = 0; m < 4; ++m) {
;           bf16_t* rp = outp + (size_t)(r0 + ai * GHALF + m * 16) * DFF + pn * 128 + wc * 32 + fq * 8;
;           unsigned pk[4];
; #pragma unroll
;           for (int bj = 0; bj < 2; ++bj) {
;             const f32x4 g = acc[ai][bj][m][0], u = acc[ai][bj][m][1];
;             const float o0 = silu_f(g[0]) * u[0], o1 = silu_f(g[1]) * u[1], o2 = silu_f(g[2]) * u[2], o3 = silu_f(g[3]) * u[3];
;             pk[2 * bj] = pk2(o0, o1); pk[2 * bj + 1] = pk2(o2, o3);
;           }
;           *reinterpret_cast<u32x4*>(rp) = mk4(pk[0], pk[1], pk[2], pk[3]);
;         }
;     ...
;       if (!has_next) break;
	v_add_f32_e32 v48, 1.0, v48
	v_add_f32_e32 v49, 1.0, v49
	v_rcp_f32_e32 v48, v48
	v_rcp_f32_e32 v49, v49
	s_nop 0
	v_pk_mul_f32 v[40:41], v[40:41], v[48:49]
	s_nop 0
	v_pk_mul_f32 v[40:41], v[44:45], v[40:41]
	v_mul_f32_e32 v44, 0xbfb8aa3b, v42
	v_mul_f32_e32 v45, 0xbfb8aa3b, v43
	v_exp_f32_e32 v44, v44
	v_exp_f32_e32 v45, v45
	v_cvt_pk_bf16_f32 v40, v40, v41
	v_add_f32_e32 v44, 1.0, v44
	v_add_f32_e32 v45, 1.0, v45
	v_rcp_f32_e32 v44, v44
	v_rcp_f32_e32 v45, v45
	s_nop 0
	v_pk_mul_f32 v[42:43], v[42:43], v[44:45]
	s_nop 0
	v_pk_mul_f32 v[42:43], v[46:47], v[42:43]
	s_nop 0
	v_cvt_pk_bf16_f32 v41, v42, v43
	v_mul_f32_e32 v42, 0xbfb8aa3b, v32
	v_mul_f32_e32 v43, 0xbfb8aa3b, v33
	v_exp_f32_e32 v42, v42
	v_exp_f32_e32 v43, v43
	v_add_f32_e32 v42, 1.0, v42
	v_add_f32_e32 v43, 1.0, v43
	v_rcp_f32_e32 v42, v42
	v_rcp_f32_e32 v43, v43
	s_nop 0
	v_pk_mul_f32 v[32:33], v[32:33], v[42:43]
	s_nop 0
	v_pk_mul_f32 v[32:33], v[36:37], v[32:33]
	v_mul_f32_e32 v36, 0xbfb8aa3b, v34
	v_mul_f32_e32 v37, 0xbfb8aa3b, v35
	v_exp_f32_e32 v36, v36
	v_exp_f32_e32 v37, v37
	v_cvt_pk_bf16_f32 v42, v32, v33
	v_mad_i64_i32 v[32:33], s[0:1], v50, s2, v[136:137]
	v_add_f32_e32 v36, 1.0, v36
	v_add_f32_e32 v37, 1.0, v37
	v_rcp_f32_e32 v36, v36
	v_rcp_f32_e32 v37, v37
	s_nop 0
	v_pk_mul_f32 v[34:35], v[34:35], v[36:37]
	s_nop 0
	v_pk_mul_f32 v[34:35], v[38:39], v[34:35]
	s_nop 0
	v_cvt_pk_bf16_f32 v43, v34, v35
	global_store_dwordx4 v[32:33], v[40:43], off
	v_mul_f32_e32 v32, 0xbfb8aa3b, v24
	v_mul_f32_e32 v33, 0xbfb8aa3b, v25
	v_exp_f32_e32 v32, v32
	v_exp_f32_e32 v33, v33
	v_add_u32_e32 v34, 0xa0, v141
	v_add_f32_e32 v32, 1.0, v32
	v_add_f32_e32 v33, 1.0, v33
	v_rcp_f32_e32 v32, v32
	v_rcp_f32_e32 v33, v33
	s_nop 0
	v_pk_mul_f32 v[24:25], v[24:25], v[32:33]
	s_nop 0
	v_pk_mul_f32 v[24:25], v[28:29], v[24:25]
	v_mul_f32_e32 v28, 0xbfb8aa3b, v26
	v_mul_f32_e32 v29, 0xbfb8aa3b, v27
	v_exp_f32_e32 v28, v28
	v_exp_f32_e32 v29, v29
	v_cvt_pk_bf16_f32 v24, v24, v25
	v_add_f32_e32 v28, 1.0, v28
	v_add_f32_e32 v29, 1.0, v29
	v_rcp_f32_e32 v28, v28
	v_rcp_f32_e32 v29, v29
	s_nop 0
	v_pk_mul_f32 v[26:27], v[26:27], v[28:29]
	s_nop 0
	v_pk_mul_f32 v[26:27], v[30:31], v[26:27]
	s_nop 0
	v_cvt_pk_bf16_f32 v25, v26, v27
	v_mul_f32_e32 v26, 0xbfb8aa3b, v16
	v_mul_f32_e32 v27, 0xbfb8aa3b, v17
	v_exp_f32_e32 v26, v26
	v_exp_f32_e32 v27, v27
	v_add_f32_e32 v26, 1.0, v26
	v_add_f32_e32 v27, 1.0, v27
	v_rcp_f32_e32 v26, v26
	v_rcp_f32_e32 v27, v27
	s_nop 0
	v_pk_mul_f32 v[16:17], v[16:17], v[26:27]
	s_nop 0
	v_pk_mul_f32 v[16:17], v[20:21], v[16:17]
	v_mul_f32_e32 v20, 0xbfb8aa3b, v18
	v_mul_f32_e32 v21, 0xbfb8aa3b, v19
	v_exp_f32_e32 v20, v20
	v_exp_f32_e32 v21, v21
	v_cvt_pk_bf16_f32 v26, v16, v17
	v_mad_i64_i32 v[16:17], s[0:1], v34, s2, v[136:137]
	v_add_f32_e32 v20, 1.0, v20
	v_add_f32_e32 v21, 1.0, v21
	v_rcp_f32_e32 v20, v20
	v_rcp_f32_e32 v21, v21
	s_nop 0
	v_pk_mul_f32 v[18:19], v[18:19], v[20:21]
	s_nop 0
	v_pk_mul_f32 v[18:19], v[22:23], v[18:19]
	s_nop 0
	v_cvt_pk_bf16_f32 v27, v18, v19
	global_store_dwordx4 v[16:17], v[24:27], off
	v_mul_f32_e32 v16, 0xbfb8aa3b, v8
	v_mul_f32_e32 v17, 0xbfb8aa3b, v9
	v_exp_f32_e32 v16, v16
	v_exp_f32_e32 v17, v17
	v_add_u32_e32 v18, 0xb0, v141
	v_add_f32_e32 v16, 1.0, v16
	v_add_f32_e32 v17, 1.0, v17
	v_rcp_f32_e32 v16, v16
	v_rcp_f32_e32 v17, v17
	s_nop 0
	v_pk_mul_f32 v[8:9], v[8:9], v[16:17]
	s_nop 0
	v_pk_mul_f32 v[8:9], v[12:13], v[8:9]
	v_mul_f32_e32 v12, 0xbfb8aa3b, v10
	v_mul_f32_e32 v13, 0xbfb8aa3b, v11
	v_exp_f32_e32 v12, v12
	v_exp_f32_e32 v13, v13
	v_cvt_pk_bf16_f32 v8, v8, v9
	v_add_f32_e32 v12, 1.0, v12
	v_add_f32_e32 v13, 1.0, v13
	v_rcp_f32_e32 v12, v12
	v_rcp_f32_e32 v13, v13
	s_nop 0
	v_pk_mul_f32 v[10:11], v[10:11], v[12:13]
	s_nop 0
	v_pk_mul_f32 v[10:11], v[14:15], v[10:11]
	s_nop 0
	v_cvt_pk_bf16_f32 v9, v10, v11
	v_mul_f32_e32 v10, 0xbfb8aa3b, v0
	v_mul_f32_e32 v11, 0xbfb8aa3b, v1
	v_exp_f32_e32 v10, v10
	v_exp_f32_e32 v11, v11
	v_add_f32_e32 v10, 1.0, v10
	v_add_f32_e32 v11, 1.0, v11
	v_rcp_f32_e32 v10, v10
	v_rcp_f32_e32 v11, v11
	s_nop 0
	v_pk_mul_f32 v[0:1], v[0:1], v[10:11]
	s_nop 0
	v_pk_mul_f32 v[0:1], v[4:5], v[0:1]
	v_mul_f32_e32 v4, 0xbfb8aa3b, v2
	v_mul_f32_e32 v5, 0xbfb8aa3b, v3
	v_exp_f32_e32 v4, v4
	v_exp_f32_e32 v5, v5
	v_cvt_pk_bf16_f32 v10, v0, v1
	v_mad_i64_i32 v[0:1], s[0:1], v18, s2, v[136:137]
	v_add_f32_e32 v4, 1.0, v4
	v_add_f32_e32 v5, 1.0, v5
	v_rcp_f32_e32 v4, v4
	v_rcp_f32_e32 v5, v5
	s_mov_b64 s[2:3], -1
	v_pk_mul_f32 v[2:3], v[2:3], v[4:5]
	s_nop 0
	v_pk_mul_f32 v[2:3], v[6:7], v[2:3]
	s_nop 0
	v_cvt_pk_bf16_f32 v11, v2, v3
	global_store_dwordx4 v[0:1], v[8:11], off
	s_cbranch_vccz .LBB0_316
; __device__ __forceinline__ f32x4 zero4() { float z = 0.f; asm volatile("" : "+v"(z)); return (f32x4){z, z, z, z}; }
; __device__ __forceinline__ void gemm_phase(const Params& p, int l, const bf16_t* __restrict__ A, const bf16_t* __restrict__ Bt, int M, int N, int K,
;                            int epi, bf16_t* __restrict__ outp, char* smem, int wvi) {
;     ...
; #pragma unroll
;       for (int a = 0; a < 2; ++a)
; #pragma unroll
;         for (int b = 0; b < 2; ++b)
; #pragma unroll
;           for (int m = 0; m < 4; ++m)
; #pragma unroll
;             for (int n = 0; n < 2; ++n) acc[a][b][m][n] = zero4();
;       Lw = Ln; pm = npm; pn = npn; cA = nA; cB = nB;
	v_mov_b32_e32 v120, v177
	v_mov_b32_e32 v124, v177
	v_mov_b32_e32 v104, v177
	v_mov_b32_e32 v108, v177
	v_mov_b32_e32 v88, v177
	v_mov_b32_e32 v92, v177
	v_mov_b32_e32 v72, v177
	v_mov_b32_e32 v76, v177
	v_mov_b32_e32 v112, v177
	v_mov_b32_e32 v116, v177
	v_mov_b32_e32 v96, v177
	v_mov_b32_e32 v100, v177
	v_mov_b32_e32 v80, v177
	v_mov_b32_e32 v84, v177
	v_mov_b32_e32 v64, v177
	v_mov_b32_e32 v68, v177
	v_mov_b32_e32 v56, v177
	v_mov_b32_e32 v60, v177
	v_mov_b32_e32 v40, v177
	v_mov_b32_e32 v44, v177
	v_mov_b32_e32 v24, v177
	v_mov_b32_e32 v28, v177
	v_mov_b32_e32 v8, v177
	v_mov_b32_e32 v12, v177
	v_mov_b32_e32 v48, v177
	v_mov_b32_e32 v52, v177
	v_mov_b32_e32 v32, v177
	v_mov_b32_e32 v36, v177
	v_mov_b32_e32 v16, v177
	v_mov_b32_e32 v20, v177
	v_mov_b32_e32 v0, v177
	v_mov_b32_e32 v4, v177
	s_nop 0
	v_mov_b32_e32 v121, v120
	v_mov_b32_e32 v122, v120
	v_mov_b32_e32 v123, v120
	v_mov_b32_e32 v125, v124
	v_mov_b32_e32 v126, v124
	v_mov_b32_e32 v127, v124
	v_mov_b32_e32 v105, v104
	v_mov_b32_e32 v106, v104
	v_mov_b32_e32 v107, v104
	v_mov_b32_e32 v109, v108
	v_mov_b32_e32 v110, v108
	v_mov_b32_e32 v111, v108
	v_mov_b32_e32 v89, v88
	v_mov_b32_e32 v90, v88
	v_mov_b32_e32 v91, v88
	v_mov_b32_e32 v93, v92
	v_mov_b32_e32 v94, v92
	v_mov_b32_e32 v95, v92
	s_nop 0
	v_mov_b32_e32 v73, v72
	v_mov_b32_e32 v74, v72
	v_mov_b32_e32 v75, v72
	v_mov_b32_e32 v77, v76
	v_mov_b32_e32 v78, v76
	v_mov_b32_e32 v79, v76
	v_mov_b32_e32 v113, v112
	v_mov_b32_e32 v114, v112
	v_mov_b32_e32 v115, v112
	v_mov_b32_e32 v117, v116
	v_mov_b32_e32 v118, v116
	v_mov_b32_e32 v119, v116
	v_mov_b32_e32 v97, v96
	v_mov_b32_e32 v98, v96
	v_mov_b32_e32 v99, v96
	v_mov_b32_e32 v101, v100
	v_mov_b32_e32 v102, v100
	v_mov_b32_e32 v103, v100
	s_nop 0
	v_mov_b32_e32 v81, v80
	v_mov_b32_e32 v82, v80
	v_mov_b32_e32 v83, v80
	v_mov_b32_e32 v85, v84
	v_mov_b32_e32 v86, v84
	v_mov_b32_e32 v87, v84
	v_mov_b32_e32 v65, v64
	v_mov_b32_e32 v66, v64
	v_mov_b32_e32 v67, v64
	v_mov_b32_e32 v69, v68
	v_mov_b32_e32 v70, v68
	v_mov_b32_e32 v71, v68
	v_mov_b32_e32 v57, v56
	v_mov_b32_e32 v58, v56
	v_mov_b32_e32 v59, v56
	v_mov_b32_e32 v61, v60
	v_mov_b32_e32 v62, v60
	v_mov_b32_e32 v63, v60
	s_nop 0
	v_mov_b32_e32 v41, v40
	v_mov_b32_e32 v42, v40
	v_mov_b32_e32 v43, v40
	v_mov_b32_e32 v45, v44
	v_mov_b32_e32 v46, v44
	v_mov_b32_e32 v47, v44
	v_mov_b32_e32 v25, v24
	v_mov_b32_e32 v26, v24
	v_mov_b32_e32 v27, v24
	v_mov_b32_e32 v29, v28
	v_mov_b32_e32 v30, v28
	v_mov_b32_e32 v31, v28
	v_mov_b32_e32 v9, v8
	v_mov_b32_e32 v10, v8
	v_mov_b32_e32 v11, v8
	v_mov_b32_e32 v13, v12
	v_mov_b32_e32 v14, v12
	v_mov_b32_e32 v15, v12
	s_nop 0
	v_mov_b32_e32 v49, v48
	v_mov_b32_e32 v50, v48
	v_mov_b32_e32 v51, v48
	v_mov_b32_e32 v53, v52
	v_mov_b32_e32 v54, v52
	v_mov_b32_e32 v55, v52
	v_mov_b32_e32 v33, v32
	v_mov_b32_e32 v34, v32
	v_mov_b32_e32 v35, v32
	v_mov_b32_e32 v37, v36
	v_mov_b32_e32 v38, v36
	v_mov_b32_e32 v39, v36
	v_mov_b32_e32 v17, v16
	v_mov_b32_e32 v18, v16
	v_mov_b32_e32 v19, v16
	v_mov_b32_e32 v21, v20
	v_mov_b32_e32 v22, v20
	v_mov_b32_e32 v23, v20
	s_mov_b64 s[2:3], 0
	v_mov_b32_e32 v1, v0
	v_mov_b32_e32 v2, v0
	v_mov_b32_e32 v3, v0
	v_mov_b32_e32 v5, v4
	v_mov_b32_e32 v6, v4
	v_mov_b32_e32 v7, v4
	s_branch .LBB0_316

; __device__ __forceinline__ void gemm_phase(const Params& p, int l, const bf16_t* __restrict__ A, const bf16_t* __restrict__ Bt, int M, int N, int K,
;                            int epi, bf16_t* __restrict__ outp, char* smem, int wvi) {
;     ...
;   const int wid = wvi; int tidx = wvi * 64 + lane_id(); asm volatile("" : "+v"(tidx));
;   const int lane = tidx & 63, wr = wid >> 2, wc = wid & 3, fr = lane & 15, fq = lane >> 4;
;   const int nt = K / GBK;
;   unsigned voff[2];
; #pragma unroll
;   for (int i = 0; i < 2; ++i) { int R, C; stage_rc(tidx * 16 + i * 8192, R, C); voff[i] = (unsigned)(R * K + C) * 2u; }
;   const size_t kstep = (size_t)(GBK * 2), hstep = (size_t)GHALF * K * 2, tstep = 2 * hstep;
;   const unsigned ldsw = (unsigned)wid * 1024u;
;   const int aoff = lds_byte(wr * 64 + fr, fq * 8), boff = lds_byte(wc * 32 + fr, fq * 8);
;   constexpr int HTB = GHT * 2;
;     ...
;   const int nM = M / GBM, nN = N / GBM, nwg = nM * nN;
;   auto tile_of = [&](int Lw, int& pm_, int& pn_) {
;     int wgid = Lw;
;     { const int q = nwg / GNXCD, r = nwg % GNXCD, xcd = wgid % GNXCD, off = wgid / GNXCD; wgid = (xcd < r ? xcd * (q + 1) : r * (q + 1) + (xcd - r) * q) + off; }
;     const int nig = GWGM * nN, gid = wgid / nig, fm = gid * GWGM, gsz = min(nM - fm, GWGM);
;     pm_ = fm + ((wgid % nig) % gsz); pn_ = (wgid % nig) / gsz;
;   };
;   int Lw = blockIdx.x;
;   if (Lw < nwg) {
;     int pm, pn; tile_of(Lw, pm, pn);
;     const char* cA = (const char*)A + (size_t)pm * tstep;
;     const char* cB = (const char*)Bt + (size_t)pn * tstep;
;     f32x4 acc[2][2][4][2];
; #pragma unroll
;     for (int a = 0; a < 2; ++a)
; #pragma unroll
;       for (int b = 0; b < 2; ++b)
; #pragma unroll
;         for (int m = 0; m < 4; ++m)
; #pragma unroll
;           for (int n = 0; n < 2; ++n) acc[a][b][m][n] = zero4();
;     bf16x8 At[4][2], B0[2][2], B1[2][2];
;     G_STAGE(G_SB(0, 0), cB); G_STAGE(G_SA(0, 0), cA); G_STAGE(G_SB(0, 1), cB + hstep); G_STAGE(G_SA(0, 1), cA + hstep);
;     if (wr == 1) G_BAR;
; __device__ __forceinline__ void run_phase(const Params& p, int ph, char* smem0, int wvi) {
;     ...
;     case 7: {
;       const int np = last ? 1024 : 1088;
;       for (int it = obid(wvi); it < np; it += vgrid()) hy_final_item(p, l, it, smem, wvi);
;     } break;
;     case 8: gemm_phase(p, l, p.bufA, p.wOut, last ? TL : TA, DM, DM, EPI_PLAIN, p.bufB, smem0, wvi); break;
.LBB0_363:
	s_cmp_gt_i32 s55, 6
	s_mov_b64 s[2:3], -1
	s_cbranch_scc0 .LBB0_389
	s_cmp_gt_i32 s55, 7
	s_cbranch_scc0 .LBB0_380
	v_readlane_b32 s0, v244, 21
	v_readlane_b32 s1, v244, 22
	s_and_b64 s[0:1], s[0:1], exec
	s_movk_i32 s0, 0x110
	s_cselect_b32 s20, s0, 0x100
	v_readlane_b32 s0, v248, 9
	s_waitcnt vmcnt(1)
	v_mbcnt_lo_u32_b32 v0, -1, 0
	v_mbcnt_hi_u32_b32 v0, -1, v0
	s_lshl_b32 s21, s20, 2
	v_add_u32_e32 v130, s0, v0
	v_readlane_b32 s0, v248, 0
	s_cmp_ge_i32 s0, s21
	s_cbranch_scc1 .LBB0_379
	v_lshlrev_b32_e32 v0, 4, v130
	v_add_u32_e32 v1, 0x2000, v0
	v_ashrrev_i32_e32 v2, 31, v1
	v_lshrrev_b32_e32 v2, 22, v2
	v_add_u32_e32 v2, v1, v2
	v_ashrrev_i32_e32 v134, 10, v2
	v_mul_i32_i24_e32 v2, 0x400, v134
	v_sub_u32_e32 v1, v1, v2
	v_lshrrev_b32_e32 v2, 4, v1
	v_bitop3_b32 v1, v2, v1, 32 bitop3:0x6c
	v_ashrrev_i32_e32 v2, 31, v1
	v_lshrrev_b32_e32 v2, 26, v2
	v_add_u32_e32 v2, v1, v2
	v_ashrrev_i32_e32 v135, 6, v2
	v_and_b32_e32 v2, 0xc0, v2
	v_sub_u32_e32 v1, v1, v2
	v_ashrrev_i16_sdwa v1, v199, sext(v1) dst_sel:DWORD dst_unused:UNUSED_PAD src0_sel:DWORD src1_sel:BYTE_0
	v_bfe_i32 v139, v1, 0, 16
	v_bfe_i32 v1, v130, 27, 1
	s_lshr_b32 s22, s20, 1
	v_readlane_b32 s0, v248, 35
	v_lshrrev_b32_e32 v1, 22, v1
	s_or_b32 s23, s22, 1
	v_readlane_b32 s1, v248, 36
	v_add_u32_e32 v1, v0, v1
	s_and_b64 s[0:1], s[0:1], exec
	v_and_b32_e32 v1, 0xfffffc00, v1
	s_cselect_b32 s0, s23, s22
	v_readlane_b32 s1, v247, 6
	v_sub_u32_e32 v0, v0, v1
	s_mul_i32 s0, s0, s1
	v_readlane_b32 s1, v247, 9
	v_lshrrev_b32_e32 v1, 4, v0
	s_add_i32 s0, s0, s1
	v_bitop3_b32 v0, v1, v0, 32 bitop3:0x6c
	s_ashr_i32 s1, s0, 31
	v_ashrrev_i32_e32 v1, 31, v0
	s_lshr_b32 s1, s1, 27
	v_lshrrev_b32_e32 v1, 26, v1
	s_add_i32 s1, s0, s1
	v_add_u32_e32 v1, v0, v1
	v_ashrrev_i32_e32 v2, 31, v130
	s_ashr_i32 s2, s1, 5
	v_lshlrev_b32_e32 v3, 3, v134
	v_ashrrev_i32_e32 v132, 6, v1
	v_lshrrev_b32_e32 v2, 26, v2
	v_and_b32_e32 v1, 0xc0, v1
	s_lshl_b32 s2, s2, 3
	v_and_b32_e32 v3, 0x1ffff0, v3
	s_waitcnt vmcnt(0)
	v_lshlrev_b32_e32 v4, 5, v134
	v_add_u32_e32 v2, v130, v2
	v_sub_u32_e32 v0, v0, v1
	s_sub_i32 s3, s20, s2
	v_add_u32_e32 v3, v135, v3
	v_and_b32_e32 v138, 32, v4
	v_ashrrev_i32_e32 v133, 6, v2
	v_ashrrev_i16_sdwa v0, v199, sext(v0) dst_sel:DWORD dst_unused:UNUSED_PAD src0_sel:DWORD src1_sel:BYTE_0
	s_min_i32 s3, s3, 8
	v_lshl_or_b32 v3, v3, 10, v138
	v_lshlrev_b32_e32 v2, 3, v133
	v_bfe_i32 v141, v0, 0, 16
	v_cvt_f32_i32_e32 v0, s3
	v_add_lshl_u32 v128, v3, v139, 1
	v_and_b32_e32 v2, 0x1ffff0, v2
	v_lshlrev_b32_e32 v3, 5, v133
	v_add_u32_e32 v2, v132, v2
	v_and_b32_e32 v140, 32, v3
	s_andn2_b32 s1, s1, 31
	v_lshl_or_b32 v2, v2, 10, v140
	s_sub_i32 s5, s0, s1
	v_add_lshl_u32 v176, v2, v141, 1
	v_cvt_f32_i32_e32 v1, s5
	v_rcp_iflag_f32_e32 v2, v0
	s_xor_b32 s0, s5, s3
	s_ashr_i32 s0, s0, 30
	s_or_b32 s4, s0, 1
	v_mul_f32_e32 v2, v1, v2
	v_trunc_f32_e32 v2, v2
	v_fma_f32 v1, -v2, v0, v1
	v_cvt_i32_f32_e32 v2, v2
	v_cmp_ge_f32_e64 s[0:1], |v1|, |v0|
	s_and_b64 s[0:1], s[0:1], exec
	s_cselect_b32 s0, s4, 0
	v_readfirstlane_b32 s1, v2
	s_add_i32 s4, s1, s0
	s_mul_i32 s0, s4, s3
	s_sub_i32 s0, s5, s0
	s_sext_i32_i8 s0, s0
	s_add_i32 s8, s2, s0
	s_ashr_i32 s9, s8, 31
	s_bfe_i64 s[2:3], s[4:5], 0x80000
	v_readlane_b32 s36, v246, 63
	s_lshl_b64 s[0:1], s[8:9], 19
	s_lshl_b64 s[12:13], s[2:3], 19
	v_readlane_b32 s42, v245, 5
	v_readlane_b32 s43, v245, 6
	s_add_u32 s2, s42, s12
	s_addc_u32 s3, s43, s13
	s_add_i32 s9, s58, 0
	v_mov_b32_e32 v20, v177
	v_mov_b32_e32 v28, v177
	v_mov_b32_e32 v12, v177
	v_mov_b32_e32 v24, v177
	v_mov_b32_e32 v4, v177
	v_mov_b32_e32 v16, v177
	v_mov_b32_e32 v0, v177
	v_mov_b32_e32 v8, v177
	v_mov_b32_e32 v80, v177
	v_mov_b32_e32 v92, v177
	v_mov_b32_e32 v64, v177
	v_mov_b32_e32 v84, v177
	v_mov_b32_e32 v52, v177
	v_mov_b32_e32 v76, v177
	v_mov_b32_e32 v40, v177
	v_mov_b32_e32 v60, v177
	v_mov_b32_e32 v68, v177
	v_mov_b32_e32 v88, v177
	v_mov_b32_e32 v48, v177
	v_mov_b32_e32 v72, v177
	v_mov_b32_e32 v36, v177
	v_mov_b32_e32 v56, v177
	v_mov_b32_e32 v32, v177
	v_mov_b32_e32 v44, v177
	v_mov_b32_e32 v120, v177
	v_mov_b32_e32 v124, v177
	v_mov_b32_e32 v112, v177
	v_mov_b32_e32 v116, v177
	v_mov_b32_e32 v104, v177
	v_mov_b32_e32 v108, v177
	v_mov_b32_e32 v96, v177
	v_mov_b32_e32 v100, v177
	s_add_i32 m0, s9, 0x10000
	v_readlane_b32 s44, v245, 7
	global_load_lds_dwordx4 v176, s[2:3]
	s_add_i32 m0, s9, 0x12000
	v_readlane_b32 s45, v245, 8
	s_add_u32 s16, s44, s0
	global_load_lds_dwordx4 v128, s[2:3]
	s_addc_u32 s17, s45, s1
	s_mov_b32 m0, s9
	s_add_i32 s24, s9, 0x2000
	global_load_lds_dwordx4 v176, s[16:17]
	s_mov_b32 m0, s24
	s_add_u32 s0, s2, 0x40000
	global_load_lds_dwordx4 v128, s[16:17]
	s_addc_u32 s1, s3, 0
	s_add_i32 m0, s9, 0x14000
	v_readlane_b32 s37, v245, 0
	global_load_lds_dwordx4 v176, s[0:1]
	s_add_i32 m0, s9, 0x16000
	v_readlane_b32 s38, v245, 1
	global_load_lds_dwordx4 v128, s[0:1]
	s_add_u32 s0, s16, 0x40000
	s_addc_u32 s1, s17, 0
	s_add_i32 s25, s9, 0x4000
	s_mov_b32 m0, s25
	s_add_i32 s26, s9, 0x6000
	global_load_lds_dwordx4 v176, s[0:1]
	s_mov_b32 m0, s26
	v_readlane_b32 s39, v245, 2
	global_load_lds_dwordx4 v128, s[0:1]
	v_readlane_b32 s0, v248, 13
	v_readlane_b32 s1, v248, 14
	s_andn2_b64 vcc, exec, s[0:1]
	v_readlane_b32 s40, v245, 3
	v_readlane_b32 s41, v245, 4
	v_readlane_b32 s46, v245, 9
	v_readlane_b32 s47, v245, 10
	v_readlane_b32 s48, v245, 11
	v_readlane_b32 s49, v245, 12
	v_readlane_b32 s50, v245, 13
	v_readlane_b32 s51, v245, 14
	s_cbranch_vccnz .LBB0_368
	s_barrier
	s_setprio 1

; #define G_STAGE(bufoff, gbase) do { _Pragma("unroll") for (int _i = 0; _i < 2; ++_i) \
;     __builtin_amdgcn_global_load_lds((const unsigned*)((const char*)(gbase) + voff[_i]), (GLAS unsigned*)(lds + (bufoff) + ldsw + _i * 8192), 16, 0, 0); } while (0)
; #define G_LDA(dst, b, h) do { _Pragma("unroll") for (int m = 0; m < 4; ++m) _Pragma("unroll") for (int k = 0; k < 2; ++k) \
;     dst[m][k] = *(const GLAS bf16x8*)(lds + G_SA(b, h) + aoff + m * 2048 + k * 1024); } while (0)
; #define G_LDB(dst, b, h) do { _Pragma("unroll") for (int n = 0; n < 2; ++n) _Pragma("unroll") for (int k = 0; k < 2; ++k) \
;     dst[n][k] = *(const GLAS bf16x8*)(lds + G_SB(b, h) + boff + n * 2048 + k * 1024); } while (0)
; #define G_MMA(ai, bj, At_, Bt_) do { __builtin_amdgcn_s_setprio(1); \
;     _Pragma("unroll") for (int m = 0; m < 4; ++m) _Pragma("unroll") for (int n = 0; n < 2; ++n) _Pragma("unroll") for (int k = 0; k < 2; ++k) \
;       acc[ai][bj][m][n] = __builtin_amdgcn_mfma_f32_16x16x32_bf16(Bt_[n][k], At_[m][k], acc[ai][bj][m][n], 0, 0, 0); \
;     __builtin_amdgcn_s_setprio(0); } while (0)
; #define G_WAIT_V(n) asm volatile("s_waitcnt vmcnt(" #n ")" ::: "memory")
; #define G_WAIT_L(n) asm volatile("s_waitcnt lgkmcnt(" #n ")" ::: "memory")
; #define G_BAR __builtin_amdgcn_s_barrier()
; __device__ __forceinline__ void gemm_phase(const Params& p, int l, const bf16_t* __restrict__ A, const bf16_t* __restrict__ Bt, int M, int N, int K,
;                            int epi, bf16_t* __restrict__ outp, char* smem, int wvi) {
;     ...
;       for (int t = 0; t < nt; t += 2) {
;         const bool lastt = (t == nt - 2);
;         const char* a1 = cA + (size_t)(t + 1) * kstep;
;         const char* a2 = lastt ? nA : cA + (size_t)(t + 2) * kstep; const char* b2 = lastt ? nB : cB + (size_t)(t + 2) * kstep;
;         const char* a3 = a2 + kstep; const char* b3 = b2 + kstep;
;         G_LDB(B0, 0, 0); G_SCHED; G_LDA(At, 0, 0); G_STAGE(G_SA(1, 1), a1 + hstep);
;         G_WAIT_L(8); G_BAR; G_WAIT_L(0); G_MMA(0, 0, At, B0); G_BAR; G_SCHED;
;         G_LDB(B1, 0, 1); G_STAGE(G_SB(0, 0), b2);
;         G_BAR; G_WAIT_L(0); G_MMA(0, 1, At, B1); G_BAR;
;         G_LDA(At, 0, 1); G_STAGE(G_SA(0, 0), a2);
;         G_BAR; G_WAIT_L(0); G_MMA(1, 0, At, B0); G_BAR; G_SCHED;
;         G_STAGE(G_SB(0, 1), b2 + hstep);
;         G_WAIT_V(6); G_BAR; G_MMA(1, 1, At, B1); G_BAR;
.LBB0_373:
	s_add_u32 s2, s16, 0x100
	s_addc_u32 s3, s17, 0
	s_add_i32 s34, 0, 0x10000
	v_add_u32_e32 v139, s34, v137
	ds_read_b128 v[140:143], v139
	ds_read_b128 v[144:147], v139 offset:1024
	ds_read_b128 v[148:151], v139 offset:2048
	ds_read_b128 v[152:155], v139 offset:3072
	s_cmp_eq_u32 s55, 12
	s_cselect_b32 s29, s11, s3
	s_cselect_b32 s28, s10, s2
	s_cselect_b32 s13, s7, s53
	s_cselect_b32 s12, s5, s31
	v_lshl_add_u64 v[190:191], s[16:17], 0, v[132:133]
	s_add_i32 m0, s9, 0xc000
	ds_read_b128 v[156:159], v138
	ds_read_b128 v[160:163], v138 offset:1024
	ds_read_b128 v[164:167], v138 offset:2048
	ds_read_b128 v[168:171], v138 offset:3072
	ds_read_b128 v[172:175], v138 offset:4096
	ds_read_b128 v[182:185], v138 offset:5120
	ds_read_b128 v[186:189], v138 offset:6144
	ds_read_b128 v[214:217], v138 offset:7168
	global_load_lds_dwordx4 v[190:191], off
	v_lshl_add_u64 v[190:191], s[16:17], 0, v[134:135]
	s_add_i32 m0, s9, 0xe000
	s_nop 0
	global_load_lds_dwordx4 v[190:191], off
	s_waitcnt lgkmcnt(8)
	s_barrier
	s_waitcnt lgkmcnt(0)
	s_waitcnt lgkmcnt(0)
	v_mfma_f32_16x16x32_bf16 v[20:23], v[140:143], v[156:159], v[20:23]
	v_mfma_f32_16x16x32_bf16 v[28:31], v[148:151], v[156:159], v[28:31]
	v_mfma_f32_16x16x32_bf16 v[12:15], v[140:143], v[164:167], v[12:15]
	v_mfma_f32_16x16x32_bf16 v[24:27], v[148:151], v[164:167], v[24:27]
	v_mfma_f32_16x16x32_bf16 v[4:7], v[140:143], v[172:175], v[4:7]
	v_mfma_f32_16x16x32_bf16 v[16:19], v[148:151], v[172:175], v[16:19]
	v_mfma_f32_16x16x32_bf16 v[0:3], v[140:143], v[186:189], v[0:3]
	v_mfma_f32_16x16x32_bf16 v[8:11], v[148:151], v[186:189], v[8:11]
	v_mfma_f32_16x16x32_bf16 v[20:23], v[144:147], v[160:163], v[20:23]
	v_mfma_f32_16x16x32_bf16 v[28:31], v[152:155], v[160:163], v[28:31]
	v_mfma_f32_16x16x32_bf16 v[12:15], v[144:147], v[168:171], v[12:15]
	v_mfma_f32_16x16x32_bf16 v[24:27], v[152:155], v[168:171], v[24:27]
	v_mfma_f32_16x16x32_bf16 v[4:7], v[144:147], v[182:185], v[4:7]
	v_mfma_f32_16x16x32_bf16 v[16:19], v[152:155], v[182:185], v[16:19]
	v_mfma_f32_16x16x32_bf16 v[0:3], v[144:147], v[214:217], v[0:3]
	v_mfma_f32_16x16x32_bf16 v[8:11], v[152:155], v[214:217], v[8:11]
	s_barrier
	s_add_i32 s35, 0, 0x14000
	s_add_i32 s16, s34, s58
	v_add_u32_e32 v139, s35, v137
	v_lshl_add_u64 v[190:191], s[12:13], 0, v[176:177]
	s_mov_b32 m0, s16
	ds_read_b128 v[218:221], v139
	ds_read_b128 v[222:225], v139 offset:1024
	ds_read_b128 v[226:229], v139 offset:2048
	ds_read_b128 v[230:233], v139 offset:3072
	global_load_lds_dwordx4 v[190:191], off
	v_lshl_add_u64 v[234:235], s[12:13], 0, v[128:129]
	s_add_i32 m0, s16, 0x2000
	s_nop 0
	global_load_lds_dwordx4 v[234:235], off
	s_barrier
	s_waitcnt lgkmcnt(0)
	s_waitcnt lgkmcnt(0)
	v_mfma_f32_16x16x32_bf16 v[80:83], v[218:221], v[156:159], v[80:83]
	v_mfma_f32_16x16x32_bf16 v[92:95], v[226:229], v[156:159], v[92:95]
	v_mfma_f32_16x16x32_bf16 v[64:67], v[218:221], v[164:167], v[64:67]
	v_mfma_f32_16x16x32_bf16 v[84:87], v[226:229], v[164:167], v[84:87]
	v_mfma_f32_16x16x32_bf16 v[52:55], v[218:221], v[172:175], v[52:55]
	v_mfma_f32_16x16x32_bf16 v[76:79], v[226:229], v[172:175], v[76:79]
	v_mfma_f32_16x16x32_bf16 v[40:43], v[218:221], v[186:189], v[40:43]
	v_mfma_f32_16x16x32_bf16 v[60:63], v[226:229], v[186:189], v[60:63]
	v_mfma_f32_16x16x32_bf16 v[80:83], v[222:225], v[160:163], v[80:83]
	v_mfma_f32_16x16x32_bf16 v[92:95], v[230:233], v[160:163], v[92:95]
	v_mfma_f32_16x16x32_bf16 v[64:67], v[222:225], v[168:171], v[64:67]
	v_mfma_f32_16x16x32_bf16 v[84:87], v[230:233], v[168:171], v[84:87]
	v_mfma_f32_16x16x32_bf16 v[52:55], v[222:225], v[182:185], v[52:55]
	v_mfma_f32_16x16x32_bf16 v[76:79], v[230:233], v[182:185], v[76:79]
	v_mfma_f32_16x16x32_bf16 v[40:43], v[222:225], v[214:217], v[40:43]
	v_mfma_f32_16x16x32_bf16 v[60:63], v[230:233], v[214:217], v[60:63]
	s_mov_b32 m0, s9
	v_lshl_add_u64 v[236:237], s[28:29], 0, v[176:177]
	s_barrier
	ds_read_b128 v[156:159], v138 offset:16384
	ds_read_b128 v[160:163], v138 offset:17408
	ds_read_b128 v[164:167], v138 offset:18432
	ds_read_b128 v[168:171], v138 offset:19456
	ds_read_b128 v[172:175], v138 offset:20480
	ds_read_b128 v[182:185], v138 offset:21504
	ds_read_b128 v[186:189], v138 offset:22528
	ds_read_b128 v[214:217], v138 offset:23552
	global_load_lds_dwordx4 v[236:237], off
	v_lshl_add_u64 v[238:239], s[28:29], 0, v[128:129]
	s_mov_b32 m0, s24
	s_nop 0
	global_load_lds_dwordx4 v[238:239], off
	s_barrier
	s_waitcnt lgkmcnt(0)
	s_waitcnt lgkmcnt(0)
	v_mfma_f32_16x16x32_bf16 v[68:71], v[140:143], v[156:159], v[68:71]
	v_mfma_f32_16x16x32_bf16 v[88:91], v[148:151], v[156:159], v[88:91]
	v_mfma_f32_16x16x32_bf16 v[48:51], v[140:143], v[164:167], v[48:51]
	v_mfma_f32_16x16x32_bf16 v[72:75], v[148:151], v[164:167], v[72:75]
	v_mfma_f32_16x16x32_bf16 v[36:39], v[140:143], v[172:175], v[36:39]
	v_mfma_f32_16x16x32_bf16 v[56:59], v[148:151], v[172:175], v[56:59]
	v_mfma_f32_16x16x32_bf16 v[32:35], v[140:143], v[186:189], v[32:35]
	v_mfma_f32_16x16x32_bf16 v[44:47], v[148:151], v[186:189], v[44:47]
	v_mfma_f32_16x16x32_bf16 v[68:71], v[144:147], v[160:163], v[68:71]
	v_mfma_f32_16x16x32_bf16 v[88:91], v[152:155], v[160:163], v[88:91]
	v_mfma_f32_16x16x32_bf16 v[48:51], v[144:147], v[168:171], v[48:51]
	v_mfma_f32_16x16x32_bf16 v[72:75], v[152:155], v[168:171], v[72:75]
	v_mfma_f32_16x16x32_bf16 v[36:39], v[144:147], v[182:185], v[36:39]
	v_mfma_f32_16x16x32_bf16 v[56:59], v[152:155], v[182:185], v[56:59]
	v_mfma_f32_16x16x32_bf16 v[32:35], v[144:147], v[214:217], v[32:35]
	v_mfma_f32_16x16x32_bf16 v[44:47], v[152:155], v[214:217], v[44:47]
	s_barrier
; #define G_STAGE(bufoff, gbase) do { _Pragma("unroll") for (int _i = 0; _i < 2; ++_i) \
;     __builtin_amdgcn_global_load_lds((const unsigned*)((const char*)(gbase) + voff[_i]), (GLAS unsigned*)(lds + (bufoff) + ldsw + _i * 8192), 16, 0, 0); } while (0)
; #define G_LDA(dst, b, h) do { _Pragma("unroll") for (int m = 0; m < 4; ++m) _Pragma("unroll") for (int k = 0; k < 2; ++k) \
;     dst[m][k] = *(const GLAS bf16x8*)(lds + G_SA(b, h) + aoff + m * 2048 + k * 1024); } while (0)
; #define G_LDB(dst, b, h) do { _Pragma("unroll") for (int n = 0; n < 2; ++n) _Pragma("unroll") for (int k = 0; k < 2; ++k) \
;     dst[n][k] = *(const GLAS bf16x8*)(lds + G_SB(b, h) + boff + n * 2048 + k * 1024); } while (0)
; #define G_MMA(ai, bj, At_, Bt_) do { __builtin_amdgcn_s_setprio(1); \
;     _Pragma("unroll") for (int m = 0; m < 4; ++m) _Pragma("unroll") for (int n = 0; n < 2; ++n) _Pragma("unroll") for (int k = 0; k < 2; ++k) \
;       acc[ai][bj][m][n] = __builtin_amdgcn_mfma_f32_16x16x32_bf16(Bt_[n][k], At_[m][k], acc[ai][bj][m][n], 0, 0, 0); \
;     __builtin_amdgcn_s_setprio(0); } while (0)
; #define G_WAIT_V(n) asm volatile("s_waitcnt vmcnt(" #n ")" ::: "memory")
; #define G_WAIT_L(n) asm volatile("s_waitcnt lgkmcnt(" #n ")" ::: "memory")
; #define G_BAR __builtin_amdgcn_s_barrier()
; #define G_SCHED __builtin_amdgcn_sched_barrier(0)
; __device__ __forceinline__ void gemm_phase(const Params& p, int l, const bf16_t* __restrict__ A, const bf16_t* __restrict__ Bt, int M, int N, int K,
;                            int epi, bf16_t* __restrict__ outp, char* smem, int wvi) {
;     ...
;         G_WAIT_V(6); G_BAR; G_MMA(1, 1, At, B1); G_BAR;
;         G_LDB(B0, 1, 0); G_SCHED; G_LDA(At, 1, 0); G_STAGE(G_SA(0, 1), a2 + hstep);
;         G_WAIT_L(8); G_BAR; G_WAIT_L(0); G_MMA(0, 0, At, B0); G_BAR; G_SCHED;
;         G_LDB(B1, 1, 1); G_STAGE(G_SB(1, 0), b3);
;         G_BAR; G_WAIT_L(0); G_MMA(0, 1, At, B1); G_BAR;
;         G_LDA(At, 1, 1); G_STAGE(G_SA(1, 0), a3);
;         G_BAR; G_WAIT_L(0); G_MMA(1, 0, At, B0); G_BAR; G_SCHED;
	s_add_u32 s16, s12, 0x40000
	s_addc_u32 s17, s13, 0
	s_add_i32 s34, s35, s58
	v_lshl_add_u64 v[140:141], s[16:17], 0, v[176:177]
	s_mov_b32 m0, s34
	s_nop 0
	global_load_lds_dwordx4 v[140:141], off
	v_lshl_add_u64 v[140:141], s[16:17], 0, v[128:129]
	s_add_i32 m0, s34, 0x2000
	s_nop 0
	global_load_lds_dwordx4 v[140:141], off
	s_waitcnt vmcnt(6)
	s_barrier
	v_mfma_f32_16x16x32_bf16 v[120:123], v[218:221], v[156:159], v[120:123]
	v_mfma_f32_16x16x32_bf16 v[124:127], v[226:229], v[156:159], v[124:127]
	v_mfma_f32_16x16x32_bf16 v[112:115], v[218:221], v[164:167], v[112:115]
	v_mfma_f32_16x16x32_bf16 v[116:119], v[226:229], v[164:167], v[116:119]
	v_mfma_f32_16x16x32_bf16 v[104:107], v[218:221], v[172:175], v[104:107]
	v_mfma_f32_16x16x32_bf16 v[108:111], v[226:229], v[172:175], v[108:111]
	v_mfma_f32_16x16x32_bf16 v[96:99], v[218:221], v[186:189], v[96:99]
	v_mfma_f32_16x16x32_bf16 v[100:103], v[226:229], v[186:189], v[100:103]
	v_mfma_f32_16x16x32_bf16 v[120:123], v[222:225], v[160:163], v[120:123]
	v_mfma_f32_16x16x32_bf16 v[124:127], v[230:233], v[160:163], v[124:127]
	v_mfma_f32_16x16x32_bf16 v[112:115], v[222:225], v[168:171], v[112:115]
	v_mfma_f32_16x16x32_bf16 v[116:119], v[230:233], v[168:171], v[116:119]
	v_mfma_f32_16x16x32_bf16 v[104:107], v[222:225], v[182:185], v[104:107]
	v_mfma_f32_16x16x32_bf16 v[108:111], v[230:233], v[182:185], v[108:111]
	v_mfma_f32_16x16x32_bf16 v[96:99], v[222:225], v[214:217], v[96:99]
	v_mfma_f32_16x16x32_bf16 v[100:103], v[230:233], v[214:217], v[100:103]
	s_add_i32 s34, 0, 0x18000
	v_add_u32_e32 v139, s34, v137
	s_barrier
	ds_read_b128 v[140:143], v139
	ds_read_b128 v[144:147], v139 offset:1024
	ds_read_b128 v[148:151], v139 offset:2048
	ds_read_b128 v[152:155], v139 offset:3072
	s_add_u32 s16, s28, 0x40000
	s_addc_u32 s17, s29, 0
	s_mov_b32 m0, s25
	v_lshl_add_u64 v[218:219], s[16:17], 0, v[176:177]
	ds_read_b128 v[156:159], v138 offset:32768
	ds_read_b128 v[160:163], v138 offset:33792
	ds_read_b128 v[164:167], v138 offset:34816
	ds_read_b128 v[168:171], v138 offset:35840
	ds_read_b128 v[172:175], v138 offset:36864
	ds_read_b128 v[182:185], v138 offset:37888
	ds_read_b128 v[186:189], v138 offset:38912
	ds_read_b128 v[214:217], v138 offset:39936
	global_load_lds_dwordx4 v[218:219], off
	v_lshl_add_u64 v[218:219], s[16:17], 0, v[128:129]
	s_mov_b32 m0, s26
	s_nop 0
	global_load_lds_dwordx4 v[218:219], off
	s_waitcnt lgkmcnt(8)
	s_barrier
	s_waitcnt lgkmcnt(0)
	s_waitcnt lgkmcnt(0)
	v_mfma_f32_16x16x32_bf16 v[20:23], v[140:143], v[156:159], v[20:23]
	v_mfma_f32_16x16x32_bf16 v[28:31], v[148:151], v[156:159], v[28:31]
	v_mfma_f32_16x16x32_bf16 v[12:15], v[140:143], v[164:167], v[12:15]
	v_mfma_f32_16x16x32_bf16 v[24:27], v[148:151], v[164:167], v[24:27]
	v_mfma_f32_16x16x32_bf16 v[4:7], v[140:143], v[172:175], v[4:7]
	v_mfma_f32_16x16x32_bf16 v[16:19], v[148:151], v[172:175], v[16:19]
	v_mfma_f32_16x16x32_bf16 v[0:3], v[140:143], v[186:189], v[0:3]
	v_mfma_f32_16x16x32_bf16 v[8:11], v[148:151], v[186:189], v[8:11]
	v_mfma_f32_16x16x32_bf16 v[20:23], v[144:147], v[160:163], v[20:23]
	v_mfma_f32_16x16x32_bf16 v[28:31], v[152:155], v[160:163], v[28:31]
	v_mfma_f32_16x16x32_bf16 v[12:15], v[144:147], v[168:171], v[12:15]
	v_mfma_f32_16x16x32_bf16 v[24:27], v[152:155], v[168:171], v[24:27]
	v_mfma_f32_16x16x32_bf16 v[4:7], v[144:147], v[182:185], v[4:7]
	v_mfma_f32_16x16x32_bf16 v[16:19], v[152:155], v[182:185], v[16:19]
	v_mfma_f32_16x16x32_bf16 v[0:3], v[144:147], v[214:217], v[0:3]
	v_mfma_f32_16x16x32_bf16 v[8:11], v[152:155], v[214:217], v[8:11]
	s_barrier
	s_add_i32 s16, 0, 0x1c000
	s_add_i32 s17, s34, s58
	v_add_u32_e32 v139, s16, v137
	v_lshl_add_u64 v[190:191], v[190:191], 0, s[64:65]
	s_mov_b32 m0, s17
	ds_read_b128 v[218:221], v139
	ds_read_b128 v[222:225], v139 offset:1024
	ds_read_b128 v[226:229], v139 offset:2048
	ds_read_b128 v[230:233], v139 offset:3072
	global_load_lds_dwordx4 v[190:191], off
	v_lshl_add_u64 v[190:191], v[234:235], 0, s[64:65]
	s_add_i32 m0, s17, 0x2000
	s_nop 0
	global_load_lds_dwordx4 v[190:191], off
	s_barrier
	s_waitcnt lgkmcnt(0)
	s_waitcnt lgkmcnt(0)
	v_mfma_f32_16x16x32_bf16 v[80:83], v[218:221], v[156:159], v[80:83]
	v_mfma_f32_16x16x32_bf16 v[92:95], v[226:229], v[156:159], v[92:95]
	v_mfma_f32_16x16x32_bf16 v[64:67], v[218:221], v[164:167], v[64:67]
	v_mfma_f32_16x16x32_bf16 v[84:87], v[226:229], v[164:167], v[84:87]
	v_mfma_f32_16x16x32_bf16 v[52:55], v[218:221], v[172:175], v[52:55]
	v_mfma_f32_16x16x32_bf16 v[76:79], v[226:229], v[172:175], v[76:79]
	v_mfma_f32_16x16x32_bf16 v[40:43], v[218:221], v[186:189], v[40:43]
	v_mfma_f32_16x16x32_bf16 v[60:63], v[226:229], v[186:189], v[60:63]
	v_mfma_f32_16x16x32_bf16 v[80:83], v[222:225], v[160:163], v[80:83]
	v_mfma_f32_16x16x32_bf16 v[92:95], v[230:233], v[160:163], v[92:95]
	v_mfma_f32_16x16x32_bf16 v[64:67], v[222:225], v[168:171], v[64:67]
	v_mfma_f32_16x16x32_bf16 v[84:87], v[230:233], v[168:171], v[84:87]
	v_mfma_f32_16x16x32_bf16 v[52:55], v[222:225], v[182:185], v[52:55]
	v_mfma_f32_16x16x32_bf16 v[76:79], v[230:233], v[182:185], v[76:79]
	v_mfma_f32_16x16x32_bf16 v[40:43], v[222:225], v[214:217], v[40:43]
	v_mfma_f32_16x16x32_bf16 v[60:63], v[230:233], v[214:217], v[60:63]
	s_mov_b32 m0, s0
	v_lshl_add_u64 v[190:191], v[236:237], 0, s[64:65]
	s_barrier
	ds_read_b128 v[156:159], v138 offset:49152
	ds_read_b128 v[160:163], v138 offset:50176
	ds_read_b128 v[164:167], v138 offset:51200
	ds_read_b128 v[168:171], v138 offset:52224
	ds_read_b128 v[172:175], v138 offset:53248
	ds_read_b128 v[182:185], v138 offset:54272
	ds_read_b128 v[186:189], v138 offset:55296
	ds_read_b128 v[214:217], v138 offset:56320
	global_load_lds_dwordx4 v[190:191], off
	v_lshl_add_u64 v[190:191], v[238:239], 0, s[64:65]
	s_mov_b32 m0, s1
	s_nop 0
	global_load_lds_dwordx4 v[190:191], off
	s_barrier
; __device__ __forceinline__ u32x4 mk4(unsigned a, unsigned b, unsigned c, unsigned d) { return (u32x4){a, b, c, d}; }
; #define G_STAGE(bufoff, gbase) do { _Pragma("unroll") for (int _i = 0; _i < 2; ++_i) \
;     __builtin_amdgcn_global_load_lds((const unsigned*)((const char*)(gbase) + voff[_i]), (GLAS unsigned*)(lds + (bufoff) + ldsw + _i * 8192), 16, 0, 0); } while (0)
; #define G_MMA(ai, bj, At_, Bt_) do { __builtin_amdgcn_s_setprio(1); \
;     _Pragma("unroll") for (int m = 0; m < 4; ++m) _Pragma("unroll") for (int n = 0; n < 2; ++n) _Pragma("unroll") for (int k = 0; k < 2; ++k) \
;       acc[ai][bj][m][n] = __builtin_amdgcn_mfma_f32_16x16x32_bf16(Bt_[n][k], At_[m][k], acc[ai][bj][m][n], 0, 0, 0); \
;     __builtin_amdgcn_s_setprio(0); } while (0)
; #define G_WAIT_V(n) asm volatile("s_waitcnt vmcnt(" #n ")" ::: "memory")
; #define G_WAIT_L(n) asm volatile("s_waitcnt lgkmcnt(" #n ")" ::: "memory")
; #define G_BAR __builtin_amdgcn_s_barrier()
; #define G_SCHED __builtin_amdgcn_sched_barrier(0)
; __device__ __forceinline__ void gemm_phase(const Params& p, int l, const bf16_t* __restrict__ A, const bf16_t* __restrict__ Bt, int M, int N, int K,
;                            int epi, bf16_t* __restrict__ outp, char* smem, int wvi) {
;     ...
;         G_BAR; G_WAIT_L(0); G_MMA(1, 0, At, B0); G_BAR; G_SCHED;
;         G_STAGE(G_SB(1, 1), b3 + hstep);
;         G_WAIT_V(6); G_BAR; G_MMA(1, 1, At, B1); G_BAR;
;       }
;       const int brow = pm * GBM, bcol = pn * GBM;
;     const int r0 = brow + wr * 64 + fr;
;     if (epi == EPI_PLAIN) {
; #pragma unroll
;       for (int ai = 0; ai < 2; ++ai)
; #pragma unroll
;         for (int m = 0; m < 4; ++m) {
;           bf16_t* rp = outp + (size_t)(r0 + ai * GHALF + m * 16) * N + bcol + wc * 32 + fq * 8;
; #pragma unroll
;           for (int bj = 0; bj < 2; ++bj) {
;             const f32x4 v0 = acc[ai][bj][m][0], v1 = acc[ai][bj][m][1];
;             *reinterpret_cast<u32x4*>(rp + bj * GHALF) = mk4(pk2(v0[0], v0[1]), pk2(v0[2], v0[3]), pk2(v1[0], v1[1]), pk2(v1[2], v1[3]));
;           }
;         }
	s_waitcnt lgkmcnt(0)
	s_waitcnt lgkmcnt(0)
	v_mfma_f32_16x16x32_bf16 v[68:71], v[140:143], v[156:159], v[68:71]
	v_mfma_f32_16x16x32_bf16 v[88:91], v[148:151], v[156:159], v[88:91]
	v_mfma_f32_16x16x32_bf16 v[48:51], v[140:143], v[164:167], v[48:51]
	v_mfma_f32_16x16x32_bf16 v[72:75], v[148:151], v[164:167], v[72:75]
	v_mfma_f32_16x16x32_bf16 v[36:39], v[140:143], v[172:175], v[36:39]
	v_mfma_f32_16x16x32_bf16 v[56:59], v[148:151], v[172:175], v[56:59]
	v_mfma_f32_16x16x32_bf16 v[32:35], v[140:143], v[186:189], v[32:35]
	v_mfma_f32_16x16x32_bf16 v[44:47], v[148:151], v[186:189], v[44:47]
	v_mfma_f32_16x16x32_bf16 v[68:71], v[144:147], v[160:163], v[68:71]
	v_mfma_f32_16x16x32_bf16 v[88:91], v[152:155], v[160:163], v[88:91]
	v_mfma_f32_16x16x32_bf16 v[48:51], v[144:147], v[168:171], v[48:51]
	v_mfma_f32_16x16x32_bf16 v[72:75], v[152:155], v[168:171], v[72:75]
	v_mfma_f32_16x16x32_bf16 v[36:39], v[144:147], v[182:185], v[36:39]
	v_mfma_f32_16x16x32_bf16 v[56:59], v[152:155], v[182:185], v[56:59]
	v_mfma_f32_16x16x32_bf16 v[32:35], v[144:147], v[214:217], v[32:35]
	v_mfma_f32_16x16x32_bf16 v[44:47], v[152:155], v[214:217], v[44:47]
	s_barrier
	s_add_u32 s12, s12, 0x40080
	s_addc_u32 s13, s13, 0
	s_add_i32 s16, s16, s58
	v_lshl_add_u64 v[140:141], s[12:13], 0, v[176:177]
	s_mov_b32 m0, s16
	s_nop 0
	global_load_lds_dwordx4 v[140:141], off
	v_lshl_add_u64 v[140:141], s[12:13], 0, v[128:129]
	s_add_i32 m0, s16, 0x2000
	s_nop 0
	global_load_lds_dwordx4 v[140:141], off
	s_waitcnt vmcnt(6)
	s_barrier
	v_mfma_f32_16x16x32_bf16 v[120:123], v[218:221], v[156:159], v[120:123]
	v_mfma_f32_16x16x32_bf16 v[124:127], v[226:229], v[156:159], v[124:127]
	v_mfma_f32_16x16x32_bf16 v[112:115], v[218:221], v[164:167], v[112:115]
	v_mfma_f32_16x16x32_bf16 v[116:119], v[226:229], v[164:167], v[116:119]
	v_mfma_f32_16x16x32_bf16 v[104:107], v[218:221], v[172:175], v[104:107]
	v_mfma_f32_16x16x32_bf16 v[108:111], v[226:229], v[172:175], v[108:111]
	v_mfma_f32_16x16x32_bf16 v[96:99], v[218:221], v[186:189], v[96:99]
	v_mfma_f32_16x16x32_bf16 v[100:103], v[226:229], v[186:189], v[100:103]
	v_mfma_f32_16x16x32_bf16 v[120:123], v[222:225], v[160:163], v[120:123]
	v_mfma_f32_16x16x32_bf16 v[124:127], v[230:233], v[160:163], v[124:127]
	v_mfma_f32_16x16x32_bf16 v[112:115], v[222:225], v[168:171], v[112:115]
	v_mfma_f32_16x16x32_bf16 v[116:119], v[230:233], v[168:171], v[116:119]
	v_mfma_f32_16x16x32_bf16 v[104:107], v[222:225], v[182:185], v[104:107]
	v_mfma_f32_16x16x32_bf16 v[108:111], v[230:233], v[182:185], v[108:111]
	v_mfma_f32_16x16x32_bf16 v[96:99], v[222:225], v[214:217], v[96:99]
	v_mfma_f32_16x16x32_bf16 v[100:103], v[230:233], v[214:217], v[100:103]
	s_add_i32 s55, s55, 2
	s_add_u32 s31, s31, 0x100
	s_addc_u32 s53, s53, 0
	s_cmp_gt_u32 s55, 13
	s_mov_b64 s[16:17], s[2:3]
	s_barrier
	s_cbranch_scc0 .LBB0_373
	s_lshl_b32 s2, s30, 8
	v_lshl_add_u32 v140, s8, 8, v136
	s_ashr_i32 s3, s2, 31
	v_ashrrev_i32_e32 v141, 31, v140
	v_lshl_add_u64 v[142:143], s[2:3], 1, v[130:131]
	v_lshlrev_b64 v[144:145], 11, v[140:141]
	v_lshl_add_u64 v[144:145], v[142:143], 0, v[144:145]
	v_cvt_pk_bf16_f32 v20, v20, v21
	v_cvt_pk_bf16_f32 v21, v22, v23
	v_cvt_pk_bf16_f32 v22, v28, v29
	v_cvt_pk_bf16_f32 v23, v30, v31
	global_store_dwordx4 v[144:145], v[20:23], off
	v_cvt_pk_bf16_f32 v12, v12, v13
	v_cvt_pk_bf16_f32 v13, v14, v15
	v_cvt_pk_bf16_f32 v20, v80, v81
	v_cvt_pk_bf16_f32 v21, v82, v83
	v_cvt_pk_bf16_f32 v22, v92, v93
	v_cvt_pk_bf16_f32 v23, v94, v95
	global_store_dwordx4 v[144:145], v[20:23], off offset:256
	v_cvt_pk_bf16_f32 v14, v24, v25
	v_cvt_pk_bf16_f32 v15, v26, v27
	v_or_b32_e32 v20, 16, v140
	v_ashrrev_i32_e32 v21, 31, v20
	v_lshlrev_b64 v[20:21], 11, v[20:21]
	v_lshl_add_u64 v[20:21], v[142:143], 0, v[20:21]
	global_store_dwordx4 v[20:21], v[12:15], off
	v_cvt_pk_bf16_f32 v4, v4, v5
	v_cvt_pk_bf16_f32 v5, v6, v7
	v_cvt_pk_bf16_f32 v12, v64, v65
	v_cvt_pk_bf16_f32 v13, v66, v67
	v_cvt_pk_bf16_f32 v14, v84, v85
	v_cvt_pk_bf16_f32 v15, v86, v87
	global_store_dwordx4 v[20:21], v[12:15], off offset:256
	v_cvt_pk_bf16_f32 v6, v16, v17
	v_cvt_pk_bf16_f32 v7, v18, v19
	v_or_b32_e32 v12, 32, v140
	v_ashrrev_i32_e32 v13, 31, v12
	v_lshlrev_b64 v[12:13], 11, v[12:13]
	v_lshl_add_u64 v[12:13], v[142:143], 0, v[12:13]
	global_store_dwordx4 v[12:13], v[4:7], off
	v_cvt_pk_bf16_f32 v0, v0, v1
	v_cvt_pk_bf16_f32 v1, v2, v3
	v_cvt_pk_bf16_f32 v4, v52, v53
	v_cvt_pk_bf16_f32 v5, v54, v55
	v_cvt_pk_bf16_f32 v6, v76, v77
	v_cvt_pk_bf16_f32 v7, v78, v79
	global_store_dwordx4 v[12:13], v[4:7], off offset:256
	v_cvt_pk_bf16_f32 v2, v8, v9
	v_cvt_pk_bf16_f32 v3, v10, v11
	v_or_b32_e32 v4, 48, v140
	v_ashrrev_i32_e32 v5, 31, v4
	v_lshlrev_b64 v[4:5], 11, v[4:5]
	v_lshl_add_u64 v[4:5], v[142:143], 0, v[4:5]
	global_store_dwordx4 v[4:5], v[0:3], off
	s_mov_b64 s[2:3], 0x40000
	s_movk_i32 s53, 0x440
	v_cvt_pk_bf16_f32 v0, v40, v41
	v_cvt_pk_bf16_f32 v1, v42, v43
	v_cvt_pk_bf16_f32 v2, v60, v61
	v_cvt_pk_bf16_f32 v3, v62, v63
	global_store_dwordx4 v[4:5], v[0:3], off offset:256
	v_lshl_add_u64 v[4:5], v[144:145], 0, s[2:3]
	s_mov_b32 s2, 0x40000
	v_add_co_u32_e32 v6, vcc, s2, v144
	v_cvt_pk_bf16_f32 v0, v68, v69
	v_cvt_pk_bf16_f32 v1, v70, v71
	v_cvt_pk_bf16_f32 v2, v88, v89
; __device__ __forceinline__ u32x4 mk4(unsigned a, unsigned b, unsigned c, unsigned d) { return (u32x4){a, b, c, d}; }
; __device__ __forceinline__ f32x4 zero4() { float z = 0.f; asm volatile("" : "+v"(z)); return (f32x4){z, z, z, z}; }
; __device__ __forceinline__ void gemm_phase(const Params& p, int l, const bf16_t* __restrict__ A, const bf16_t* __restrict__ Bt, int M, int N, int K,
;                            int epi, bf16_t* __restrict__ outp, char* smem, int wvi) {
;     ...
;           bf16_t* rp = outp + (size_t)(r0 + ai * GHALF + m * 16) * N + bcol + wc * 32 + fq * 8;
; #pragma unroll
;           for (int bj = 0; bj < 2; ++bj) {
;             const f32x4 v0 = acc[ai][bj][m][0], v1 = acc[ai][bj][m][1];
;             *reinterpret_cast<u32x4*>(rp + bj * GHALF) = mk4(pk2(v0[0], v0[1]), pk2(v0[2], v0[3]), pk2(v1[0], v1[1]), pk2(v1[2], v1[3]));
;           }
;         }
;     ...
;       if (!has_next) break;
; #pragma unroll
;       for (int a = 0; a < 2; ++a)
; #pragma unroll
;         for (int b = 0; b < 2; ++b)
; #pragma unroll
;           for (int m = 0; m < 4; ++m)
; #pragma unroll
;             for (int n = 0; n < 2; ++n) acc[a][b][m][n] = zero4();
;       Lw = Ln; pm = npm; pn = npn; cA = nA; cB = nB;
	v_cvt_pk_bf16_f32 v3, v90, v91
	v_addc_co_u32_e32 v7, vcc, 0, v145, vcc
	global_store_dwordx4 v[6:7], v[0:3], off
	s_mov_b64 s[2:3], 0x48000
	v_readlane_b32 s55, v244, 31
	v_cvt_pk_bf16_f32 v0, v120, v121
	v_cvt_pk_bf16_f32 v1, v122, v123
	v_cvt_pk_bf16_f32 v2, v124, v125
	v_cvt_pk_bf16_f32 v3, v126, v127
	global_store_dwordx4 v[4:5], v[0:3], off offset:256
	v_lshl_add_u64 v[4:5], v[144:145], 0, s[2:3]
	s_mov_b32 s2, 0x48000
	v_add_co_u32_e32 v6, vcc, s2, v144
	v_cvt_pk_bf16_f32 v0, v48, v49
	v_cvt_pk_bf16_f32 v1, v50, v51
	v_cvt_pk_bf16_f32 v2, v72, v73
	v_cvt_pk_bf16_f32 v3, v74, v75
	v_addc_co_u32_e32 v7, vcc, 0, v145, vcc
	global_store_dwordx4 v[6:7], v[0:3], off
	s_mov_b64 s[2:3], 0x50000
	s_nop 0
	v_cvt_pk_bf16_f32 v0, v112, v113
	v_cvt_pk_bf16_f32 v1, v114, v115
	v_cvt_pk_bf16_f32 v2, v116, v117
	v_cvt_pk_bf16_f32 v3, v118, v119
	global_store_dwordx4 v[4:5], v[0:3], off offset:256
	v_lshl_add_u64 v[4:5], v[144:145], 0, s[2:3]
	s_mov_b32 s2, 0x50000
	v_add_co_u32_e32 v6, vcc, s2, v144
	v_cvt_pk_bf16_f32 v0, v36, v37
	v_cvt_pk_bf16_f32 v1, v38, v39
	v_cvt_pk_bf16_f32 v2, v56, v57
	v_cvt_pk_bf16_f32 v3, v58, v59
	v_addc_co_u32_e32 v7, vcc, 0, v145, vcc
	global_store_dwordx4 v[6:7], v[0:3], off
	s_mov_b64 s[2:3], 0x58000
	s_nop 0
	v_cvt_pk_bf16_f32 v0, v104, v105
	v_cvt_pk_bf16_f32 v1, v106, v107
	v_cvt_pk_bf16_f32 v2, v108, v109
	v_cvt_pk_bf16_f32 v3, v110, v111
	global_store_dwordx4 v[4:5], v[0:3], off offset:256
	v_lshl_add_u64 v[4:5], v[144:145], 0, s[2:3]
	s_mov_b32 s2, 0x58000
	v_add_co_u32_e32 v6, vcc, s2, v144
	v_cvt_pk_bf16_f32 v0, v32, v33
	v_cvt_pk_bf16_f32 v1, v34, v35
	v_cvt_pk_bf16_f32 v2, v44, v45
	v_cvt_pk_bf16_f32 v3, v46, v47
	v_addc_co_u32_e32 v7, vcc, 0, v145, vcc
	global_store_dwordx4 v[6:7], v[0:3], off
	s_mov_b64 s[2:3], -1
	s_and_b64 vcc, exec, s[14:15]
	v_cvt_pk_bf16_f32 v0, v96, v97
	v_cvt_pk_bf16_f32 v1, v98, v99
	v_cvt_pk_bf16_f32 v2, v100, v101
	v_cvt_pk_bf16_f32 v3, v102, v103
	global_store_dwordx4 v[4:5], v[0:3], off offset:256
	s_cbranch_vccz .LBB0_369
	v_mov_b32_e32 v20, v177
	v_mov_b32_e32 v28, v177
	v_mov_b32_e32 v12, v177
	v_mov_b32_e32 v24, v177
	v_mov_b32_e32 v4, v177
	v_mov_b32_e32 v16, v177
	v_mov_b32_e32 v0, v177
	v_mov_b32_e32 v8, v177
	v_mov_b32_e32 v80, v177
	v_mov_b32_e32 v92, v177
	v_mov_b32_e32 v64, v177
	v_mov_b32_e32 v84, v177
	v_mov_b32_e32 v52, v177
	v_mov_b32_e32 v76, v177
	v_mov_b32_e32 v40, v177
	v_mov_b32_e32 v60, v177
	v_mov_b32_e32 v68, v177
	v_mov_b32_e32 v88, v177
	v_mov_b32_e32 v48, v177
	v_mov_b32_e32 v72, v177
	v_mov_b32_e32 v36, v177
	v_mov_b32_e32 v56, v177
	v_mov_b32_e32 v32, v177
	v_mov_b32_e32 v44, v177
	v_mov_b32_e32 v120, v177
	v_mov_b32_e32 v124, v177
	v_mov_b32_e32 v112, v177
	v_mov_b32_e32 v116, v177
	v_mov_b32_e32 v104, v177
	v_mov_b32_e32 v108, v177
	v_mov_b32_e32 v96, v177
	v_mov_b32_e32 v100, v177
	s_nop 0
	v_mov_b32_e32 v21, v20
	v_mov_b32_e32 v22, v20
	v_mov_b32_e32 v23, v20
	v_mov_b32_e32 v29, v28
	v_mov_b32_e32 v30, v28
	v_mov_b32_e32 v31, v28
	v_mov_b32_e32 v13, v12
	v_mov_b32_e32 v14, v12
	v_mov_b32_e32 v15, v12
	v_mov_b32_e32 v25, v24
	v_mov_b32_e32 v26, v24
	v_mov_b32_e32 v27, v24
	v_mov_b32_e32 v5, v4
	v_mov_b32_e32 v6, v4
	v_mov_b32_e32 v7, v4
	v_mov_b32_e32 v17, v16
	v_mov_b32_e32 v18, v16
	v_mov_b32_e32 v19, v16
	s_nop 0
	v_mov_b32_e32 v1, v0
	v_mov_b32_e32 v2, v0
	v_mov_b32_e32 v3, v0
	v_mov_b32_e32 v9, v8
	v_mov_b32_e32 v10, v8
	v_mov_b32_e32 v11, v8
	v_mov_b32_e32 v81, v80
	v_mov_b32_e32 v82, v80
	v_mov_b32_e32 v83, v80
	v_mov_b32_e32 v93, v92
	v_mov_b32_e32 v94, v92
	v_mov_b32_e32 v95, v92
	v_mov_b32_e32 v65, v64
	v_mov_b32_e32 v66, v64
	v_mov_b32_e32 v67, v64
	v_mov_b32_e32 v85, v84
	v_mov_b32_e32 v86, v84
	v_mov_b32_e32 v87, v84
	s_nop 0
	v_mov_b32_e32 v53, v52
	v_mov_b32_e32 v54, v52
	v_mov_b32_e32 v55, v52
	v_mov_b32_e32 v77, v76
	v_mov_b32_e32 v78, v76
	v_mov_b32_e32 v79, v76
	v_mov_b32_e32 v41, v40
	v_mov_b32_e32 v42, v40
	v_mov_b32_e32 v43, v40
	v_mov_b32_e32 v61, v60
	v_mov_b32_e32 v62, v60
	v_mov_b32_e32 v63, v60
	v_mov_b32_e32 v69, v68
	v_mov_b32_e32 v70, v68
	v_mov_b32_e32 v71, v68
	v_mov_b32_e32 v89, v88
	v_mov_b32_e32 v90, v88
	v_mov_b32_e32 v91, v88
	s_nop 0
	v_mov_b32_e32 v49, v48
	v_mov_b32_e32 v50, v48
	v_mov_b32_e32 v51, v48
	v_mov_b32_e32 v73, v72
	v_mov_b32_e32 v74, v72
	v_mov_b32_e32 v75, v72
	v_mov_b32_e32 v37, v36
	v_mov_b32_e32 v38, v36
	v_mov_b32_e32 v39, v36
	v_mov_b32_e32 v57, v56
	v_mov_b32_e32 v58, v56
	v_mov_b32_e32 v59, v56
	v_mov_b32_e32 v33, v32
	v_mov_b32_e32 v34, v32
	v_mov_b32_e32 v35, v32
	v_mov_b32_e32 v45, v44
	v_mov_b32_e32 v46, v44
	v_mov_b32_e32 v47, v44
	s_nop 0
	v_mov_b32_e32 v121, v120
	v_mov_b32_e32 v122, v120
	v_mov_b32_e32 v123, v120
	v_mov_b32_e32 v125, v124
	v_mov_b32_e32 v126, v124
	v_mov_b32_e32 v127, v124
	v_mov_b32_e32 v113, v112
	v_mov_b32_e32 v114, v112
	v_mov_b32_e32 v115, v112
	v_mov_b32_e32 v117, v116
	v_mov_b32_e32 v118, v116
	v_mov_b32_e32 v119, v116
	v_mov_b32_e32 v105, v104
	v_mov_b32_e32 v106, v104
	v_mov_b32_e32 v107, v104
	v_mov_b32_e32 v109, v108
	v_mov_b32_e32 v110, v108
	v_mov_b32_e32 v111, v108
	s_mov_b64 s[2:3], 0
	v_mov_b32_e32 v97, v96
	v_mov_b32_e32 v98, v96
	v_mov_b32_e32 v99, v96
	v_mov_b32_e32 v101, v100
	v_mov_b32_e32 v102, v100
	v_mov_b32_e32 v103, v100
	s_branch .LBB0_369

; __device__ __forceinline__ f32x4 zero4() { float z = 0.f; asm volatile("" : "+v"(z)); return (f32x4){z, z, z, z}; }
; #define G_STAGE(bufoff, gbase) do { _Pragma("unroll") for (int _i = 0; _i < 2; ++_i) \
;     __builtin_amdgcn_global_load_lds((const unsigned*)((const char*)(gbase) + voff[_i]), (GLAS unsigned*)(lds + (bufoff) + ldsw + _i * 8192), 16, 0, 0); } while (0)
; __device__ __forceinline__ void gemm_phase(const Params& p, int l, const bf16_t* __restrict__ A, const bf16_t* __restrict__ Bt, int M, int N, int K,
;                            int epi, bf16_t* __restrict__ outp, char* smem, int wvi) {
;     ...
;   const int wid = wvi; int tidx = wvi * 64 + lane_id(); asm volatile("" : "+v"(tidx));
;   const int lane = tidx & 63, wr = wid >> 2, wc = wid & 3, fr = lane & 15, fq = lane >> 4;
;   const int nt = K / GBK;
;   unsigned voff[2];
; #pragma unroll
;   for (int i = 0; i < 2; ++i) { int R, C; stage_rc(tidx * 16 + i * 8192, R, C); voff[i] = (unsigned)(R * K + C) * 2u; }
;   const size_t kstep = (size_t)(GBK * 2), hstep = (size_t)GHALF * K * 2, tstep = 2 * hstep;
;   const unsigned ldsw = (unsigned)wid * 1024u;
;   const int aoff = lds_byte(wr * 64 + fr, fq * 8), boff = lds_byte(wc * 32 + fr, fq * 8);
;   constexpr int HTB = GHT * 2;
;     ...
;   const int nM = M / GBM, nN = N / GBM, nwg = nM * nN;
;   auto tile_of = [&](int Lw, int& pm_, int& pn_) {
;     int wgid = Lw;
;     { const int q = nwg / GNXCD, r = nwg % GNXCD, xcd = wgid % GNXCD, off = wgid / GNXCD; wgid = (xcd < r ? xcd * (q + 1) : r * (q + 1) + (xcd - r) * q) + off; }
;     const int nig = GWGM * nN, gid = wgid / nig, fm = gid * GWGM, gsz = min(nM - fm, GWGM);
;     pm_ = fm + ((wgid % nig) % gsz); pn_ = (wgid % nig) / gsz;
;   };
;   int Lw = blockIdx.x;
;   if (Lw < nwg) {
;     int pm, pn; tile_of(Lw, pm, pn);
;     const char* cA = (const char*)A + (size_t)pm * tstep;
;     const char* cB = (const char*)Bt + (size_t)pn * tstep;
;     f32x4 acc[2][2][4][2];
; #pragma unroll
;     for (int a = 0; a < 2; ++a)
; #pragma unroll
;       for (int b = 0; b < 2; ++b)
; #pragma unroll
;         for (int m = 0; m < 4; ++m)
; #pragma unroll
;           for (int n = 0; n < 2; ++n) acc[a][b][m][n] = zero4();
;     bf16x8 At[4][2], B0[2][2], B1[2][2];
;     G_STAGE(G_SB(0, 0), cB); G_STAGE(G_SA(0, 0), cA); G_STAGE(G_SB(0, 1), cB + hstep); G_STAGE(G_SA(0, 1), cA + hstep);
;     if (wr == 1) G_BAR;
.LBB0_559:
	s_andn2_b64 vcc, exec, s[2:3]
	s_cbranch_vccnz .LBB0_976
	v_readlane_b32 s0, v248, 9
	s_waitcnt vmcnt(1)
	v_mbcnt_lo_u32_b32 v0, -1, 0
	v_mbcnt_hi_u32_b32 v0, -1, v0
	s_nop 0
	v_add_u32_e32 v133, s0, v0
	v_readlane_b32 s0, v248, 33
	v_readlane_b32 s1, v248, 34
	s_andn2_b64 vcc, exec, s[0:1]
	s_cbranch_vccnz .LBB0_975
	v_lshlrev_b32_e32 v0, 4, v133
	v_add_u32_e32 v1, 0x2000, v0
	v_ashrrev_i32_e32 v2, 31, v1
	v_lshrrev_b32_e32 v2, 22, v2
	v_add_u32_e32 v2, v1, v2
	v_ashrrev_i32_e32 v128, 10, v2
	v_mul_i32_i24_e32 v2, 0x400, v128
	v_sub_u32_e32 v1, v1, v2
	v_lshrrev_b32_e32 v2, 4, v1
	v_bitop3_b32 v1, v2, v1, 32 bitop3:0x6c
	v_ashrrev_i32_e32 v2, 31, v1
	v_lshrrev_b32_e32 v2, 26, v2
	v_add_u32_e32 v2, v1, v2
	v_ashrrev_i32_e32 v129, 6, v2
	v_and_b32_e32 v2, 0xc0, v2
	v_sub_u32_e32 v1, v1, v2
	v_ashrrev_i16_sdwa v1, v199, sext(v1) dst_sel:DWORD dst_unused:UNUSED_PAD src0_sel:DWORD src1_sel:BYTE_0
	v_bfe_i32 v131, v1, 0, 16
	v_bfe_i32 v1, v133, 27, 1
	v_lshrrev_b32_e32 v1, 22, v1
	v_add_u32_e32 v1, v0, v1
	v_and_b32_e32 v1, 0xfffffc00, v1
	v_sub_u32_e32 v0, v0, v1
	v_lshrrev_b32_e32 v1, 4, v0
	v_bitop3_b32 v0, v1, v0, 32 bitop3:0x6c
	v_ashrrev_i32_e32 v2, 31, v133
	v_lshlrev_b32_e32 v3, 3, v128
	v_ashrrev_i32_e32 v1, 31, v0
	v_lshrrev_b32_e32 v2, 26, v2
	v_and_b32_e32 v3, 0x1ffff0, v3
	s_waitcnt vmcnt(0)
	v_lshlrev_b32_e32 v4, 5, v128
	v_lshrrev_b32_e32 v1, 26, v1
	v_add_u32_e32 v2, v133, v2
	v_add_u32_e32 v3, v129, v3
	v_and_b32_e32 v130, 32, v4
	v_add_u32_e32 v1, v0, v1
	v_ashrrev_i32_e32 v134, 6, v2
	v_lshl_or_b32 v3, v3, 10, v130
	v_ashrrev_i32_e32 v132, 6, v1
	v_lshlrev_b32_e32 v2, 3, v134
	v_and_b32_e32 v1, 0xc0, v1
	v_add_lshl_u32 v144, v3, v131, 1
	v_and_b32_e32 v2, 0x1ffff0, v2
	v_lshlrev_b32_e32 v3, 5, v134
	v_sub_u32_e32 v0, v0, v1
	v_add_u32_e32 v2, v132, v2
	v_and_b32_e32 v135, 32, v3
	v_ashrrev_i16_sdwa v0, v199, sext(v0) dst_sel:DWORD dst_unused:UNUSED_PAD src0_sel:DWORD src1_sel:BYTE_0
	v_lshl_or_b32 v2, v2, 10, v135
	v_bfe_i32 v136, v0, 0, 16
	s_add_i32 s30, s58, 0
	v_readlane_b32 s0, v248, 48
	v_add_lshl_u32 v146, v2, v136, 1
	v_mov_b32_e32 v20, v177
	v_mov_b32_e32 v28, v177
	v_mov_b32_e32 v12, v177
	v_mov_b32_e32 v24, v177
	v_mov_b32_e32 v4, v177
	v_mov_b32_e32 v16, v177
	v_mov_b32_e32 v0, v177
	v_mov_b32_e32 v8, v177
	v_mov_b32_e32 v84, v177
	v_mov_b32_e32 v100, v177
	v_mov_b32_e32 v76, v177
	v_mov_b32_e32 v92, v177
	v_mov_b32_e32 v64, v177
	v_mov_b32_e32 v80, v177
	v_mov_b32_e32 v52, v177
	v_mov_b32_e32 v68, v177
	v_mov_b32_e32 v56, v177
	v_mov_b32_e32 v72, v177
	v_mov_b32_e32 v44, v177
	v_mov_b32_e32 v60, v177
	v_mov_b32_e32 v36, v177
	v_mov_b32_e32 v48, v177
	v_mov_b32_e32 v32, v177
	v_mov_b32_e32 v40, v177
	v_mov_b32_e32 v120, v177
	v_mov_b32_e32 v124, v177
	v_mov_b32_e32 v112, v177
	v_mov_b32_e32 v116, v177
	v_mov_b32_e32 v104, v177
	v_mov_b32_e32 v108, v177
	v_mov_b32_e32 v88, v177
	v_mov_b32_e32 v96, v177
	s_add_i32 m0, s30, 0x10000
	v_readlane_b32 s1, v248, 49
	s_nop 4
	global_load_lds_dwordx4 v146, s[0:1]
	s_add_i32 m0, s30, 0x12000
	s_add_i32 s31, s30, 0x2000
	global_load_lds_dwordx4 v144, s[0:1]
	v_readlane_b32 s0, v248, 44
	s_mov_b32 m0, s30
	v_readlane_b32 s1, v248, 45
	s_add_i32 s88, s30, 0x4000
	s_add_i32 s89, s30, 0x6000
	s_nop 2
	global_load_lds_dwordx4 v146, s[0:1]
	s_mov_b32 m0, s31
	s_nop 0
	global_load_lds_dwordx4 v144, s[0:1]
	v_readlane_b32 s0, v248, 42
	s_add_i32 m0, s30, 0x14000
	v_readlane_b32 s1, v248, 43
	s_nop 4
	global_load_lds_dwordx4 v146, s[0:1]
	s_add_i32 m0, s30, 0x16000
	s_nop 0
	global_load_lds_dwordx4 v144, s[0:1]
	v_readlane_b32 s0, v248, 46
	s_mov_b32 m0, s88
	v_readlane_b32 s1, v248, 47
	s_nop 4
	global_load_lds_dwordx4 v146, s[0:1]
	s_mov_b32 m0, s89
	s_nop 0
	global_load_lds_dwordx4 v144, s[0:1]
	v_readlane_b32 s0, v248, 13
	v_readlane_b32 s1, v248, 14
	s_andn2_b64 vcc, exec, s[0:1]
	s_cbranch_vccnz .LBB0_563
	s_barrier
	s_setprio 1

; #define G_STAGE(bufoff, gbase) do { _Pragma("unroll") for (int _i = 0; _i < 2; ++_i) \
;     __builtin_amdgcn_global_load_lds((const unsigned*)((const char*)(gbase) + voff[_i]), (GLAS unsigned*)(lds + (bufoff) + ldsw + _i * 8192), 16, 0, 0); } while (0)
; #define G_LDA(dst, b, h) do { _Pragma("unroll") for (int m = 0; m < 4; ++m) _Pragma("unroll") for (int k = 0; k < 2; ++k) \
;     dst[m][k] = *(const GLAS bf16x8*)(lds + G_SA(b, h) + aoff + m * 2048 + k * 1024); } while (0)
; #define G_LDB(dst, b, h) do { _Pragma("unroll") for (int n = 0; n < 2; ++n) _Pragma("unroll") for (int k = 0; k < 2; ++k) \
;     dst[n][k] = *(const GLAS bf16x8*)(lds + G_SB(b, h) + boff + n * 2048 + k * 1024); } while (0)
; #define G_MMA(ai, bj, At_, Bt_) do { __builtin_amdgcn_s_setprio(1); \
;     _Pragma("unroll") for (int m = 0; m < 4; ++m) _Pragma("unroll") for (int n = 0; n < 2; ++n) _Pragma("unroll") for (int k = 0; k < 2; ++k) \
;       acc[ai][bj][m][n] = __builtin_amdgcn_mfma_f32_16x16x32_bf16(Bt_[n][k], At_[m][k], acc[ai][bj][m][n], 0, 0, 0); \
;     __builtin_amdgcn_s_setprio(0); } while (0)
; #define G_WAIT_V(n) asm volatile("s_waitcnt vmcnt(" #n ")" ::: "memory")
; #define G_WAIT_L(n) asm volatile("s_waitcnt lgkmcnt(" #n ")" ::: "memory")
; #define G_BAR __builtin_amdgcn_s_barrier()
; __device__ __forceinline__ void gemm_phase(const Params& p, int l, const bf16_t* __restrict__ A, const bf16_t* __restrict__ Bt, int M, int N, int K,
;                            int epi, bf16_t* __restrict__ outp, char* smem, int wvi) {
;     ...
;       for (int t = 0; t < nt; t += 2) {
;         const bool lastt = (t == nt - 2);
;         const char* a1 = cA + (size_t)(t + 1) * kstep;
;         const char* a2 = lastt ? nA : cA + (size_t)(t + 2) * kstep; const char* b2 = lastt ? nB : cB + (size_t)(t + 2) * kstep;
;         const char* a3 = a2 + kstep; const char* b3 = b2 + kstep;
;         G_LDB(B0, 0, 0); G_SCHED; G_LDA(At, 0, 0); G_STAGE(G_SA(1, 1), a1 + hstep);
;         G_WAIT_L(8); G_BAR; G_WAIT_L(0); G_MMA(0, 0, At, B0); G_BAR; G_SCHED;
;         G_LDB(B1, 0, 1); G_STAGE(G_SB(0, 0), b2);
;         G_BAR; G_WAIT_L(0); G_MMA(0, 1, At, B1); G_BAR;
;         G_LDA(At, 0, 1); G_STAGE(G_SA(0, 0), a2);
;         G_BAR; G_WAIT_L(0); G_MMA(1, 0, At, B0); G_BAR; G_SCHED;
;         G_STAGE(G_SB(0, 1), b2 + hstep);
;         G_WAIT_V(6); G_BAR; G_MMA(1, 1, At, B1); G_BAR;
.LBB0_568:
	s_add_u32 s2, s6, 0x100
	s_addc_u32 s3, s7, 0
	s_add_i32 s21, 0, 0x10000
	v_add_u32_e32 v140, s21, v159
	ds_read_b128 v[128:131], v140
	ds_read_b128 v[132:135], v140 offset:1024
	ds_read_b128 v[136:139], v140 offset:2048
	ds_read_b128 v[140:143], v140 offset:3072
	s_cmp_eq_u32 s20, 12
	s_cselect_b32 s29, s13, s3
	s_cselect_b32 s28, s12, s2
	s_cselect_b32 s5, s9, s17
	s_cselect_b32 s4, s1, s11
	v_lshl_add_u64 v[156:157], s[6:7], 0, v[152:153]
	s_add_i32 m0, s30, 0xc000
	ds_read_b128 v[162:165], v160
	ds_read_b128 v[166:169], v160 offset:1024
	ds_read_b128 v[170:173], v160 offset:2048
	ds_read_b128 v[182:185], v160 offset:3072
	ds_read_b128 v[186:189], v160 offset:4096
	ds_read_b128 v[214:217], v160 offset:5120
	ds_read_b128 v[218:221], v160 offset:6144
	ds_read_b128 v[222:225], v160 offset:7168
	global_load_lds_dwordx4 v[156:157], off
	v_lshl_add_u64 v[156:157], s[6:7], 0, v[154:155]
	s_add_i32 m0, s30, 0xe000
	s_nop 0
	global_load_lds_dwordx4 v[156:157], off
	s_waitcnt lgkmcnt(8)
	s_barrier
	s_waitcnt lgkmcnt(0)
	s_waitcnt lgkmcnt(0)
	v_mfma_f32_16x16x32_bf16 v[20:23], v[128:131], v[162:165], v[20:23]
	v_mfma_f32_16x16x32_bf16 v[28:31], v[136:139], v[162:165], v[28:31]
	v_mfma_f32_16x16x32_bf16 v[12:15], v[128:131], v[170:173], v[12:15]
	v_mfma_f32_16x16x32_bf16 v[24:27], v[136:139], v[170:173], v[24:27]
	v_mfma_f32_16x16x32_bf16 v[4:7], v[128:131], v[186:189], v[4:7]
	v_mfma_f32_16x16x32_bf16 v[16:19], v[136:139], v[186:189], v[16:19]
	v_mfma_f32_16x16x32_bf16 v[0:3], v[128:131], v[218:221], v[0:3]
	v_mfma_f32_16x16x32_bf16 v[8:11], v[136:139], v[218:221], v[8:11]
	v_mfma_f32_16x16x32_bf16 v[20:23], v[132:135], v[166:169], v[20:23]
	v_mfma_f32_16x16x32_bf16 v[28:31], v[140:143], v[166:169], v[28:31]
	v_mfma_f32_16x16x32_bf16 v[12:15], v[132:135], v[182:185], v[12:15]
	v_mfma_f32_16x16x32_bf16 v[24:27], v[140:143], v[182:185], v[24:27]
	v_mfma_f32_16x16x32_bf16 v[4:7], v[132:135], v[214:217], v[4:7]
	v_mfma_f32_16x16x32_bf16 v[16:19], v[140:143], v[214:217], v[16:19]
	v_mfma_f32_16x16x32_bf16 v[0:3], v[132:135], v[222:225], v[0:3]
	v_mfma_f32_16x16x32_bf16 v[8:11], v[140:143], v[222:225], v[8:11]
	s_barrier
	s_add_i32 s22, 0, 0x14000
	v_add_u32_e32 v156, s22, v159
	s_add_i32 s6, s21, s58
	ds_read_b128 v[226:229], v156
	ds_read_b128 v[230:233], v156 offset:1024
	ds_read_b128 v[234:237], v156 offset:2048
	ds_read_b128 v[238:241], v156 offset:3072
	v_lshl_add_u64 v[156:157], s[4:5], 0, v[146:147]
	s_mov_b32 m0, s6
	v_lshl_add_u64 v[174:175], s[4:5], 0, v[144:145]
	global_load_lds_dwordx4 v[156:157], off
	s_add_i32 m0, s6, 0x2000
	s_nop 0
	global_load_lds_dwordx4 v[174:175], off
	s_barrier
	s_waitcnt lgkmcnt(0)
	s_waitcnt lgkmcnt(0)
	v_mfma_f32_16x16x32_bf16 v[84:87], v[226:229], v[162:165], v[84:87]
	v_mfma_f32_16x16x32_bf16 v[100:103], v[234:237], v[162:165], v[100:103]
	v_mfma_f32_16x16x32_bf16 v[76:79], v[226:229], v[170:173], v[76:79]
	v_mfma_f32_16x16x32_bf16 v[92:95], v[234:237], v[170:173], v[92:95]
	v_mfma_f32_16x16x32_bf16 v[64:67], v[226:229], v[186:189], v[64:67]
	v_mfma_f32_16x16x32_bf16 v[80:83], v[234:237], v[186:189], v[80:83]
	v_mfma_f32_16x16x32_bf16 v[52:55], v[226:229], v[218:221], v[52:55]
	v_mfma_f32_16x16x32_bf16 v[68:71], v[234:237], v[218:221], v[68:71]
	v_mfma_f32_16x16x32_bf16 v[84:87], v[230:233], v[166:169], v[84:87]
	v_mfma_f32_16x16x32_bf16 v[100:103], v[238:241], v[166:169], v[100:103]
	v_mfma_f32_16x16x32_bf16 v[76:79], v[230:233], v[182:185], v[76:79]
	v_mfma_f32_16x16x32_bf16 v[92:95], v[238:241], v[182:185], v[92:95]
	v_mfma_f32_16x16x32_bf16 v[64:67], v[230:233], v[214:217], v[64:67]
	v_mfma_f32_16x16x32_bf16 v[80:83], v[238:241], v[214:217], v[80:83]
	v_mfma_f32_16x16x32_bf16 v[52:55], v[230:233], v[222:225], v[52:55]
	v_mfma_f32_16x16x32_bf16 v[68:71], v[238:241], v[222:225], v[68:71]
	s_mov_b32 m0, s30
	v_lshl_add_u64 v[190:191], s[28:29], 0, v[146:147]
	s_barrier
	ds_read_b128 v[162:165], v160 offset:16384
	ds_read_b128 v[166:169], v160 offset:17408
	ds_read_b128 v[170:173], v160 offset:18432
	ds_read_b128 v[182:185], v160 offset:19456
	ds_read_b128 v[186:189], v160 offset:20480
	ds_read_b128 v[214:217], v160 offset:21504
	ds_read_b128 v[218:221], v160 offset:22528
	ds_read_b128 v[222:225], v160 offset:23552
	global_load_lds_dwordx4 v[190:191], off
	v_lshl_add_u64 v[242:243], s[28:29], 0, v[144:145]
	s_mov_b32 m0, s31
	s_nop 0
	global_load_lds_dwordx4 v[242:243], off
	s_barrier
	s_waitcnt lgkmcnt(0)
	s_waitcnt lgkmcnt(0)
	v_mfma_f32_16x16x32_bf16 v[56:59], v[128:131], v[162:165], v[56:59]
	v_mfma_f32_16x16x32_bf16 v[72:75], v[136:139], v[162:165], v[72:75]
	v_mfma_f32_16x16x32_bf16 v[44:47], v[128:131], v[170:173], v[44:47]
	v_mfma_f32_16x16x32_bf16 v[60:63], v[136:139], v[170:173], v[60:63]
	v_mfma_f32_16x16x32_bf16 v[36:39], v[128:131], v[186:189], v[36:39]
	v_mfma_f32_16x16x32_bf16 v[48:51], v[136:139], v[186:189], v[48:51]
	v_mfma_f32_16x16x32_bf16 v[32:35], v[128:131], v[218:221], v[32:35]
	v_mfma_f32_16x16x32_bf16 v[40:43], v[136:139], v[218:221], v[40:43]
	v_mfma_f32_16x16x32_bf16 v[56:59], v[132:135], v[166:169], v[56:59]
	v_mfma_f32_16x16x32_bf16 v[72:75], v[140:143], v[166:169], v[72:75]
	v_mfma_f32_16x16x32_bf16 v[44:47], v[132:135], v[182:185], v[44:47]
	v_mfma_f32_16x16x32_bf16 v[60:63], v[140:143], v[182:185], v[60:63]
	v_mfma_f32_16x16x32_bf16 v[36:39], v[132:135], v[214:217], v[36:39]
	v_mfma_f32_16x16x32_bf16 v[48:51], v[140:143], v[214:217], v[48:51]
	v_mfma_f32_16x16x32_bf16 v[32:35], v[132:135], v[222:225], v[32:35]
	v_mfma_f32_16x16x32_bf16 v[40:43], v[140:143], v[222:225], v[40:43]
	s_barrier
; #define G_STAGE(bufoff, gbase) do { _Pragma("unroll") for (int _i = 0; _i < 2; ++_i) \
;     __builtin_amdgcn_global_load_lds((const unsigned*)((const char*)(gbase) + voff[_i]), (GLAS unsigned*)(lds + (bufoff) + ldsw + _i * 8192), 16, 0, 0); } while (0)
; #define G_LDA(dst, b, h) do { _Pragma("unroll") for (int m = 0; m < 4; ++m) _Pragma("unroll") for (int k = 0; k < 2; ++k) \
;     dst[m][k] = *(const GLAS bf16x8*)(lds + G_SA(b, h) + aoff + m * 2048 + k * 1024); } while (0)
; #define G_LDB(dst, b, h) do { _Pragma("unroll") for (int n = 0; n < 2; ++n) _Pragma("unroll") for (int k = 0; k < 2; ++k) \
;     dst[n][k] = *(const GLAS bf16x8*)(lds + G_SB(b, h) + boff + n * 2048 + k * 1024); } while (0)
; #define G_MMA(ai, bj, At_, Bt_) do { __builtin_amdgcn_s_setprio(1); \
;     _Pragma("unroll") for (int m = 0; m < 4; ++m) _Pragma("unroll") for (int n = 0; n < 2; ++n) _Pragma("unroll") for (int k = 0; k < 2; ++k) \
;       acc[ai][bj][m][n] = __builtin_amdgcn_mfma_f32_16x16x32_bf16(Bt_[n][k], At_[m][k], acc[ai][bj][m][n], 0, 0, 0); \
;     __builtin_amdgcn_s_setprio(0); } while (0)
; #define G_WAIT_V(n) asm volatile("s_waitcnt vmcnt(" #n ")" ::: "memory")
; #define G_WAIT_L(n) asm volatile("s_waitcnt lgkmcnt(" #n ")" ::: "memory")
; #define G_BAR __builtin_amdgcn_s_barrier()
; #define G_SCHED __builtin_amdgcn_sched_barrier(0)
; __device__ __forceinline__ void gemm_phase(const Params& p, int l, const bf16_t* __restrict__ A, const bf16_t* __restrict__ Bt, int M, int N, int K,
;                            int epi, bf16_t* __restrict__ outp, char* smem, int wvi) {
;     ...
;         G_WAIT_V(6); G_BAR; G_MMA(1, 1, At, B1); G_BAR;
;         G_LDB(B0, 1, 0); G_SCHED; G_LDA(At, 1, 0); G_STAGE(G_SA(0, 1), a2 + hstep);
;         G_WAIT_L(8); G_BAR; G_WAIT_L(0); G_MMA(0, 0, At, B0); G_BAR; G_SCHED;
;         G_LDB(B1, 1, 1); G_STAGE(G_SB(1, 0), b3);
;         G_BAR; G_WAIT_L(0); G_MMA(0, 1, At, B1); G_BAR;
;         G_LDA(At, 1, 1); G_STAGE(G_SA(1, 0), a3);
;         G_BAR; G_WAIT_L(0); G_MMA(1, 0, At, B0); G_BAR; G_SCHED;
	s_add_u32 s6, s4, 0x40000
	s_addc_u32 s7, s5, 0
	s_add_i32 s21, s22, s58
	v_lshl_add_u64 v[128:129], s[6:7], 0, v[146:147]
	s_mov_b32 m0, s21
	s_nop 0
	global_load_lds_dwordx4 v[128:129], off
	v_lshl_add_u64 v[128:129], s[6:7], 0, v[144:145]
	s_add_i32 m0, s21, 0x2000
	s_nop 0
	global_load_lds_dwordx4 v[128:129], off
	s_waitcnt vmcnt(6)
	s_barrier
	v_mfma_f32_16x16x32_bf16 v[120:123], v[226:229], v[162:165], v[120:123]
	v_mfma_f32_16x16x32_bf16 v[124:127], v[234:237], v[162:165], v[124:127]
	v_mfma_f32_16x16x32_bf16 v[112:115], v[226:229], v[170:173], v[112:115]
	v_mfma_f32_16x16x32_bf16 v[116:119], v[234:237], v[170:173], v[116:119]
	v_mfma_f32_16x16x32_bf16 v[104:107], v[226:229], v[186:189], v[104:107]
	v_mfma_f32_16x16x32_bf16 v[108:111], v[234:237], v[186:189], v[108:111]
	v_mfma_f32_16x16x32_bf16 v[88:91], v[226:229], v[218:221], v[88:91]
	v_mfma_f32_16x16x32_bf16 v[96:99], v[234:237], v[218:221], v[96:99]
	v_mfma_f32_16x16x32_bf16 v[120:123], v[230:233], v[166:169], v[120:123]
	v_mfma_f32_16x16x32_bf16 v[124:127], v[238:241], v[166:169], v[124:127]
	v_mfma_f32_16x16x32_bf16 v[112:115], v[230:233], v[182:185], v[112:115]
	v_mfma_f32_16x16x32_bf16 v[116:119], v[238:241], v[182:185], v[116:119]
	v_mfma_f32_16x16x32_bf16 v[104:107], v[230:233], v[214:217], v[104:107]
	v_mfma_f32_16x16x32_bf16 v[108:111], v[238:241], v[214:217], v[108:111]
	v_mfma_f32_16x16x32_bf16 v[88:91], v[230:233], v[222:225], v[88:91]
	v_mfma_f32_16x16x32_bf16 v[96:99], v[238:241], v[222:225], v[96:99]
	s_add_i32 s21, 0, 0x18000
	v_add_u32_e32 v140, s21, v159
	s_barrier
	ds_read_b128 v[128:131], v140
	ds_read_b128 v[132:135], v140 offset:1024
	ds_read_b128 v[136:139], v140 offset:2048
	ds_read_b128 v[140:143], v140 offset:3072
	s_add_u32 s6, s28, 0x40000
	s_addc_u32 s7, s29, 0
	s_mov_b32 m0, s88
	v_lshl_add_u64 v[226:227], s[6:7], 0, v[146:147]
	ds_read_b128 v[162:165], v160 offset:32768
	ds_read_b128 v[166:169], v160 offset:33792
	ds_read_b128 v[170:173], v160 offset:34816
	ds_read_b128 v[182:185], v160 offset:35840
	ds_read_b128 v[186:189], v160 offset:36864
	ds_read_b128 v[214:217], v160 offset:37888
	ds_read_b128 v[218:221], v160 offset:38912
	ds_read_b128 v[222:225], v160 offset:39936
	global_load_lds_dwordx4 v[226:227], off
	v_lshl_add_u64 v[226:227], s[6:7], 0, v[144:145]
	s_mov_b32 m0, s89
	s_nop 0
	global_load_lds_dwordx4 v[226:227], off
	s_waitcnt lgkmcnt(8)
	s_barrier
	s_waitcnt lgkmcnt(0)
	s_waitcnt lgkmcnt(0)
	v_mfma_f32_16x16x32_bf16 v[20:23], v[128:131], v[162:165], v[20:23]
	v_mfma_f32_16x16x32_bf16 v[28:31], v[136:139], v[162:165], v[28:31]
	v_mfma_f32_16x16x32_bf16 v[12:15], v[128:131], v[170:173], v[12:15]
	v_mfma_f32_16x16x32_bf16 v[24:27], v[136:139], v[170:173], v[24:27]
	v_mfma_f32_16x16x32_bf16 v[4:7], v[128:131], v[186:189], v[4:7]
	v_mfma_f32_16x16x32_bf16 v[16:19], v[136:139], v[186:189], v[16:19]
	v_mfma_f32_16x16x32_bf16 v[0:3], v[128:131], v[218:221], v[0:3]
	v_mfma_f32_16x16x32_bf16 v[8:11], v[136:139], v[218:221], v[8:11]
	v_mfma_f32_16x16x32_bf16 v[20:23], v[132:135], v[166:169], v[20:23]
	v_mfma_f32_16x16x32_bf16 v[28:31], v[140:143], v[166:169], v[28:31]
	v_mfma_f32_16x16x32_bf16 v[12:15], v[132:135], v[182:185], v[12:15]
	v_mfma_f32_16x16x32_bf16 v[24:27], v[140:143], v[182:185], v[24:27]
	v_mfma_f32_16x16x32_bf16 v[4:7], v[132:135], v[214:217], v[4:7]
	v_mfma_f32_16x16x32_bf16 v[16:19], v[140:143], v[214:217], v[16:19]
	v_mfma_f32_16x16x32_bf16 v[0:3], v[132:135], v[222:225], v[0:3]
	v_mfma_f32_16x16x32_bf16 v[8:11], v[140:143], v[222:225], v[8:11]
	s_barrier
	s_add_i32 s6, 0, 0x1c000
	s_add_i32 s7, s21, s58
	v_add_u32_e32 v161, s6, v159
	v_lshl_add_u64 v[156:157], v[156:157], 0, s[64:65]
	s_mov_b32 m0, s7
	ds_read_b128 v[226:229], v161
	ds_read_b128 v[230:233], v161 offset:1024
	ds_read_b128 v[234:237], v161 offset:2048
	ds_read_b128 v[238:241], v161 offset:3072
	global_load_lds_dwordx4 v[156:157], off
	v_lshl_add_u64 v[156:157], v[174:175], 0, s[64:65]
	s_add_i32 m0, s7, 0x2000
	s_nop 0
	global_load_lds_dwordx4 v[156:157], off
	s_barrier
	s_waitcnt lgkmcnt(0)
	s_waitcnt lgkmcnt(0)
	v_mfma_f32_16x16x32_bf16 v[84:87], v[226:229], v[162:165], v[84:87]
	v_mfma_f32_16x16x32_bf16 v[100:103], v[234:237], v[162:165], v[100:103]
	v_mfma_f32_16x16x32_bf16 v[76:79], v[226:229], v[170:173], v[76:79]
	v_mfma_f32_16x16x32_bf16 v[92:95], v[234:237], v[170:173], v[92:95]
	v_mfma_f32_16x16x32_bf16 v[64:67], v[226:229], v[186:189], v[64:67]
	v_mfma_f32_16x16x32_bf16 v[80:83], v[234:237], v[186:189], v[80:83]
	v_mfma_f32_16x16x32_bf16 v[52:55], v[226:229], v[218:221], v[52:55]
	v_mfma_f32_16x16x32_bf16 v[68:71], v[234:237], v[218:221], v[68:71]
	v_mfma_f32_16x16x32_bf16 v[84:87], v[230:233], v[166:169], v[84:87]
	v_mfma_f32_16x16x32_bf16 v[100:103], v[238:241], v[166:169], v[100:103]
	v_mfma_f32_16x16x32_bf16 v[76:79], v[230:233], v[182:185], v[76:79]
	v_mfma_f32_16x16x32_bf16 v[92:95], v[238:241], v[182:185], v[92:95]
	v_mfma_f32_16x16x32_bf16 v[64:67], v[230:233], v[214:217], v[64:67]
	v_mfma_f32_16x16x32_bf16 v[80:83], v[238:241], v[214:217], v[80:83]
	v_mfma_f32_16x16x32_bf16 v[52:55], v[230:233], v[222:225], v[52:55]
	v_mfma_f32_16x16x32_bf16 v[68:71], v[238:241], v[222:225], v[68:71]
	s_mov_b32 m0, s92
	v_lshl_add_u64 v[156:157], v[190:191], 0, s[64:65]
	s_barrier
; __device__ __forceinline__ u32x4 mk4(unsigned a, unsigned b, unsigned c, unsigned d) { return (u32x4){a, b, c, d}; }
; #define G_STAGE(bufoff, gbase) do { _Pragma("unroll") for (int _i = 0; _i < 2; ++_i) \
;     __builtin_amdgcn_global_load_lds((const unsigned*)((const char*)(gbase) + voff[_i]), (GLAS unsigned*)(lds + (bufoff) + ldsw + _i * 8192), 16, 0, 0); } while (0)
; __device__ __forceinline__ void gemm_phase(const Params& p, int l, const bf16_t* __restrict__ A, const bf16_t* __restrict__ Bt, int M, int N, int K,
;                            int epi, bf16_t* __restrict__ outp, char* smem, int wvi) {
;     ...
;         G_BAR; G_WAIT_L(0); G_MMA(0, 1, At, B1); G_BAR;
;         G_LDA(At, 1, 1); G_STAGE(G_SA(1, 0), a3);
;         G_BAR; G_WAIT_L(0); G_MMA(1, 0, At, B0); G_BAR; G_SCHED;
;         G_STAGE(G_SB(1, 1), b3 + hstep);
;         G_WAIT_V(6); G_BAR; G_MMA(1, 1, At, B1); G_BAR;
;     ...
;       if (pn < 12) {
;         bf16_t* dst; int ld, c0;
;         if (pn < 3) { dst = p.big; ld = 768; c0 = pn * 256; }
;         else if (pn < 5) { dst = p.big + (size_t)TA * 768; ld = 512; c0 = (pn - 3) * 256; }
;         else if (pn < 9) { dst = p.big + (size_t)TA * 1280; ld = 1024; c0 = (pn - 5) * 256; }
;         else { dst = p.big + (size_t)TA * 2304; ld = 768; c0 = (pn - 9) * 256; }
; #pragma unroll
;         for (int ai = 0; ai < 2; ++ai)
; #pragma unroll
;           for (int m = 0; m < 4; ++m) {
;             bf16_t* rp = dst + (size_t)(r0 + ai * GHALF + m * 16) * ld + c0 + wc * 32 + fq * 8;
; #pragma unroll
;             for (int bj = 0; bj < 2; ++bj) {
;               const f32x4 v0 = acc[ai][bj][m][0], v1 = acc[ai][bj][m][1];
;               *reinterpret_cast<u32x4*>(rp + bj * GHALF) = mk4(pk2(v0[0], v0[1]), pk2(v0[2], v0[3]), pk2(v1[0], v1[1]), pk2(v1[2], v1[3]));
;             }
;           }
;       } else if (wc == 0 && fq < 2) {
;         const float* db = p.dt_bias + l * 16 + fq * 8;
;         float dbv[8];
; #pragma unroll
;         for (int i = 0; i < 8; ++i) dbv[i] = db[i];
; #pragma unroll
;         for (int ai = 0; ai < 2; ++ai)
; #pragma unroll
;           for (int m = 0; m < 4; ++m) {
;             const f32x4 v0 = acc[ai][0][m][0], v1 = acc[ai][0][m][1];
;             float4 o0, o1;
;             o0.x = softplus_f(v0[0] + dbv[0]); o0.y = softplus_f(v0[1] + dbv[1]); o0.z = softplus_f(v0[2] + dbv[2]); o0.w = softplus_f(v0[3] + dbv[3]);
	ds_read_b128 v[162:165], v160 offset:49152
	ds_read_b128 v[166:169], v160 offset:50176
	ds_read_b128 v[170:173], v160 offset:51200
	ds_read_b128 v[182:185], v160 offset:52224
	ds_read_b128 v[186:189], v160 offset:53248
	ds_read_b128 v[214:217], v160 offset:54272
	ds_read_b128 v[218:221], v160 offset:55296
	ds_read_b128 v[222:225], v160 offset:56320
	global_load_lds_dwordx4 v[156:157], off
	v_lshl_add_u64 v[156:157], v[242:243], 0, s[64:65]
	s_mov_b32 m0, s93
	s_nop 0
	global_load_lds_dwordx4 v[156:157], off
	s_barrier
	s_waitcnt lgkmcnt(0)
	s_waitcnt lgkmcnt(0)
	v_mfma_f32_16x16x32_bf16 v[56:59], v[128:131], v[162:165], v[56:59]
	v_mfma_f32_16x16x32_bf16 v[72:75], v[136:139], v[162:165], v[72:75]
	v_mfma_f32_16x16x32_bf16 v[44:47], v[128:131], v[170:173], v[44:47]
	v_mfma_f32_16x16x32_bf16 v[60:63], v[136:139], v[170:173], v[60:63]
	v_mfma_f32_16x16x32_bf16 v[36:39], v[128:131], v[186:189], v[36:39]
	v_mfma_f32_16x16x32_bf16 v[48:51], v[136:139], v[186:189], v[48:51]
	v_mfma_f32_16x16x32_bf16 v[32:35], v[128:131], v[218:221], v[32:35]
	v_mfma_f32_16x16x32_bf16 v[40:43], v[136:139], v[218:221], v[40:43]
	v_mfma_f32_16x16x32_bf16 v[56:59], v[132:135], v[166:169], v[56:59]
	v_mfma_f32_16x16x32_bf16 v[72:75], v[140:143], v[166:169], v[72:75]
	v_mfma_f32_16x16x32_bf16 v[44:47], v[132:135], v[182:185], v[44:47]
	v_mfma_f32_16x16x32_bf16 v[60:63], v[140:143], v[182:185], v[60:63]
	v_mfma_f32_16x16x32_bf16 v[36:39], v[132:135], v[214:217], v[36:39]
	v_mfma_f32_16x16x32_bf16 v[48:51], v[140:143], v[214:217], v[48:51]
	v_mfma_f32_16x16x32_bf16 v[32:35], v[132:135], v[222:225], v[32:35]
	v_mfma_f32_16x16x32_bf16 v[40:43], v[140:143], v[222:225], v[40:43]
	s_barrier
	s_add_u32 s4, s4, 0x40080
	s_addc_u32 s5, s5, 0
	s_add_i32 s6, s6, s58
	v_lshl_add_u64 v[128:129], s[4:5], 0, v[146:147]
	s_mov_b32 m0, s6
	s_nop 0
	global_load_lds_dwordx4 v[128:129], off
	v_lshl_add_u64 v[128:129], s[4:5], 0, v[144:145]
	s_add_i32 m0, s6, 0x2000
	s_nop 0
	global_load_lds_dwordx4 v[128:129], off
	s_waitcnt vmcnt(6)
	s_barrier
	v_mfma_f32_16x16x32_bf16 v[120:123], v[226:229], v[162:165], v[120:123]
	v_mfma_f32_16x16x32_bf16 v[124:127], v[234:237], v[162:165], v[124:127]
	v_mfma_f32_16x16x32_bf16 v[112:115], v[226:229], v[170:173], v[112:115]
	v_mfma_f32_16x16x32_bf16 v[116:119], v[234:237], v[170:173], v[116:119]
	v_mfma_f32_16x16x32_bf16 v[104:107], v[226:229], v[186:189], v[104:107]
	v_mfma_f32_16x16x32_bf16 v[108:111], v[234:237], v[186:189], v[108:111]
	v_mfma_f32_16x16x32_bf16 v[88:91], v[226:229], v[218:221], v[88:91]
	v_mfma_f32_16x16x32_bf16 v[96:99], v[234:237], v[218:221], v[96:99]
	v_mfma_f32_16x16x32_bf16 v[120:123], v[230:233], v[166:169], v[120:123]
	v_mfma_f32_16x16x32_bf16 v[124:127], v[238:241], v[166:169], v[124:127]
	v_mfma_f32_16x16x32_bf16 v[112:115], v[230:233], v[182:185], v[112:115]
	v_mfma_f32_16x16x32_bf16 v[116:119], v[238:241], v[182:185], v[116:119]
	v_mfma_f32_16x16x32_bf16 v[104:107], v[230:233], v[214:217], v[104:107]
	v_mfma_f32_16x16x32_bf16 v[108:111], v[238:241], v[214:217], v[108:111]
	v_mfma_f32_16x16x32_bf16 v[88:91], v[230:233], v[222:225], v[88:91]
	v_mfma_f32_16x16x32_bf16 v[96:99], v[238:241], v[222:225], v[96:99]
	s_add_i32 s20, s20, 2
	s_add_u32 s11, s11, 0x100
	s_addc_u32 s17, s17, 0
	s_cmp_gt_u32 s20, 13
	s_mov_b64 s[6:7], s[2:3]
	s_barrier
	s_cbranch_scc0 .LBB0_568
	v_lshl_add_u32 v156, s0, 8, v158
	s_cmp_gt_i32 s16, 11
	s_mov_b64 s[2:3], -1
	s_mov_b32 s9, 0x41a00000
	s_cbranch_scc0 .LBB0_957
	s_and_saveexec_b64 s[6:7], s[24:25]
	s_cbranch_execz .LBB0_956
	global_load_dwordx4 v[132:135], v[148:149], off
	global_load_dwordx4 v[128:131], v[148:149], off offset:16
	s_waitcnt vmcnt(0)
	v_add_f32_e32 v136, v20, v132
	v_cmp_nlt_f32_e32 vcc, s9, v136
	s_and_saveexec_b64 s[2:3], vcc
	s_cbranch_execz .LBB0_577
	v_mul_f32_e32 v136, 0x3fb8aa3b, v136
	v_exp_f32_e32 v137, v136
	s_nop 0
	v_cmp_ngt_f32_e32 vcc, s18, v137
	s_and_saveexec_b64 s[0:1], vcc
	s_xor_b64 s[28:29], exec, s[0:1]
	s_cbranch_execz .LBB0_574
	v_add_f32_e32 v136, 1.0, v137
	s_mov_b32 s0, 0x800000
	v_cmp_gt_f32_e32 vcc, s0, v136
	s_mov_b32 s0, 0x3f317217
	s_nop 0
	v_cndmask_b32_e64 v137, 0, 32, vcc
	v_ldexp_f32 v136, v136, v137
	v_log_f32_e32 v136, v136
	s_nop 0
	v_mul_f32_e32 v137, 0x3f317217, v136
	v_fma_f32 v137, v136, s0, -v137
	v_fmac_f32_e32 v137, 0x3377d1cf, v136
	s_mov_b32 s0, 0x7f800000
	v_fmac_f32_e32 v137, 0x3f317217, v136
	v_cmp_lt_f32_e64 s[4:5], |v136|, s0
	s_nop 1
	v_cndmask_b32_e64 v136, v136, v137, s[4:5]
	v_cndmask_b32_e32 v137, 0, v212, vcc
	v_sub_f32_e32 v136, v136, v137

; #define G_WAIT_V(n) asm volatile("s_waitcnt vmcnt(" #n ")" ::: "memory")
; #define G_BAR __builtin_amdgcn_s_barrier()
; __device__ __forceinline__ void gemm_phase(const Params& p, int l, const bf16_t* __restrict__ A, const bf16_t* __restrict__ Bt, int M, int N, int K,
;                            int epi, bf16_t* __restrict__ outp, char* smem, int wvi) {
;     ...
;     G_WAIT_V(0);
;     if (wr == 0) G_BAR;
;     G_BAR;
.LBB0_972:
	v_readlane_b32 s0, v248, 17
	s_setprio 0
	s_waitcnt vmcnt(0)
	v_readlane_b32 s1, v248, 18
	v_readlane_b32 s92, v244, 32
	s_andn2_b64 vcc, exec, s[0:1]
	v_readlane_b32 s55, v244, 31
	v_readlane_b32 s93, v244, 33
	s_cbranch_vccnz .LBB0_974
	s_barrier

; __device__ __forceinline__ f32x4 zero4() { float z = 0.f; asm volatile("" : "+v"(z)); return (f32x4){z, z, z, z}; }
; #define G_STAGE(bufoff, gbase) do { _Pragma("unroll") for (int _i = 0; _i < 2; ++_i) \
;     __builtin_amdgcn_global_load_lds((const unsigned*)((const char*)(gbase) + voff[_i]), (GLAS unsigned*)(lds + (bufoff) + ldsw + _i * 8192), 16, 0, 0); } while (0)
; __device__ __forceinline__ void gemm_phase(const Params& p, int l, const bf16_t* __restrict__ A, const bf16_t* __restrict__ Bt, int M, int N, int K,
;                            int epi, bf16_t* __restrict__ outp, char* smem, int wvi) {
;     ...
;   const int wid = wvi; int tidx = wvi * 64 + lane_id(); asm volatile("" : "+v"(tidx));
;   const int lane = tidx & 63, wr = wid >> 2, wc = wid & 3, fr = lane & 15, fq = lane >> 4;
;   const int nt = K / GBK;
;   unsigned voff[2];
; #pragma unroll
;   for (int i = 0; i < 2; ++i) { int R, C; stage_rc(tidx * 16 + i * 8192, R, C); voff[i] = (unsigned)(R * K + C) * 2u; }
;   const size_t kstep = (size_t)(GBK * 2), hstep = (size_t)GHALF * K * 2, tstep = 2 * hstep;
;   const unsigned ldsw = (unsigned)wid * 1024u;
;   const int aoff = lds_byte(wr * 64 + fr, fq * 8), boff = lds_byte(wc * 32 + fr, fq * 8);
;   constexpr int HTB = GHT * 2;
;     ...
;   const int nM = M / GBM, nN = N / GBM, nwg = nM * nN;
;   auto tile_of = [&](int Lw, int& pm_, int& pn_) {
;     int wgid = Lw;
;     { const int q = nwg / GNXCD, r = nwg % GNXCD, xcd = wgid % GNXCD, off = wgid / GNXCD; wgid = (xcd < r ? xcd * (q + 1) : r * (q + 1) + (xcd - r) * q) + off; }
;     const int nig = GWGM * nN, gid = wgid / nig, fm = gid * GWGM, gsz = min(nM - fm, GWGM);
;     pm_ = fm + ((wgid % nig) % gsz); pn_ = (wgid % nig) / gsz;
;   };
;   int Lw = blockIdx.x;
;   if (Lw < nwg) {
;     int pm, pn; tile_of(Lw, pm, pn);
;     const char* cA = (const char*)A + (size_t)pm * tstep;
;     const char* cB = (const char*)Bt + (size_t)pn * tstep;
;     f32x4 acc[2][2][4][2];
; #pragma unroll
;     for (int a = 0; a < 2; ++a)
; #pragma unroll
;       for (int b = 0; b < 2; ++b)
; #pragma unroll
;         for (int m = 0; m < 4; ++m)
; #pragma unroll
;           for (int n = 0; n < 2; ++n) acc[a][b][m][n] = zero4();
;     bf16x8 At[4][2], B0[2][2], B1[2][2];
;     G_STAGE(G_SB(0, 0), cB); G_STAGE(G_SA(0, 0), cA); G_STAGE(G_SB(0, 1), cB + hstep); G_STAGE(G_SA(0, 1), cA + hstep);
;     if (wr == 1) G_BAR;
.LBB0_1030:
	s_andn2_b64 vcc, exec, s[2:3]
	s_cbranch_vccnz .LBB0_1188
	v_readlane_b32 s0, v248, 9
	s_waitcnt vmcnt(1)
	v_mbcnt_lo_u32_b32 v0, -1, 0
	v_mbcnt_hi_u32_b32 v0, -1, v0
	s_nop 0
	v_add_u32_e32 v130, s0, v0
	v_readlane_b32 s0, v248, 54
	v_readlane_b32 s1, v248, 55
	s_andn2_b64 vcc, exec, s[0:1]
	s_cbranch_vccnz .LBB0_1045
	v_lshlrev_b32_e32 v0, 4, v130
	v_add_u32_e32 v1, 0x2000, v0
	v_ashrrev_i32_e32 v2, 31, v1
	v_lshrrev_b32_e32 v2, 22, v2
	v_add_u32_e32 v2, v1, v2
	v_ashrrev_i32_e32 v134, 10, v2
	v_mul_i32_i24_e32 v2, 0x400, v134
	v_sub_u32_e32 v1, v1, v2
	v_lshrrev_b32_e32 v2, 4, v1
	v_bitop3_b32 v1, v2, v1, 32 bitop3:0x6c
	v_ashrrev_i32_e32 v2, 31, v1
	v_lshrrev_b32_e32 v2, 26, v2
	v_add_u32_e32 v2, v1, v2
	v_ashrrev_i32_e32 v135, 6, v2
	v_and_b32_e32 v2, 0xc0, v2
	v_sub_u32_e32 v1, v1, v2
	v_ashrrev_i16_sdwa v1, v199, sext(v1) dst_sel:DWORD dst_unused:UNUSED_PAD src0_sel:DWORD src1_sel:BYTE_0
	v_bfe_i32 v139, v1, 0, 16
	v_bfe_i32 v1, v130, 27, 1
	v_lshrrev_b32_e32 v1, 22, v1
	v_add_u32_e32 v1, v0, v1
	v_and_b32_e32 v1, 0xfffffc00, v1
	v_sub_u32_e32 v0, v0, v1
	v_lshrrev_b32_e32 v1, 4, v0
	v_ashrrev_i32_e32 v2, 31, v130
	v_lshlrev_b32_e32 v3, 3, v134
	v_bitop3_b32 v0, v1, v0, 32 bitop3:0x6c
	v_lshrrev_b32_e32 v2, 26, v2
	v_and_b32_e32 v3, 0xfffff0, v3
	v_ashrrev_i32_e32 v1, 31, v0
	v_add_u32_e32 v2, v130, v2
	v_add_u32_e32 v3, v135, v3
	s_movk_i32 s0, 0xb00
	s_waitcnt vmcnt(0)
	v_lshlrev_b32_e32 v4, 5, v134
	v_lshrrev_b32_e32 v1, 26, v1
	v_ashrrev_i32_e32 v133, 6, v2
	v_mul_lo_u32 v3, v3, s0
	v_and_b32_e32 v138, 32, v4
	v_add_u32_e32 v1, v0, v1
	v_lshlrev_b32_e32 v2, 3, v133
	v_or_b32_e32 v3, v3, v138
	v_ashrrev_i32_e32 v132, 6, v1
	v_and_b32_e32 v2, 0xfffff0, v2
	v_and_b32_e32 v1, 0xc0, v1
	v_add_lshl_u32 v128, v3, v139, 1
	v_add_u32_e32 v2, v132, v2
	v_lshlrev_b32_e32 v3, 5, v133
	v_sub_u32_e32 v0, v0, v1
	v_mul_lo_u32 v2, v2, s0
	v_and_b32_e32 v140, 32, v3
	v_ashrrev_i16_sdwa v0, v199, sext(v0) dst_sel:DWORD dst_unused:UNUSED_PAD src0_sel:DWORD src1_sel:BYTE_0
	v_or_b32_e32 v2, v2, v140
	v_bfe_i32 v141, v0, 0, 16
	s_add_i32 s1, s58, 0
	v_readlane_b32 s2, v247, 2
	v_add_lshl_u32 v176, v2, v141, 1
	v_mov_b32_e32 v20, v177
	v_mov_b32_e32 v28, v177
	v_mov_b32_e32 v12, v177
	v_mov_b32_e32 v24, v177
	v_mov_b32_e32 v4, v177
	v_mov_b32_e32 v16, v177
	v_mov_b32_e32 v0, v177
	v_mov_b32_e32 v8, v177
	v_mov_b32_e32 v80, v177
	v_mov_b32_e32 v92, v177
	v_mov_b32_e32 v64, v177
	v_mov_b32_e32 v84, v177
	v_mov_b32_e32 v52, v177
	v_mov_b32_e32 v76, v177
	v_mov_b32_e32 v40, v177
	v_mov_b32_e32 v60, v177
	v_mov_b32_e32 v68, v177
	v_mov_b32_e32 v88, v177
	v_mov_b32_e32 v48, v177
	v_mov_b32_e32 v72, v177
	v_mov_b32_e32 v36, v177
	v_mov_b32_e32 v56, v177
	v_mov_b32_e32 v32, v177
	v_mov_b32_e32 v44, v177
	v_mov_b32_e32 v120, v177
	v_mov_b32_e32 v124, v177
	v_mov_b32_e32 v112, v177
	v_mov_b32_e32 v116, v177
	v_mov_b32_e32 v104, v177
	v_mov_b32_e32 v108, v177
	v_mov_b32_e32 v96, v177
	v_mov_b32_e32 v100, v177
	s_add_i32 m0, s1, 0x10000
	v_readlane_b32 s3, v247, 3
	s_nop 4
	global_load_lds_dwordx4 v176, s[2:3]
	s_add_i32 m0, s1, 0x12000
	s_add_i32 s16, s1, 0x2000
	global_load_lds_dwordx4 v128, s[2:3]
	v_readlane_b32 s2, v248, 62
	s_mov_b32 m0, s1
	v_readlane_b32 s3, v248, 63
	s_add_i32 s17, s1, 0x4000
	s_add_i32 s20, s1, 0x6000
	s_nop 2
	global_load_lds_dwordx4 v176, s[2:3]
	s_mov_b32 m0, s16
	s_nop 0
	global_load_lds_dwordx4 v128, s[2:3]
	v_readlane_b32 s2, v248, 60
	s_add_i32 m0, s1, 0x14000
	v_readlane_b32 s3, v248, 61
	s_nop 4
	global_load_lds_dwordx4 v176, s[2:3]
	s_add_i32 m0, s1, 0x16000
	s_nop 0
	global_load_lds_dwordx4 v128, s[2:3]
	v_readlane_b32 s2, v247, 0
	s_mov_b32 m0, s17
	v_readlane_b32 s3, v247, 1
	s_nop 4
	global_load_lds_dwordx4 v176, s[2:3]
	s_mov_b32 m0, s20
	s_nop 0
	global_load_lds_dwordx4 v128, s[2:3]
	v_readlane_b32 s2, v248, 13
	v_readlane_b32 s3, v248, 14
	s_andn2_b64 vcc, exec, s[2:3]
	s_cbranch_vccnz .LBB0_1034
	s_barrier
	s_setprio 1

; #define G_STAGE(bufoff, gbase) do { _Pragma("unroll") for (int _i = 0; _i < 2; ++_i) \
;     __builtin_amdgcn_global_load_lds((const unsigned*)((const char*)(gbase) + voff[_i]), (GLAS unsigned*)(lds + (bufoff) + ldsw + _i * 8192), 16, 0, 0); } while (0)
; #define G_LDA(dst, b, h) do { _Pragma("unroll") for (int m = 0; m < 4; ++m) _Pragma("unroll") for (int k = 0; k < 2; ++k) \
;     dst[m][k] = *(const GLAS bf16x8*)(lds + G_SA(b, h) + aoff + m * 2048 + k * 1024); } while (0)
; #define G_LDB(dst, b, h) do { _Pragma("unroll") for (int n = 0; n < 2; ++n) _Pragma("unroll") for (int k = 0; k < 2; ++k) \
;     dst[n][k] = *(const GLAS bf16x8*)(lds + G_SB(b, h) + boff + n * 2048 + k * 1024); } while (0)
; #define G_MMA(ai, bj, At_, Bt_) do { __builtin_amdgcn_s_setprio(1); \
;     _Pragma("unroll") for (int m = 0; m < 4; ++m) _Pragma("unroll") for (int n = 0; n < 2; ++n) _Pragma("unroll") for (int k = 0; k < 2; ++k) \
;       acc[ai][bj][m][n] = __builtin_amdgcn_mfma_f32_16x16x32_bf16(Bt_[n][k], At_[m][k], acc[ai][bj][m][n], 0, 0, 0); \
;     __builtin_amdgcn_s_setprio(0); } while (0)
; #define G_WAIT_V(n) asm volatile("s_waitcnt vmcnt(" #n ")" ::: "memory")
; #define G_WAIT_L(n) asm volatile("s_waitcnt lgkmcnt(" #n ")" ::: "memory")
; #define G_BAR __builtin_amdgcn_s_barrier()
; __device__ __forceinline__ void gemm_phase(const Params& p, int l, const bf16_t* __restrict__ A, const bf16_t* __restrict__ Bt, int M, int N, int K,
;                            int epi, bf16_t* __restrict__ outp, char* smem, int wvi) {
;     ...
;       for (int t = 0; t < nt; t += 2) {
;         const bool lastt = (t == nt - 2);
;         const char* a1 = cA + (size_t)(t + 1) * kstep;
;         const char* a2 = lastt ? nA : cA + (size_t)(t + 2) * kstep; const char* b2 = lastt ? nB : cB + (size_t)(t + 2) * kstep;
;         const char* a3 = a2 + kstep; const char* b3 = b2 + kstep;
;         G_LDB(B0, 0, 0); G_SCHED; G_LDA(At, 0, 0); G_STAGE(G_SA(1, 1), a1 + hstep);
;         G_WAIT_L(8); G_BAR; G_WAIT_L(0); G_MMA(0, 0, At, B0); G_BAR; G_SCHED;
;         G_LDB(B1, 0, 1); G_STAGE(G_SB(0, 0), b2);
;         G_BAR; G_WAIT_L(0); G_MMA(0, 1, At, B1); G_BAR;
;         G_LDA(At, 0, 1); G_STAGE(G_SA(0, 0), a2);
;         G_BAR; G_WAIT_L(0); G_MMA(1, 0, At, B0); G_BAR; G_SCHED;
;         G_STAGE(G_SB(0, 1), b2 + hstep);
;         G_WAIT_V(6); G_BAR; G_MMA(1, 1, At, B1); G_BAR;
.LBB0_1039:
	s_add_u32 s2, s12, 0x100
	s_addc_u32 s3, s13, 0
	s_add_i32 s53, 0, 0x10000
	v_add_u32_e32 v139, s53, v137
	ds_read_b128 v[140:143], v139
	ds_read_b128 v[144:147], v139 offset:1024
	ds_read_b128 v[148:151], v139 offset:2048
	ds_read_b128 v[152:155], v139 offset:3072
	s_cmp_eq_u32 s31, 40
	s_cselect_b32 s15, s5, s3
	s_cselect_b32 s14, s4, s2
	s_cselect_b32 s11, s28, s30
	s_cselect_b32 s10, s27, s29
	v_lshl_add_u64 v[190:191], s[12:13], 0, v[132:133]
	s_add_i32 m0, s1, 0xc000
	ds_read_b128 v[156:159], v138
	ds_read_b128 v[160:163], v138 offset:1024
	ds_read_b128 v[164:167], v138 offset:2048
	ds_read_b128 v[168:171], v138 offset:3072
	ds_read_b128 v[172:175], v138 offset:4096
	ds_read_b128 v[182:185], v138 offset:5120
	ds_read_b128 v[186:189], v138 offset:6144
	ds_read_b128 v[214:217], v138 offset:7168
	global_load_lds_dwordx4 v[190:191], off
	v_lshl_add_u64 v[190:191], s[12:13], 0, v[134:135]
	s_add_i32 m0, s1, 0xe000
	s_nop 0
	global_load_lds_dwordx4 v[190:191], off
	s_waitcnt lgkmcnt(8)
	s_barrier
	s_waitcnt lgkmcnt(0)
	s_waitcnt lgkmcnt(0)
	v_mfma_f32_16x16x32_bf16 v[20:23], v[140:143], v[156:159], v[20:23]
	v_mfma_f32_16x16x32_bf16 v[28:31], v[148:151], v[156:159], v[28:31]
	v_mfma_f32_16x16x32_bf16 v[12:15], v[140:143], v[164:167], v[12:15]
	v_mfma_f32_16x16x32_bf16 v[24:27], v[148:151], v[164:167], v[24:27]
	v_mfma_f32_16x16x32_bf16 v[4:7], v[140:143], v[172:175], v[4:7]
	v_mfma_f32_16x16x32_bf16 v[16:19], v[148:151], v[172:175], v[16:19]
	v_mfma_f32_16x16x32_bf16 v[0:3], v[140:143], v[186:189], v[0:3]
	v_mfma_f32_16x16x32_bf16 v[8:11], v[148:151], v[186:189], v[8:11]
	v_mfma_f32_16x16x32_bf16 v[20:23], v[144:147], v[160:163], v[20:23]
	v_mfma_f32_16x16x32_bf16 v[28:31], v[152:155], v[160:163], v[28:31]
	v_mfma_f32_16x16x32_bf16 v[12:15], v[144:147], v[168:171], v[12:15]
	v_mfma_f32_16x16x32_bf16 v[24:27], v[152:155], v[168:171], v[24:27]
	v_mfma_f32_16x16x32_bf16 v[4:7], v[144:147], v[182:185], v[4:7]
	v_mfma_f32_16x16x32_bf16 v[16:19], v[152:155], v[182:185], v[16:19]
	v_mfma_f32_16x16x32_bf16 v[0:3], v[144:147], v[214:217], v[0:3]
	v_mfma_f32_16x16x32_bf16 v[8:11], v[152:155], v[214:217], v[8:11]
	s_barrier
	s_add_i32 s55, 0, 0x14000
	s_add_i32 s12, s53, s58
	v_add_u32_e32 v139, s55, v137
	v_lshl_add_u64 v[190:191], s[10:11], 0, v[176:177]
	s_mov_b32 m0, s12
	ds_read_b128 v[218:221], v139
	ds_read_b128 v[222:225], v139 offset:1024
	ds_read_b128 v[226:229], v139 offset:2048
	ds_read_b128 v[230:233], v139 offset:3072
	global_load_lds_dwordx4 v[190:191], off
	v_lshl_add_u64 v[234:235], s[10:11], 0, v[128:129]
	s_add_i32 m0, s12, 0x2000
	s_nop 0
	global_load_lds_dwordx4 v[234:235], off
	s_barrier
	s_waitcnt lgkmcnt(0)
	s_waitcnt lgkmcnt(0)
	v_mfma_f32_16x16x32_bf16 v[80:83], v[218:221], v[156:159], v[80:83]
	v_mfma_f32_16x16x32_bf16 v[92:95], v[226:229], v[156:159], v[92:95]
	v_mfma_f32_16x16x32_bf16 v[64:67], v[218:221], v[164:167], v[64:67]
	v_mfma_f32_16x16x32_bf16 v[84:87], v[226:229], v[164:167], v[84:87]
	v_mfma_f32_16x16x32_bf16 v[52:55], v[218:221], v[172:175], v[52:55]
	v_mfma_f32_16x16x32_bf16 v[76:79], v[226:229], v[172:175], v[76:79]
	v_mfma_f32_16x16x32_bf16 v[40:43], v[218:221], v[186:189], v[40:43]
	v_mfma_f32_16x16x32_bf16 v[60:63], v[226:229], v[186:189], v[60:63]
	v_mfma_f32_16x16x32_bf16 v[80:83], v[222:225], v[160:163], v[80:83]
	v_mfma_f32_16x16x32_bf16 v[92:95], v[230:233], v[160:163], v[92:95]
	v_mfma_f32_16x16x32_bf16 v[64:67], v[222:225], v[168:171], v[64:67]
	v_mfma_f32_16x16x32_bf16 v[84:87], v[230:233], v[168:171], v[84:87]
	v_mfma_f32_16x16x32_bf16 v[52:55], v[222:225], v[182:185], v[52:55]
	v_mfma_f32_16x16x32_bf16 v[76:79], v[230:233], v[182:185], v[76:79]
	v_mfma_f32_16x16x32_bf16 v[40:43], v[222:225], v[214:217], v[40:43]
	v_mfma_f32_16x16x32_bf16 v[60:63], v[230:233], v[214:217], v[60:63]
	s_mov_b32 m0, s1
	v_lshl_add_u64 v[236:237], s[14:15], 0, v[176:177]
	s_barrier
	ds_read_b128 v[156:159], v138 offset:16384
	ds_read_b128 v[160:163], v138 offset:17408
	ds_read_b128 v[164:167], v138 offset:18432
	ds_read_b128 v[168:171], v138 offset:19456
	ds_read_b128 v[172:175], v138 offset:20480
	ds_read_b128 v[182:185], v138 offset:21504
	ds_read_b128 v[186:189], v138 offset:22528
	ds_read_b128 v[214:217], v138 offset:23552
	global_load_lds_dwordx4 v[236:237], off
	v_lshl_add_u64 v[238:239], s[14:15], 0, v[128:129]
	s_mov_b32 m0, s16
	s_nop 0
	global_load_lds_dwordx4 v[238:239], off
	s_barrier
	s_waitcnt lgkmcnt(0)
	s_waitcnt lgkmcnt(0)
	v_mfma_f32_16x16x32_bf16 v[68:71], v[140:143], v[156:159], v[68:71]
	v_mfma_f32_16x16x32_bf16 v[88:91], v[148:151], v[156:159], v[88:91]
	v_mfma_f32_16x16x32_bf16 v[48:51], v[140:143], v[164:167], v[48:51]
	v_mfma_f32_16x16x32_bf16 v[72:75], v[148:151], v[164:167], v[72:75]
	v_mfma_f32_16x16x32_bf16 v[36:39], v[140:143], v[172:175], v[36:39]
	v_mfma_f32_16x16x32_bf16 v[56:59], v[148:151], v[172:175], v[56:59]
	v_mfma_f32_16x16x32_bf16 v[32:35], v[140:143], v[186:189], v[32:35]
	v_mfma_f32_16x16x32_bf16 v[44:47], v[148:151], v[186:189], v[44:47]
	v_mfma_f32_16x16x32_bf16 v[68:71], v[144:147], v[160:163], v[68:71]
	v_mfma_f32_16x16x32_bf16 v[88:91], v[152:155], v[160:163], v[88:91]
	v_mfma_f32_16x16x32_bf16 v[48:51], v[144:147], v[168:171], v[48:51]
	v_mfma_f32_16x16x32_bf16 v[72:75], v[152:155], v[168:171], v[72:75]
	v_mfma_f32_16x16x32_bf16 v[36:39], v[144:147], v[182:185], v[36:39]
	v_mfma_f32_16x16x32_bf16 v[56:59], v[152:155], v[182:185], v[56:59]
	v_mfma_f32_16x16x32_bf16 v[32:35], v[144:147], v[214:217], v[32:35]
	v_mfma_f32_16x16x32_bf16 v[44:47], v[152:155], v[214:217], v[44:47]
	s_barrier
; #define G_STAGE(bufoff, gbase) do { _Pragma("unroll") for (int _i = 0; _i < 2; ++_i) \
;     __builtin_amdgcn_global_load_lds((const unsigned*)((const char*)(gbase) + voff[_i]), (GLAS unsigned*)(lds + (bufoff) + ldsw + _i * 8192), 16, 0, 0); } while (0)
; #define G_LDA(dst, b, h) do { _Pragma("unroll") for (int m = 0; m < 4; ++m) _Pragma("unroll") for (int k = 0; k < 2; ++k) \
;     dst[m][k] = *(const GLAS bf16x8*)(lds + G_SA(b, h) + aoff + m * 2048 + k * 1024); } while (0)
; #define G_LDB(dst, b, h) do { _Pragma("unroll") for (int n = 0; n < 2; ++n) _Pragma("unroll") for (int k = 0; k < 2; ++k) \
;     dst[n][k] = *(const GLAS bf16x8*)(lds + G_SB(b, h) + boff + n * 2048 + k * 1024); } while (0)
; #define G_MMA(ai, bj, At_, Bt_) do { __builtin_amdgcn_s_setprio(1); \
;     _Pragma("unroll") for (int m = 0; m < 4; ++m) _Pragma("unroll") for (int n = 0; n < 2; ++n) _Pragma("unroll") for (int k = 0; k < 2; ++k) \
;       acc[ai][bj][m][n] = __builtin_amdgcn_mfma_f32_16x16x32_bf16(Bt_[n][k], At_[m][k], acc[ai][bj][m][n], 0, 0, 0); \
;     __builtin_amdgcn_s_setprio(0); } while (0)
; #define G_WAIT_V(n) asm volatile("s_waitcnt vmcnt(" #n ")" ::: "memory")
; #define G_WAIT_L(n) asm volatile("s_waitcnt lgkmcnt(" #n ")" ::: "memory")
; #define G_BAR __builtin_amdgcn_s_barrier()
; #define G_SCHED __builtin_amdgcn_sched_barrier(0)
; __device__ __forceinline__ void gemm_phase(const Params& p, int l, const bf16_t* __restrict__ A, const bf16_t* __restrict__ Bt, int M, int N, int K,
;                            int epi, bf16_t* __restrict__ outp, char* smem, int wvi) {
;     ...
;         G_WAIT_V(6); G_BAR; G_MMA(1, 1, At, B1); G_BAR;
;         G_LDB(B0, 1, 0); G_SCHED; G_LDA(At, 1, 0); G_STAGE(G_SA(0, 1), a2 + hstep);
;         G_WAIT_L(8); G_BAR; G_WAIT_L(0); G_MMA(0, 0, At, B0); G_BAR; G_SCHED;
;         G_LDB(B1, 1, 1); G_STAGE(G_SB(1, 0), b3);
;         G_BAR; G_WAIT_L(0); G_MMA(0, 1, At, B1); G_BAR;
;         G_LDA(At, 1, 1); G_STAGE(G_SA(1, 0), a3);
;         G_BAR; G_WAIT_L(0); G_MMA(1, 0, At, B0); G_BAR; G_SCHED;
	s_add_u32 s12, s10, 0xb0000
	s_addc_u32 s13, s11, 0
	s_add_i32 s53, s55, s58
	v_lshl_add_u64 v[140:141], s[12:13], 0, v[176:177]
	s_mov_b32 m0, s53
	s_nop 0
	global_load_lds_dwordx4 v[140:141], off
	v_lshl_add_u64 v[140:141], s[12:13], 0, v[128:129]
	s_add_i32 m0, s53, 0x2000
	s_nop 0
	global_load_lds_dwordx4 v[140:141], off
	s_waitcnt vmcnt(6)
	s_barrier
	v_mfma_f32_16x16x32_bf16 v[120:123], v[218:221], v[156:159], v[120:123]
	v_mfma_f32_16x16x32_bf16 v[124:127], v[226:229], v[156:159], v[124:127]
	v_mfma_f32_16x16x32_bf16 v[112:115], v[218:221], v[164:167], v[112:115]
	v_mfma_f32_16x16x32_bf16 v[116:119], v[226:229], v[164:167], v[116:119]
	v_mfma_f32_16x16x32_bf16 v[104:107], v[218:221], v[172:175], v[104:107]
	v_mfma_f32_16x16x32_bf16 v[108:111], v[226:229], v[172:175], v[108:111]
	v_mfma_f32_16x16x32_bf16 v[96:99], v[218:221], v[186:189], v[96:99]
	v_mfma_f32_16x16x32_bf16 v[100:103], v[226:229], v[186:189], v[100:103]
	v_mfma_f32_16x16x32_bf16 v[120:123], v[222:225], v[160:163], v[120:123]
	v_mfma_f32_16x16x32_bf16 v[124:127], v[230:233], v[160:163], v[124:127]
	v_mfma_f32_16x16x32_bf16 v[112:115], v[222:225], v[168:171], v[112:115]
	v_mfma_f32_16x16x32_bf16 v[116:119], v[230:233], v[168:171], v[116:119]
	v_mfma_f32_16x16x32_bf16 v[104:107], v[222:225], v[182:185], v[104:107]
	v_mfma_f32_16x16x32_bf16 v[108:111], v[230:233], v[182:185], v[108:111]
	v_mfma_f32_16x16x32_bf16 v[96:99], v[222:225], v[214:217], v[96:99]
	v_mfma_f32_16x16x32_bf16 v[100:103], v[230:233], v[214:217], v[100:103]
	s_add_i32 s53, 0, 0x18000
	v_add_u32_e32 v139, s53, v137
	s_barrier
	ds_read_b128 v[140:143], v139
	ds_read_b128 v[144:147], v139 offset:1024
	ds_read_b128 v[148:151], v139 offset:2048
	ds_read_b128 v[152:155], v139 offset:3072
	s_add_u32 s12, s14, 0xb0000
	s_addc_u32 s13, s15, 0
	s_mov_b32 m0, s17
	v_lshl_add_u64 v[218:219], s[12:13], 0, v[176:177]
	ds_read_b128 v[156:159], v138 offset:32768
	ds_read_b128 v[160:163], v138 offset:33792
	ds_read_b128 v[164:167], v138 offset:34816
	ds_read_b128 v[168:171], v138 offset:35840
	ds_read_b128 v[172:175], v138 offset:36864
	ds_read_b128 v[182:185], v138 offset:37888
	ds_read_b128 v[186:189], v138 offset:38912
	ds_read_b128 v[214:217], v138 offset:39936
	global_load_lds_dwordx4 v[218:219], off
	v_lshl_add_u64 v[218:219], s[12:13], 0, v[128:129]
	s_mov_b32 m0, s20
	s_nop 0
	global_load_lds_dwordx4 v[218:219], off
	s_waitcnt lgkmcnt(8)
	s_barrier
	s_waitcnt lgkmcnt(0)
	s_waitcnt lgkmcnt(0)
	v_mfma_f32_16x16x32_bf16 v[20:23], v[140:143], v[156:159], v[20:23]
	v_mfma_f32_16x16x32_bf16 v[28:31], v[148:151], v[156:159], v[28:31]
	v_mfma_f32_16x16x32_bf16 v[12:15], v[140:143], v[164:167], v[12:15]
	v_mfma_f32_16x16x32_bf16 v[24:27], v[148:151], v[164:167], v[24:27]
	v_mfma_f32_16x16x32_bf16 v[4:7], v[140:143], v[172:175], v[4:7]
	v_mfma_f32_16x16x32_bf16 v[16:19], v[148:151], v[172:175], v[16:19]
	v_mfma_f32_16x16x32_bf16 v[0:3], v[140:143], v[186:189], v[0:3]
	v_mfma_f32_16x16x32_bf16 v[8:11], v[148:151], v[186:189], v[8:11]
	v_mfma_f32_16x16x32_bf16 v[20:23], v[144:147], v[160:163], v[20:23]
	v_mfma_f32_16x16x32_bf16 v[28:31], v[152:155], v[160:163], v[28:31]
	v_mfma_f32_16x16x32_bf16 v[12:15], v[144:147], v[168:171], v[12:15]
	v_mfma_f32_16x16x32_bf16 v[24:27], v[152:155], v[168:171], v[24:27]
	v_mfma_f32_16x16x32_bf16 v[4:7], v[144:147], v[182:185], v[4:7]
	v_mfma_f32_16x16x32_bf16 v[16:19], v[152:155], v[182:185], v[16:19]
	v_mfma_f32_16x16x32_bf16 v[0:3], v[144:147], v[214:217], v[0:3]
	v_mfma_f32_16x16x32_bf16 v[8:11], v[152:155], v[214:217], v[8:11]
	s_barrier
	s_add_i32 s12, 0, 0x1c000
	s_add_i32 s13, s53, s58
	v_add_u32_e32 v139, s12, v137
	v_lshl_add_u64 v[190:191], v[190:191], 0, s[64:65]
	s_mov_b32 m0, s13
	ds_read_b128 v[218:221], v139
	ds_read_b128 v[222:225], v139 offset:1024
	ds_read_b128 v[226:229], v139 offset:2048
	ds_read_b128 v[230:233], v139 offset:3072
	global_load_lds_dwordx4 v[190:191], off
	v_lshl_add_u64 v[190:191], v[234:235], 0, s[64:65]
	s_add_i32 m0, s13, 0x2000
	s_nop 0
	global_load_lds_dwordx4 v[190:191], off
	s_barrier
	s_waitcnt lgkmcnt(0)
	s_waitcnt lgkmcnt(0)
	v_mfma_f32_16x16x32_bf16 v[80:83], v[218:221], v[156:159], v[80:83]
	v_mfma_f32_16x16x32_bf16 v[92:95], v[226:229], v[156:159], v[92:95]
	v_mfma_f32_16x16x32_bf16 v[64:67], v[218:221], v[164:167], v[64:67]
	v_mfma_f32_16x16x32_bf16 v[84:87], v[226:229], v[164:167], v[84:87]
	v_mfma_f32_16x16x32_bf16 v[52:55], v[218:221], v[172:175], v[52:55]
	v_mfma_f32_16x16x32_bf16 v[76:79], v[226:229], v[172:175], v[76:79]
	v_mfma_f32_16x16x32_bf16 v[40:43], v[218:221], v[186:189], v[40:43]
	v_mfma_f32_16x16x32_bf16 v[60:63], v[226:229], v[186:189], v[60:63]
	v_mfma_f32_16x16x32_bf16 v[80:83], v[222:225], v[160:163], v[80:83]
	v_mfma_f32_16x16x32_bf16 v[92:95], v[230:233], v[160:163], v[92:95]
	v_mfma_f32_16x16x32_bf16 v[64:67], v[222:225], v[168:171], v[64:67]
	v_mfma_f32_16x16x32_bf16 v[84:87], v[230:233], v[168:171], v[84:87]
	v_mfma_f32_16x16x32_bf16 v[52:55], v[222:225], v[182:185], v[52:55]
	v_mfma_f32_16x16x32_bf16 v[76:79], v[230:233], v[182:185], v[76:79]
	v_mfma_f32_16x16x32_bf16 v[40:43], v[222:225], v[214:217], v[40:43]
	v_mfma_f32_16x16x32_bf16 v[60:63], v[230:233], v[214:217], v[60:63]
	s_mov_b32 m0, s0
	v_lshl_add_u64 v[190:191], v[236:237], 0, s[64:65]
	s_barrier
	ds_read_b128 v[156:159], v138 offset:49152
	ds_read_b128 v[160:163], v138 offset:50176
	ds_read_b128 v[164:167], v138 offset:51200
	ds_read_b128 v[168:171], v138 offset:52224
	ds_read_b128 v[172:175], v138 offset:53248
	ds_read_b128 v[182:185], v138 offset:54272
	ds_read_b128 v[186:189], v138 offset:55296
	ds_read_b128 v[214:217], v138 offset:56320
	global_load_lds_dwordx4 v[190:191], off
	v_lshl_add_u64 v[190:191], v[238:239], 0, s[64:65]
	s_mov_b32 m0, s21
	s_nop 0
	global_load_lds_dwordx4 v[190:191], off
	s_barrier
; __device__ __forceinline__ u32x4 mk4(unsigned a, unsigned b, unsigned c, unsigned d) { return (u32x4){a, b, c, d}; }
; #define G_STAGE(bufoff, gbase) do { _Pragma("unroll") for (int _i = 0; _i < 2; ++_i) \
;     __builtin_amdgcn_global_load_lds((const unsigned*)((const char*)(gbase) + voff[_i]), (GLAS unsigned*)(lds + (bufoff) + ldsw + _i * 8192), 16, 0, 0); } while (0)
; #define G_MMA(ai, bj, At_, Bt_) do { __builtin_amdgcn_s_setprio(1); \
;     _Pragma("unroll") for (int m = 0; m < 4; ++m) _Pragma("unroll") for (int n = 0; n < 2; ++n) _Pragma("unroll") for (int k = 0; k < 2; ++k) \
;       acc[ai][bj][m][n] = __builtin_amdgcn_mfma_f32_16x16x32_bf16(Bt_[n][k], At_[m][k], acc[ai][bj][m][n], 0, 0, 0); \
;     __builtin_amdgcn_s_setprio(0); } while (0)
; #define G_WAIT_V(n) asm volatile("s_waitcnt vmcnt(" #n ")" ::: "memory")
; #define G_WAIT_L(n) asm volatile("s_waitcnt lgkmcnt(" #n ")" ::: "memory")
; #define G_BAR __builtin_amdgcn_s_barrier()
; #define G_SCHED __builtin_amdgcn_sched_barrier(0)
; __device__ __forceinline__ void gemm_phase(const Params& p, int l, const bf16_t* __restrict__ A, const bf16_t* __restrict__ Bt, int M, int N, int K,
;                            int epi, bf16_t* __restrict__ outp, char* smem, int wvi) {
;     ...
;         G_BAR; G_WAIT_L(0); G_MMA(1, 0, At, B0); G_BAR; G_SCHED;
;         G_STAGE(G_SB(1, 1), b3 + hstep);
;         G_WAIT_V(6); G_BAR; G_MMA(1, 1, At, B1); G_BAR;
;       }
;       const int brow = pm * GBM, bcol = pn * GBM;
;     const int r0 = brow + wr * 64 + fr;
;     if (epi == EPI_PLAIN) {
; #pragma unroll
;       for (int ai = 0; ai < 2; ++ai)
; #pragma unroll
;         for (int m = 0; m < 4; ++m) {
;           bf16_t* rp = outp + (size_t)(r0 + ai * GHALF + m * 16) * N + bcol + wc * 32 + fq * 8;
; #pragma unroll
;           for (int bj = 0; bj < 2; ++bj) {
;             const f32x4 v0 = acc[ai][bj][m][0], v1 = acc[ai][bj][m][1];
;             *reinterpret_cast<u32x4*>(rp + bj * GHALF) = mk4(pk2(v0[0], v0[1]), pk2(v0[2], v0[3]), pk2(v1[0], v1[1]), pk2(v1[2], v1[3]));
;           }
;         }
	s_waitcnt lgkmcnt(0)
	s_waitcnt lgkmcnt(0)
	v_mfma_f32_16x16x32_bf16 v[68:71], v[140:143], v[156:159], v[68:71]
	v_mfma_f32_16x16x32_bf16 v[88:91], v[148:151], v[156:159], v[88:91]
	v_mfma_f32_16x16x32_bf16 v[48:51], v[140:143], v[164:167], v[48:51]
	v_mfma_f32_16x16x32_bf16 v[72:75], v[148:151], v[164:167], v[72:75]
	v_mfma_f32_16x16x32_bf16 v[36:39], v[140:143], v[172:175], v[36:39]
	v_mfma_f32_16x16x32_bf16 v[56:59], v[148:151], v[172:175], v[56:59]
	v_mfma_f32_16x16x32_bf16 v[32:35], v[140:143], v[186:189], v[32:35]
	v_mfma_f32_16x16x32_bf16 v[44:47], v[148:151], v[186:189], v[44:47]
	v_mfma_f32_16x16x32_bf16 v[68:71], v[144:147], v[160:163], v[68:71]
	v_mfma_f32_16x16x32_bf16 v[88:91], v[152:155], v[160:163], v[88:91]
	v_mfma_f32_16x16x32_bf16 v[48:51], v[144:147], v[168:171], v[48:51]
	v_mfma_f32_16x16x32_bf16 v[72:75], v[152:155], v[168:171], v[72:75]
	v_mfma_f32_16x16x32_bf16 v[36:39], v[144:147], v[182:185], v[36:39]
	v_mfma_f32_16x16x32_bf16 v[56:59], v[152:155], v[182:185], v[56:59]
	v_mfma_f32_16x16x32_bf16 v[32:35], v[144:147], v[214:217], v[32:35]
	v_mfma_f32_16x16x32_bf16 v[44:47], v[152:155], v[214:217], v[44:47]
	s_barrier
	s_add_u32 s10, s10, 0xb0080
	s_addc_u32 s11, s11, 0
	s_add_i32 s12, s12, s58
	v_lshl_add_u64 v[140:141], s[10:11], 0, v[176:177]
	s_mov_b32 m0, s12
	s_nop 0
	global_load_lds_dwordx4 v[140:141], off
	v_lshl_add_u64 v[140:141], s[10:11], 0, v[128:129]
	s_add_i32 m0, s12, 0x2000
	s_nop 0
	global_load_lds_dwordx4 v[140:141], off
	s_waitcnt vmcnt(6)
	s_barrier
	v_mfma_f32_16x16x32_bf16 v[120:123], v[218:221], v[156:159], v[120:123]
	v_mfma_f32_16x16x32_bf16 v[124:127], v[226:229], v[156:159], v[124:127]
	v_mfma_f32_16x16x32_bf16 v[112:115], v[218:221], v[164:167], v[112:115]
	v_mfma_f32_16x16x32_bf16 v[116:119], v[226:229], v[164:167], v[116:119]
	v_mfma_f32_16x16x32_bf16 v[104:107], v[218:221], v[172:175], v[104:107]
	v_mfma_f32_16x16x32_bf16 v[108:111], v[226:229], v[172:175], v[108:111]
	v_mfma_f32_16x16x32_bf16 v[96:99], v[218:221], v[186:189], v[96:99]
	v_mfma_f32_16x16x32_bf16 v[100:103], v[226:229], v[186:189], v[100:103]
	v_mfma_f32_16x16x32_bf16 v[120:123], v[222:225], v[160:163], v[120:123]
	v_mfma_f32_16x16x32_bf16 v[124:127], v[230:233], v[160:163], v[124:127]
	v_mfma_f32_16x16x32_bf16 v[112:115], v[222:225], v[168:171], v[112:115]
	v_mfma_f32_16x16x32_bf16 v[116:119], v[230:233], v[168:171], v[116:119]
	v_mfma_f32_16x16x32_bf16 v[104:107], v[222:225], v[182:185], v[104:107]
	v_mfma_f32_16x16x32_bf16 v[108:111], v[230:233], v[182:185], v[108:111]
	v_mfma_f32_16x16x32_bf16 v[96:99], v[222:225], v[214:217], v[96:99]
	v_mfma_f32_16x16x32_bf16 v[100:103], v[230:233], v[214:217], v[100:103]
	s_add_i32 s31, s31, 2
	s_add_u32 s29, s29, 0x100
	s_addc_u32 s30, s30, 0
	s_cmp_gt_u32 s31, 41
	s_mov_b64 s[12:13], s[2:3]
	s_barrier
	s_cbranch_scc0 .LBB0_1039
	s_lshl_b32 s2, s26, 8
	v_lshl_add_u32 v140, s25, 8, v136
	s_ashr_i32 s3, s2, 31
	v_ashrrev_i32_e32 v141, 31, v140
	v_lshl_add_u64 v[142:143], s[2:3], 1, v[130:131]
	v_lshlrev_b64 v[144:145], 11, v[140:141]
	v_lshl_add_u64 v[144:145], v[142:143], 0, v[144:145]
	v_cvt_pk_bf16_f32 v20, v20, v21
	v_cvt_pk_bf16_f32 v21, v22, v23
	v_cvt_pk_bf16_f32 v22, v28, v29
	v_cvt_pk_bf16_f32 v23, v30, v31
	global_store_dwordx4 v[144:145], v[20:23], off
	v_cvt_pk_bf16_f32 v12, v12, v13
	v_cvt_pk_bf16_f32 v13, v14, v15
	v_cvt_pk_bf16_f32 v20, v80, v81
	v_cvt_pk_bf16_f32 v21, v82, v83
	v_cvt_pk_bf16_f32 v22, v92, v93
	v_cvt_pk_bf16_f32 v23, v94, v95
	global_store_dwordx4 v[144:145], v[20:23], off offset:256
	v_cvt_pk_bf16_f32 v14, v24, v25
	v_cvt_pk_bf16_f32 v15, v26, v27
	v_or_b32_e32 v20, 16, v140
	v_ashrrev_i32_e32 v21, 31, v20
	v_lshlrev_b64 v[20:21], 11, v[20:21]
	v_lshl_add_u64 v[20:21], v[142:143], 0, v[20:21]
	global_store_dwordx4 v[20:21], v[12:15], off
	v_cvt_pk_bf16_f32 v4, v4, v5
	v_cvt_pk_bf16_f32 v5, v6, v7
	v_cvt_pk_bf16_f32 v12, v64, v65
	v_cvt_pk_bf16_f32 v13, v66, v67
	v_cvt_pk_bf16_f32 v14, v84, v85
	v_cvt_pk_bf16_f32 v15, v86, v87
	global_store_dwordx4 v[20:21], v[12:15], off offset:256
	v_cvt_pk_bf16_f32 v6, v16, v17
	v_cvt_pk_bf16_f32 v7, v18, v19
	v_or_b32_e32 v12, 32, v140
	v_ashrrev_i32_e32 v13, 31, v12
	v_lshlrev_b64 v[12:13], 11, v[12:13]
	v_lshl_add_u64 v[12:13], v[142:143], 0, v[12:13]
	global_store_dwordx4 v[12:13], v[4:7], off
	v_cvt_pk_bf16_f32 v0, v0, v1
	v_cvt_pk_bf16_f32 v1, v2, v3
	v_cvt_pk_bf16_f32 v4, v52, v53
	v_cvt_pk_bf16_f32 v5, v54, v55
	v_cvt_pk_bf16_f32 v6, v76, v77
	v_cvt_pk_bf16_f32 v7, v78, v79
	global_store_dwordx4 v[12:13], v[4:7], off offset:256
	v_cvt_pk_bf16_f32 v2, v8, v9
	v_cvt_pk_bf16_f32 v3, v10, v11
	v_or_b32_e32 v4, 48, v140
	v_ashrrev_i32_e32 v5, 31, v4
	v_lshlrev_b64 v[4:5], 11, v[4:5]
	v_lshl_add_u64 v[4:5], v[142:143], 0, v[4:5]
	global_store_dwordx4 v[4:5], v[0:3], off
	s_mov_b64 s[2:3], 0x40000
	s_nop 0
	v_cvt_pk_bf16_f32 v0, v40, v41
	v_cvt_pk_bf16_f32 v1, v42, v43
	v_cvt_pk_bf16_f32 v2, v60, v61
	v_cvt_pk_bf16_f32 v3, v62, v63
	global_store_dwordx4 v[4:5], v[0:3], off offset:256
	v_lshl_add_u64 v[4:5], v[144:145], 0, s[2:3]
	s_mov_b32 s2, 0x40000
	v_add_co_u32_e32 v6, vcc, s2, v144
	v_cvt_pk_bf16_f32 v0, v68, v69
	v_cvt_pk_bf16_f32 v1, v70, v71
	v_cvt_pk_bf16_f32 v2, v88, v89
; __device__ __forceinline__ u32x4 mk4(unsigned a, unsigned b, unsigned c, unsigned d) { return (u32x4){a, b, c, d}; }
; __device__ __forceinline__ f32x4 zero4() { float z = 0.f; asm volatile("" : "+v"(z)); return (f32x4){z, z, z, z}; }
; __device__ __forceinline__ void gemm_phase(const Params& p, int l, const bf16_t* __restrict__ A, const bf16_t* __restrict__ Bt, int M, int N, int K,
;                            int epi, bf16_t* __restrict__ outp, char* smem, int wvi) {
;     ...
;           bf16_t* rp = outp + (size_t)(r0 + ai * GHALF + m * 16) * N + bcol + wc * 32 + fq * 8;
; #pragma unroll
;           for (int bj = 0; bj < 2; ++bj) {
;             const f32x4 v0 = acc[ai][bj][m][0], v1 = acc[ai][bj][m][1];
;             *reinterpret_cast<u32x4*>(rp + bj * GHALF) = mk4(pk2(v0[0], v0[1]), pk2(v0[2], v0[3]), pk2(v1[0], v1[1]), pk2(v1[2], v1[3]));
;           }
;         }
;     ...
;       if (!has_next) break;
; #pragma unroll
;       for (int a = 0; a < 2; ++a)
; #pragma unroll
;         for (int b = 0; b < 2; ++b)
; #pragma unroll
;           for (int m = 0; m < 4; ++m)
; #pragma unroll
;             for (int n = 0; n < 2; ++n) acc[a][b][m][n] = zero4();
;       Lw = Ln; pm = npm; pn = npn; cA = nA; cB = nB;
	v_cvt_pk_bf16_f32 v3, v90, v91
	v_addc_co_u32_e32 v7, vcc, 0, v145, vcc
	global_store_dwordx4 v[6:7], v[0:3], off
	s_mov_b64 s[2:3], 0x48000
	s_nop 0
	v_cvt_pk_bf16_f32 v0, v120, v121
	v_cvt_pk_bf16_f32 v1, v122, v123
	v_cvt_pk_bf16_f32 v2, v124, v125
	v_cvt_pk_bf16_f32 v3, v126, v127
	global_store_dwordx4 v[4:5], v[0:3], off offset:256
	v_lshl_add_u64 v[4:5], v[144:145], 0, s[2:3]
	s_mov_b32 s2, 0x48000
	v_add_co_u32_e32 v6, vcc, s2, v144
	v_cvt_pk_bf16_f32 v0, v48, v49
	v_cvt_pk_bf16_f32 v1, v50, v51
	v_cvt_pk_bf16_f32 v2, v72, v73
	v_cvt_pk_bf16_f32 v3, v74, v75
	v_addc_co_u32_e32 v7, vcc, 0, v145, vcc
	global_store_dwordx4 v[6:7], v[0:3], off
	s_mov_b64 s[2:3], 0x50000
	s_nop 0
	v_cvt_pk_bf16_f32 v0, v112, v113
	v_cvt_pk_bf16_f32 v1, v114, v115
	v_cvt_pk_bf16_f32 v2, v116, v117
	v_cvt_pk_bf16_f32 v3, v118, v119
	global_store_dwordx4 v[4:5], v[0:3], off offset:256
	v_lshl_add_u64 v[4:5], v[144:145], 0, s[2:3]
	s_mov_b32 s2, 0x50000
	v_add_co_u32_e32 v6, vcc, s2, v144
	v_cvt_pk_bf16_f32 v0, v36, v37
	v_cvt_pk_bf16_f32 v1, v38, v39
	v_cvt_pk_bf16_f32 v2, v56, v57
	v_cvt_pk_bf16_f32 v3, v58, v59
	v_addc_co_u32_e32 v7, vcc, 0, v145, vcc
	global_store_dwordx4 v[6:7], v[0:3], off
	s_mov_b64 s[2:3], 0x58000
	s_nop 0
	v_cvt_pk_bf16_f32 v0, v104, v105
	v_cvt_pk_bf16_f32 v1, v106, v107
	v_cvt_pk_bf16_f32 v2, v108, v109
	v_cvt_pk_bf16_f32 v3, v110, v111
	global_store_dwordx4 v[4:5], v[0:3], off offset:256
	v_lshl_add_u64 v[4:5], v[144:145], 0, s[2:3]
	s_mov_b32 s2, 0x58000
	v_add_co_u32_e32 v6, vcc, s2, v144
	v_cvt_pk_bf16_f32 v0, v32, v33
	v_cvt_pk_bf16_f32 v1, v34, v35
	v_cvt_pk_bf16_f32 v2, v44, v45
	v_cvt_pk_bf16_f32 v3, v46, v47
	v_addc_co_u32_e32 v7, vcc, 0, v145, vcc
	global_store_dwordx4 v[6:7], v[0:3], off
	s_mov_b64 s[2:3], -1
	s_and_b64 vcc, exec, s[8:9]
	v_cvt_pk_bf16_f32 v0, v96, v97
	v_cvt_pk_bf16_f32 v1, v98, v99
	v_cvt_pk_bf16_f32 v2, v100, v101
	v_cvt_pk_bf16_f32 v3, v102, v103
	global_store_dwordx4 v[4:5], v[0:3], off offset:256
	s_cbranch_vccz .LBB0_1035
	v_mov_b32_e32 v20, v177
	v_mov_b32_e32 v28, v177
	v_mov_b32_e32 v12, v177
	v_mov_b32_e32 v24, v177
	v_mov_b32_e32 v4, v177
	v_mov_b32_e32 v16, v177
	v_mov_b32_e32 v0, v177
	v_mov_b32_e32 v8, v177
	v_mov_b32_e32 v80, v177
	v_mov_b32_e32 v92, v177
	v_mov_b32_e32 v64, v177
	v_mov_b32_e32 v84, v177
	v_mov_b32_e32 v52, v177
	v_mov_b32_e32 v76, v177
	v_mov_b32_e32 v40, v177
	v_mov_b32_e32 v60, v177
	v_mov_b32_e32 v68, v177
	v_mov_b32_e32 v88, v177
	v_mov_b32_e32 v48, v177
	v_mov_b32_e32 v72, v177
	v_mov_b32_e32 v36, v177
	v_mov_b32_e32 v56, v177
	v_mov_b32_e32 v32, v177
	v_mov_b32_e32 v44, v177
	v_mov_b32_e32 v120, v177
	v_mov_b32_e32 v124, v177
	v_mov_b32_e32 v112, v177
	v_mov_b32_e32 v116, v177
	v_mov_b32_e32 v104, v177
	v_mov_b32_e32 v108, v177
	v_mov_b32_e32 v96, v177
	v_mov_b32_e32 v100, v177
	s_nop 0
	v_mov_b32_e32 v21, v20
	v_mov_b32_e32 v22, v20
	v_mov_b32_e32 v23, v20
	v_mov_b32_e32 v29, v28
	v_mov_b32_e32 v30, v28
	v_mov_b32_e32 v31, v28
	v_mov_b32_e32 v13, v12
	v_mov_b32_e32 v14, v12
	v_mov_b32_e32 v15, v12
	v_mov_b32_e32 v25, v24
	v_mov_b32_e32 v26, v24
	v_mov_b32_e32 v27, v24
	v_mov_b32_e32 v5, v4
	v_mov_b32_e32 v6, v4
	v_mov_b32_e32 v7, v4
	v_mov_b32_e32 v17, v16
	v_mov_b32_e32 v18, v16
	v_mov_b32_e32 v19, v16
	s_nop 0
	v_mov_b32_e32 v1, v0
	v_mov_b32_e32 v2, v0
	v_mov_b32_e32 v3, v0
	v_mov_b32_e32 v9, v8
	v_mov_b32_e32 v10, v8
	v_mov_b32_e32 v11, v8
	v_mov_b32_e32 v81, v80
	v_mov_b32_e32 v82, v80
	v_mov_b32_e32 v83, v80
	v_mov_b32_e32 v93, v92
	v_mov_b32_e32 v94, v92
	v_mov_b32_e32 v95, v92
	v_mov_b32_e32 v65, v64
	v_mov_b32_e32 v66, v64
	v_mov_b32_e32 v67, v64
	v_mov_b32_e32 v85, v84
	v_mov_b32_e32 v86, v84
	v_mov_b32_e32 v87, v84
	s_nop 0
	v_mov_b32_e32 v53, v52
	v_mov_b32_e32 v54, v52
	v_mov_b32_e32 v55, v52
	v_mov_b32_e32 v77, v76
	v_mov_b32_e32 v78, v76
	v_mov_b32_e32 v79, v76
	v_mov_b32_e32 v41, v40
	v_mov_b32_e32 v42, v40
	v_mov_b32_e32 v43, v40
	v_mov_b32_e32 v61, v60
	v_mov_b32_e32 v62, v60
	v_mov_b32_e32 v63, v60
	v_mov_b32_e32 v69, v68
	v_mov_b32_e32 v70, v68
	v_mov_b32_e32 v71, v68
	v_mov_b32_e32 v89, v88
	v_mov_b32_e32 v90, v88
	v_mov_b32_e32 v91, v88
	s_nop 0
	v_mov_b32_e32 v49, v48
	v_mov_b32_e32 v50, v48
	v_mov_b32_e32 v51, v48
	v_mov_b32_e32 v73, v72
	v_mov_b32_e32 v74, v72
	v_mov_b32_e32 v75, v72
	v_mov_b32_e32 v37, v36
	v_mov_b32_e32 v38, v36
	v_mov_b32_e32 v39, v36
	v_mov_b32_e32 v57, v56
	v_mov_b32_e32 v58, v56
	v_mov_b32_e32 v59, v56
	v_mov_b32_e32 v33, v32
	v_mov_b32_e32 v34, v32
	v_mov_b32_e32 v35, v32
	v_mov_b32_e32 v45, v44
	v_mov_b32_e32 v46, v44
	v_mov_b32_e32 v47, v44
	s_nop 0
	v_mov_b32_e32 v121, v120
	v_mov_b32_e32 v122, v120
	v_mov_b32_e32 v123, v120
	v_mov_b32_e32 v125, v124
	v_mov_b32_e32 v126, v124
	v_mov_b32_e32 v127, v124
	v_mov_b32_e32 v113, v112
	v_mov_b32_e32 v114, v112
	v_mov_b32_e32 v115, v112
	v_mov_b32_e32 v117, v116
	v_mov_b32_e32 v118, v116
	v_mov_b32_e32 v119, v116
	v_mov_b32_e32 v105, v104
	v_mov_b32_e32 v106, v104
	v_mov_b32_e32 v107, v104
	v_mov_b32_e32 v109, v108
	v_mov_b32_e32 v110, v108
	v_mov_b32_e32 v111, v108
	s_mov_b64 s[2:3], 0
	v_mov_b32_e32 v97, v96
	v_mov_b32_e32 v98, v96
	v_mov_b32_e32 v99, v96
	v_mov_b32_e32 v101, v100
	v_mov_b32_e32 v102, v100
	v_mov_b32_e32 v103, v100
	s_branch .LBB0_1035

; __device__ __forceinline__ f32x4 zero4() { float z = 0.f; asm volatile("" : "+v"(z)); return (f32x4){z, z, z, z}; }
; #define G_STAGE(bufoff, gbase) do { _Pragma("unroll") for (int _i = 0; _i < 2; ++_i) \
;     __builtin_amdgcn_global_load_lds((const unsigned*)((const char*)(gbase) + voff[_i]), (GLAS unsigned*)(lds + (bufoff) + ldsw + _i * 8192), 16, 0, 0); } while (0)
; __device__ __forceinline__ void gemm_phase(const Params& p, int l, const bf16_t* __restrict__ A, const bf16_t* __restrict__ Bt, int M, int N, int K,
;                            int epi, bf16_t* __restrict__ outp, char* smem, int wvi) {
;     ...
;   const int wid = wvi; int tidx = wvi * 64 + lane_id(); asm volatile("" : "+v"(tidx));
;   const int lane = tidx & 63, wr = wid >> 2, wc = wid & 3, fr = lane & 15, fq = lane >> 4;
;   const int nt = K / GBK;
;   unsigned voff[2];
; #pragma unroll
;   for (int i = 0; i < 2; ++i) { int R, C; stage_rc(tidx * 16 + i * 8192, R, C); voff[i] = (unsigned)(R * K + C) * 2u; }
;   const size_t kstep = (size_t)(GBK * 2), hstep = (size_t)GHALF * K * 2, tstep = 2 * hstep;
;   const unsigned ldsw = (unsigned)wid * 1024u;
;   const int aoff = lds_byte(wr * 64 + fr, fq * 8), boff = lds_byte(wc * 32 + fr, fq * 8);
;   constexpr int HTB = GHT * 2;
;     ...
;   const int nM = M / GBM, nN = N / GBM, nwg = nM * nN;
;   auto tile_of = [&](int Lw, int& pm_, int& pn_) {
;     int wgid = Lw;
;     { const int q = nwg / GNXCD, r = nwg % GNXCD, xcd = wgid % GNXCD, off = wgid / GNXCD; wgid = (xcd < r ? xcd * (q + 1) : r * (q + 1) + (xcd - r) * q) + off; }
;     const int nig = GWGM * nN, gid = wgid / nig, fm = gid * GWGM, gsz = min(nM - fm, GWGM);
;     pm_ = fm + ((wgid % nig) % gsz); pn_ = (wgid % nig) / gsz;
;   };
;   int Lw = blockIdx.x;
;   if (Lw < nwg) {
;     int pm, pn; tile_of(Lw, pm, pn);
;     const char* cA = (const char*)A + (size_t)pm * tstep;
;     const char* cB = (const char*)Bt + (size_t)pn * tstep;
;     f32x4 acc[2][2][4][2];
; #pragma unroll
;     for (int a = 0; a < 2; ++a)
; #pragma unroll
;       for (int b = 0; b < 2; ++b)
; #pragma unroll
;         for (int m = 0; m < 4; ++m)
; #pragma unroll
;           for (int n = 0; n < 2; ++n) acc[a][b][m][n] = zero4();
;     bf16x8 At[4][2], B0[2][2], B1[2][2];
;     G_STAGE(G_SB(0, 0), cB); G_STAGE(G_SA(0, 0), cA); G_STAGE(G_SB(0, 1), cB + hstep); G_STAGE(G_SA(0, 1), cA + hstep);
;     if (wr == 1) G_BAR;
.LBB0_1189:
	s_andn2_b64 vcc, exec, s[2:3]
	s_cbranch_vccnz .LBB0_1246
	s_cmp_lg_u32 s55, 0
	s_cbranch_scc1 .LBB0_1246
	v_readlane_b32 s0, v248, 9
	s_waitcnt vmcnt(1)
	v_mbcnt_lo_u32_b32 v0, -1, 0
	v_mbcnt_hi_u32_b32 v0, -1, v0
	s_nop 0
	v_add_u32_e32 v130, s0, v0
	v_readlane_b32 s0, v247, 7
	v_readlane_b32 s1, v247, 8
	s_andn2_b64 vcc, exec, s[0:1]
	s_cbranch_vccnz .LBB0_1205
	v_lshlrev_b32_e32 v0, 4, v130
	v_add_u32_e32 v1, 0x2000, v0
	v_ashrrev_i32_e32 v2, 31, v1
	v_lshrrev_b32_e32 v2, 22, v2
	v_add_u32_e32 v2, v1, v2
	v_ashrrev_i32_e32 v134, 10, v2
	v_mul_i32_i24_e32 v2, 0x400, v134
	v_sub_u32_e32 v1, v1, v2
	v_lshrrev_b32_e32 v2, 4, v1
	v_bitop3_b32 v1, v2, v1, 32 bitop3:0x6c
	v_ashrrev_i32_e32 v2, 31, v1
	v_lshrrev_b32_e32 v2, 26, v2
	v_add_u32_e32 v2, v1, v2
	v_ashrrev_i32_e32 v135, 6, v2
	v_and_b32_e32 v2, 0xc0, v2
	v_sub_u32_e32 v1, v1, v2
	v_ashrrev_i16_sdwa v1, v199, sext(v1) dst_sel:DWORD dst_unused:UNUSED_PAD src0_sel:DWORD src1_sel:BYTE_0
	v_bfe_i32 v137, v1, 0, 16
	v_bfe_i32 v1, v130, 27, 1
	v_lshrrev_b32_e32 v1, 22, v1
	v_add_u32_e32 v1, v0, v1
	v_and_b32_e32 v1, 0xfffffc00, v1
	v_sub_u32_e32 v0, v0, v1
	v_lshrrev_b32_e32 v1, 4, v0
	v_bitop3_b32 v0, v1, v0, 32 bitop3:0x6c
	v_ashrrev_i32_e32 v2, 31, v130
	v_lshlrev_b32_e32 v3, 3, v134
	v_ashrrev_i32_e32 v1, 31, v0
	v_lshrrev_b32_e32 v2, 26, v2
	v_and_b32_e32 v3, 0x1ffff0, v3
	s_waitcnt vmcnt(0)
	v_lshlrev_b32_e32 v4, 5, v134
	v_lshrrev_b32_e32 v1, 26, v1
	v_add_u32_e32 v2, v130, v2
	v_add_u32_e32 v3, v135, v3
	v_and_b32_e32 v136, 32, v4
	v_add_u32_e32 v1, v0, v1
	v_ashrrev_i32_e32 v133, 6, v2
	v_lshl_or_b32 v3, v3, 10, v136
	v_ashrrev_i32_e32 v132, 6, v1
	v_lshlrev_b32_e32 v2, 3, v133
	v_and_b32_e32 v1, 0xc0, v1
	v_add_lshl_u32 v128, v3, v137, 1
	v_and_b32_e32 v2, 0x1ffff0, v2
	v_lshlrev_b32_e32 v3, 5, v133
	v_sub_u32_e32 v0, v0, v1
	v_add_u32_e32 v2, v132, v2
	v_and_b32_e32 v140, 32, v3
	v_ashrrev_i16_sdwa v0, v199, sext(v0) dst_sel:DWORD dst_unused:UNUSED_PAD src0_sel:DWORD src1_sel:BYTE_0
	v_lshl_or_b32 v2, v2, 10, v140
	v_bfe_i32 v141, v0, 0, 16
	s_add_i32 s30, s58, 0
	v_readlane_b32 s0, v247, 21
	v_add_lshl_u32 v176, v2, v141, 1
	v_mov_b32_e32 v120, v177
	v_mov_b32_e32 v124, v177
	v_mov_b32_e32 v104, v177
	v_mov_b32_e32 v108, v177
	v_mov_b32_e32 v88, v177
	v_mov_b32_e32 v92, v177
	v_mov_b32_e32 v72, v177
	v_mov_b32_e32 v76, v177
	v_mov_b32_e32 v112, v177
	v_mov_b32_e32 v116, v177
	v_mov_b32_e32 v96, v177
	v_mov_b32_e32 v100, v177
	v_mov_b32_e32 v80, v177
	v_mov_b32_e32 v84, v177
	v_mov_b32_e32 v64, v177
	v_mov_b32_e32 v68, v177
	v_mov_b32_e32 v56, v177
	v_mov_b32_e32 v60, v177
	v_mov_b32_e32 v40, v177
	v_mov_b32_e32 v44, v177
	v_mov_b32_e32 v24, v177
	v_mov_b32_e32 v28, v177
	v_mov_b32_e32 v8, v177
	v_mov_b32_e32 v12, v177
	v_mov_b32_e32 v48, v177
	v_mov_b32_e32 v52, v177
	v_mov_b32_e32 v32, v177
	v_mov_b32_e32 v36, v177
	v_mov_b32_e32 v16, v177
	v_mov_b32_e32 v20, v177
	v_mov_b32_e32 v0, v177
	v_mov_b32_e32 v4, v177
	s_add_i32 m0, s30, 0x10000
	v_readlane_b32 s1, v247, 22
	s_nop 4
	global_load_lds_dwordx4 v176, s[0:1]
	s_add_i32 m0, s30, 0x12000
	s_add_i32 s31, s30, 0x2000
	global_load_lds_dwordx4 v128, s[0:1]
	v_readlane_b32 s0, v247, 17
	s_mov_b32 m0, s30
	v_readlane_b32 s1, v247, 18
	s_add_i32 s55, s30, 0x4000
	s_add_i32 s88, s30, 0x6000
	s_nop 2
	global_load_lds_dwordx4 v176, s[0:1]
	s_mov_b32 m0, s31
	s_nop 0
	global_load_lds_dwordx4 v128, s[0:1]
	v_readlane_b32 s0, v247, 15
	s_add_i32 m0, s30, 0x14000
	v_readlane_b32 s1, v247, 16
	s_nop 4
	global_load_lds_dwordx4 v176, s[0:1]
	s_add_i32 m0, s30, 0x16000
	s_nop 0
	global_load_lds_dwordx4 v128, s[0:1]
	v_readlane_b32 s0, v247, 19
	s_mov_b32 m0, s55
	v_readlane_b32 s1, v247, 20
	s_nop 4
	global_load_lds_dwordx4 v176, s[0:1]
	s_mov_b32 m0, s88
	s_nop 0
	global_load_lds_dwordx4 v128, s[0:1]
	v_readlane_b32 s0, v248, 13
	v_readlane_b32 s1, v248, 14
	s_andn2_b64 vcc, exec, s[0:1]
	s_cbranch_vccnz .LBB0_1194
	s_barrier
	s_setprio 1

; #define G_STAGE(bufoff, gbase) do { _Pragma("unroll") for (int _i = 0; _i < 2; ++_i) \
;     __builtin_amdgcn_global_load_lds((const unsigned*)((const char*)(gbase) + voff[_i]), (GLAS unsigned*)(lds + (bufoff) + ldsw + _i * 8192), 16, 0, 0); } while (0)
; #define G_LDA(dst, b, h) do { _Pragma("unroll") for (int m = 0; m < 4; ++m) _Pragma("unroll") for (int k = 0; k < 2; ++k) \
;     dst[m][k] = *(const GLAS bf16x8*)(lds + G_SA(b, h) + aoff + m * 2048 + k * 1024); } while (0)
; #define G_LDB(dst, b, h) do { _Pragma("unroll") for (int n = 0; n < 2; ++n) _Pragma("unroll") for (int k = 0; k < 2; ++k) \
;     dst[n][k] = *(const GLAS bf16x8*)(lds + G_SB(b, h) + boff + n * 2048 + k * 1024); } while (0)
; #define G_MMA(ai, bj, At_, Bt_) do { __builtin_amdgcn_s_setprio(1); \
;     _Pragma("unroll") for (int m = 0; m < 4; ++m) _Pragma("unroll") for (int n = 0; n < 2; ++n) _Pragma("unroll") for (int k = 0; k < 2; ++k) \
;       acc[ai][bj][m][n] = __builtin_amdgcn_mfma_f32_16x16x32_bf16(Bt_[n][k], At_[m][k], acc[ai][bj][m][n], 0, 0, 0); \
;     __builtin_amdgcn_s_setprio(0); } while (0)
; #define G_WAIT_V(n) asm volatile("s_waitcnt vmcnt(" #n ")" ::: "memory")
; #define G_WAIT_L(n) asm volatile("s_waitcnt lgkmcnt(" #n ")" ::: "memory")
; #define G_BAR __builtin_amdgcn_s_barrier()
; __device__ __forceinline__ void gemm_phase(const Params& p, int l, const bf16_t* __restrict__ A, const bf16_t* __restrict__ Bt, int M, int N, int K,
;                            int epi, bf16_t* __restrict__ outp, char* smem, int wvi) {
;     ...
;       for (int t = 0; t < nt; t += 2) {
;         const bool lastt = (t == nt - 2);
;         const char* a1 = cA + (size_t)(t + 1) * kstep;
;         const char* a2 = lastt ? nA : cA + (size_t)(t + 2) * kstep; const char* b2 = lastt ? nB : cB + (size_t)(t + 2) * kstep;
;         const char* a3 = a2 + kstep; const char* b3 = b2 + kstep;
;         G_LDB(B0, 0, 0); G_SCHED; G_LDA(At, 0, 0); G_STAGE(G_SA(1, 1), a1 + hstep);
;         G_WAIT_L(8); G_BAR; G_WAIT_L(0); G_MMA(0, 0, At, B0); G_BAR; G_SCHED;
;         G_LDB(B1, 0, 1); G_STAGE(G_SB(0, 0), b2);
;         G_BAR; G_WAIT_L(0); G_MMA(0, 1, At, B1); G_BAR;
;         G_LDA(At, 0, 1); G_STAGE(G_SA(0, 0), a2);
;         G_BAR; G_WAIT_L(0); G_MMA(1, 0, At, B0); G_BAR; G_SCHED;
;         G_STAGE(G_SB(0, 1), b2 + hstep);
;         G_WAIT_V(6); G_BAR; G_MMA(1, 1, At, B1); G_BAR;
.LBB0_1199:
	s_add_u32 s2, s16, 0x100
	s_addc_u32 s3, s17, 0
	s_add_i32 s24, 0, 0x10000
	v_add_u32_e32 v136, s24, v139
	ds_read_b128 v[142:145], v136
	ds_read_b128 v[146:149], v136 offset:1024
	ds_read_b128 v[150:153], v136 offset:2048
	ds_read_b128 v[154:157], v136 offset:3072
	s_cmp_eq_u32 s23, 12
	s_cselect_b32 s29, s9, s3
	s_cselect_b32 s28, s8, s2
	s_cselect_b32 s15, s7, s22
	s_cselect_b32 s14, s5, s21
	v_lshl_add_u64 v[136:137], s[16:17], 0, v[132:133]
	s_add_i32 m0, s30, 0xc000
	ds_read_b128 v[158:161], v140
	ds_read_b128 v[162:165], v140 offset:1024
	ds_read_b128 v[166:169], v140 offset:2048
	ds_read_b128 v[170:173], v140 offset:3072
	ds_read_b128 v[182:185], v140 offset:4096
	ds_read_b128 v[186:189], v140 offset:5120
	ds_read_b128 v[214:217], v140 offset:6144
	ds_read_b128 v[218:221], v140 offset:7168
	global_load_lds_dwordx4 v[136:137], off
	v_lshl_add_u64 v[136:137], s[16:17], 0, v[134:135]
	s_add_i32 m0, s30, 0xe000
	s_nop 0
	global_load_lds_dwordx4 v[136:137], off
	s_waitcnt lgkmcnt(8)
	s_barrier
	s_waitcnt lgkmcnt(0)
	s_waitcnt lgkmcnt(0)
	v_mfma_f32_16x16x32_bf16 v[120:123], v[142:145], v[158:161], v[120:123]
	v_mfma_f32_16x16x32_bf16 v[124:127], v[150:153], v[158:161], v[124:127]
	v_mfma_f32_16x16x32_bf16 v[104:107], v[142:145], v[166:169], v[104:107]
	v_mfma_f32_16x16x32_bf16 v[108:111], v[150:153], v[166:169], v[108:111]
	v_mfma_f32_16x16x32_bf16 v[88:91], v[142:145], v[182:185], v[88:91]
	v_mfma_f32_16x16x32_bf16 v[92:95], v[150:153], v[182:185], v[92:95]
	v_mfma_f32_16x16x32_bf16 v[72:75], v[142:145], v[214:217], v[72:75]
	v_mfma_f32_16x16x32_bf16 v[76:79], v[150:153], v[214:217], v[76:79]
	v_mfma_f32_16x16x32_bf16 v[120:123], v[146:149], v[162:165], v[120:123]
	v_mfma_f32_16x16x32_bf16 v[124:127], v[154:157], v[162:165], v[124:127]
	v_mfma_f32_16x16x32_bf16 v[104:107], v[146:149], v[170:173], v[104:107]
	v_mfma_f32_16x16x32_bf16 v[108:111], v[154:157], v[170:173], v[108:111]
	v_mfma_f32_16x16x32_bf16 v[88:91], v[146:149], v[186:189], v[88:91]
	v_mfma_f32_16x16x32_bf16 v[92:95], v[154:157], v[186:189], v[92:95]
	v_mfma_f32_16x16x32_bf16 v[72:75], v[146:149], v[218:221], v[72:75]
	v_mfma_f32_16x16x32_bf16 v[76:79], v[154:157], v[218:221], v[76:79]
	s_barrier
	s_add_i32 s25, 0, 0x14000
	v_add_u32_e32 v136, s25, v139
	s_add_i32 s16, s24, s58
	ds_read_b128 v[222:225], v136
	ds_read_b128 v[226:229], v136 offset:1024
	ds_read_b128 v[230:233], v136 offset:2048
	ds_read_b128 v[234:237], v136 offset:3072
	v_lshl_add_u64 v[136:137], s[14:15], 0, v[176:177]
	s_mov_b32 m0, s16
	v_lshl_add_u64 v[174:175], s[14:15], 0, v[128:129]
	global_load_lds_dwordx4 v[136:137], off
	s_add_i32 m0, s16, 0x2000
	s_nop 0
	global_load_lds_dwordx4 v[174:175], off
	s_barrier
	s_waitcnt lgkmcnt(0)
	s_waitcnt lgkmcnt(0)
	v_mfma_f32_16x16x32_bf16 v[112:115], v[222:225], v[158:161], v[112:115]
	v_mfma_f32_16x16x32_bf16 v[116:119], v[230:233], v[158:161], v[116:119]
	v_mfma_f32_16x16x32_bf16 v[96:99], v[222:225], v[166:169], v[96:99]
	v_mfma_f32_16x16x32_bf16 v[100:103], v[230:233], v[166:169], v[100:103]
	v_mfma_f32_16x16x32_bf16 v[80:83], v[222:225], v[182:185], v[80:83]
	v_mfma_f32_16x16x32_bf16 v[84:87], v[230:233], v[182:185], v[84:87]
	v_mfma_f32_16x16x32_bf16 v[64:67], v[222:225], v[214:217], v[64:67]
	v_mfma_f32_16x16x32_bf16 v[68:71], v[230:233], v[214:217], v[68:71]
	v_mfma_f32_16x16x32_bf16 v[112:115], v[226:229], v[162:165], v[112:115]
	v_mfma_f32_16x16x32_bf16 v[116:119], v[234:237], v[162:165], v[116:119]
	v_mfma_f32_16x16x32_bf16 v[96:99], v[226:229], v[170:173], v[96:99]
	v_mfma_f32_16x16x32_bf16 v[100:103], v[234:237], v[170:173], v[100:103]
	v_mfma_f32_16x16x32_bf16 v[80:83], v[226:229], v[186:189], v[80:83]
	v_mfma_f32_16x16x32_bf16 v[84:87], v[234:237], v[186:189], v[84:87]
	v_mfma_f32_16x16x32_bf16 v[64:67], v[226:229], v[218:221], v[64:67]
	v_mfma_f32_16x16x32_bf16 v[68:71], v[234:237], v[218:221], v[68:71]
	s_mov_b32 m0, s30
	v_lshl_add_u64 v[190:191], s[28:29], 0, v[176:177]
	s_barrier
	ds_read_b128 v[158:161], v140 offset:16384
	ds_read_b128 v[162:165], v140 offset:17408
	ds_read_b128 v[166:169], v140 offset:18432
	ds_read_b128 v[170:173], v140 offset:19456
	ds_read_b128 v[182:185], v140 offset:20480
	ds_read_b128 v[186:189], v140 offset:21504
	ds_read_b128 v[214:217], v140 offset:22528
	ds_read_b128 v[218:221], v140 offset:23552
	global_load_lds_dwordx4 v[190:191], off
	v_lshl_add_u64 v[238:239], s[28:29], 0, v[128:129]
	s_mov_b32 m0, s31
	s_nop 0
	global_load_lds_dwordx4 v[238:239], off
	s_barrier
	s_waitcnt lgkmcnt(0)
	s_waitcnt lgkmcnt(0)
	v_mfma_f32_16x16x32_bf16 v[56:59], v[142:145], v[158:161], v[56:59]
	v_mfma_f32_16x16x32_bf16 v[60:63], v[150:153], v[158:161], v[60:63]
	v_mfma_f32_16x16x32_bf16 v[40:43], v[142:145], v[166:169], v[40:43]
	v_mfma_f32_16x16x32_bf16 v[44:47], v[150:153], v[166:169], v[44:47]
	v_mfma_f32_16x16x32_bf16 v[24:27], v[142:145], v[182:185], v[24:27]
	v_mfma_f32_16x16x32_bf16 v[28:31], v[150:153], v[182:185], v[28:31]
	v_mfma_f32_16x16x32_bf16 v[8:11], v[142:145], v[214:217], v[8:11]
	v_mfma_f32_16x16x32_bf16 v[12:15], v[150:153], v[214:217], v[12:15]
	v_mfma_f32_16x16x32_bf16 v[56:59], v[146:149], v[162:165], v[56:59]
	v_mfma_f32_16x16x32_bf16 v[60:63], v[154:157], v[162:165], v[60:63]
	v_mfma_f32_16x16x32_bf16 v[40:43], v[146:149], v[170:173], v[40:43]
	v_mfma_f32_16x16x32_bf16 v[44:47], v[154:157], v[170:173], v[44:47]
	v_mfma_f32_16x16x32_bf16 v[24:27], v[146:149], v[186:189], v[24:27]
	v_mfma_f32_16x16x32_bf16 v[28:31], v[154:157], v[186:189], v[28:31]
	v_mfma_f32_16x16x32_bf16 v[8:11], v[146:149], v[218:221], v[8:11]
	v_mfma_f32_16x16x32_bf16 v[12:15], v[154:157], v[218:221], v[12:15]
	s_barrier
; #define G_STAGE(bufoff, gbase) do { _Pragma("unroll") for (int _i = 0; _i < 2; ++_i) \
;     __builtin_amdgcn_global_load_lds((const unsigned*)((const char*)(gbase) + voff[_i]), (GLAS unsigned*)(lds + (bufoff) + ldsw + _i * 8192), 16, 0, 0); } while (0)
; #define G_LDA(dst, b, h) do { _Pragma("unroll") for (int m = 0; m < 4; ++m) _Pragma("unroll") for (int k = 0; k < 2; ++k) \
;     dst[m][k] = *(const GLAS bf16x8*)(lds + G_SA(b, h) + aoff + m * 2048 + k * 1024); } while (0)
; #define G_LDB(dst, b, h) do { _Pragma("unroll") for (int n = 0; n < 2; ++n) _Pragma("unroll") for (int k = 0; k < 2; ++k) \
;     dst[n][k] = *(const GLAS bf16x8*)(lds + G_SB(b, h) + boff + n * 2048 + k * 1024); } while (0)
; #define G_MMA(ai, bj, At_, Bt_) do { __builtin_amdgcn_s_setprio(1); \
;     _Pragma("unroll") for (int m = 0; m < 4; ++m) _Pragma("unroll") for (int n = 0; n < 2; ++n) _Pragma("unroll") for (int k = 0; k < 2; ++k) \
;       acc[ai][bj][m][n] = __builtin_amdgcn_mfma_f32_16x16x32_bf16(Bt_[n][k], At_[m][k], acc[ai][bj][m][n], 0, 0, 0); \
;     __builtin_amdgcn_s_setprio(0); } while (0)
; #define G_WAIT_V(n) asm volatile("s_waitcnt vmcnt(" #n ")" ::: "memory")
; #define G_WAIT_L(n) asm volatile("s_waitcnt lgkmcnt(" #n ")" ::: "memory")
; #define G_BAR __builtin_amdgcn_s_barrier()
; #define G_SCHED __builtin_amdgcn_sched_barrier(0)
; __device__ __forceinline__ void gemm_phase(const Params& p, int l, const bf16_t* __restrict__ A, const bf16_t* __restrict__ Bt, int M, int N, int K,
;                            int epi, bf16_t* __restrict__ outp, char* smem, int wvi) {
;     ...
;         G_WAIT_V(6); G_BAR; G_MMA(1, 1, At, B1); G_BAR;
;         G_LDB(B0, 1, 0); G_SCHED; G_LDA(At, 1, 0); G_STAGE(G_SA(0, 1), a2 + hstep);
;         G_WAIT_L(8); G_BAR; G_WAIT_L(0); G_MMA(0, 0, At, B0); G_BAR; G_SCHED;
;         G_LDB(B1, 1, 1); G_STAGE(G_SB(1, 0), b3);
;         G_BAR; G_WAIT_L(0); G_MMA(0, 1, At, B1); G_BAR;
;         G_LDA(At, 1, 1); G_STAGE(G_SA(1, 0), a3);
;         G_BAR; G_WAIT_L(0); G_MMA(1, 0, At, B0); G_BAR; G_SCHED;
	s_add_u32 s16, s14, 0x40000
	s_addc_u32 s17, s15, 0
	s_add_i32 s24, s25, s58
	v_lshl_add_u64 v[142:143], s[16:17], 0, v[176:177]
	s_mov_b32 m0, s24
	s_nop 0
	global_load_lds_dwordx4 v[142:143], off
	v_lshl_add_u64 v[142:143], s[16:17], 0, v[128:129]
	s_add_i32 m0, s24, 0x2000
	s_nop 0
	global_load_lds_dwordx4 v[142:143], off
	s_waitcnt vmcnt(6)
	s_barrier
	v_mfma_f32_16x16x32_bf16 v[48:51], v[222:225], v[158:161], v[48:51]
	v_mfma_f32_16x16x32_bf16 v[52:55], v[230:233], v[158:161], v[52:55]
	v_mfma_f32_16x16x32_bf16 v[32:35], v[222:225], v[166:169], v[32:35]
	v_mfma_f32_16x16x32_bf16 v[36:39], v[230:233], v[166:169], v[36:39]
	v_mfma_f32_16x16x32_bf16 v[16:19], v[222:225], v[182:185], v[16:19]
	v_mfma_f32_16x16x32_bf16 v[20:23], v[230:233], v[182:185], v[20:23]
	v_mfma_f32_16x16x32_bf16 v[0:3], v[222:225], v[214:217], v[0:3]
	v_mfma_f32_16x16x32_bf16 v[4:7], v[230:233], v[214:217], v[4:7]
	v_mfma_f32_16x16x32_bf16 v[48:51], v[226:229], v[162:165], v[48:51]
	v_mfma_f32_16x16x32_bf16 v[52:55], v[234:237], v[162:165], v[52:55]
	v_mfma_f32_16x16x32_bf16 v[32:35], v[226:229], v[170:173], v[32:35]
	v_mfma_f32_16x16x32_bf16 v[36:39], v[234:237], v[170:173], v[36:39]
	v_mfma_f32_16x16x32_bf16 v[16:19], v[226:229], v[186:189], v[16:19]
	v_mfma_f32_16x16x32_bf16 v[20:23], v[234:237], v[186:189], v[20:23]
	v_mfma_f32_16x16x32_bf16 v[0:3], v[226:229], v[218:221], v[0:3]
	v_mfma_f32_16x16x32_bf16 v[4:7], v[234:237], v[218:221], v[4:7]
	s_add_i32 s24, 0, 0x18000
	v_add_u32_e32 v141, s24, v139
	s_barrier
	ds_read_b128 v[142:145], v141
	ds_read_b128 v[146:149], v141 offset:1024
	ds_read_b128 v[150:153], v141 offset:2048
	ds_read_b128 v[154:157], v141 offset:3072
	s_add_u32 s16, s28, 0x40000
	s_addc_u32 s17, s29, 0
	s_mov_b32 m0, s55
	v_lshl_add_u64 v[222:223], s[16:17], 0, v[176:177]
	ds_read_b128 v[158:161], v140 offset:32768
	ds_read_b128 v[162:165], v140 offset:33792
	ds_read_b128 v[166:169], v140 offset:34816
	ds_read_b128 v[170:173], v140 offset:35840
	ds_read_b128 v[182:185], v140 offset:36864
	ds_read_b128 v[186:189], v140 offset:37888
	ds_read_b128 v[214:217], v140 offset:38912
	ds_read_b128 v[218:221], v140 offset:39936
	global_load_lds_dwordx4 v[222:223], off
	v_lshl_add_u64 v[222:223], s[16:17], 0, v[128:129]
	s_mov_b32 m0, s88
	s_nop 0
	global_load_lds_dwordx4 v[222:223], off
	s_waitcnt lgkmcnt(8)
	s_barrier
	s_waitcnt lgkmcnt(0)
	s_waitcnt lgkmcnt(0)
	v_mfma_f32_16x16x32_bf16 v[120:123], v[142:145], v[158:161], v[120:123]
	v_mfma_f32_16x16x32_bf16 v[124:127], v[150:153], v[158:161], v[124:127]
	v_mfma_f32_16x16x32_bf16 v[104:107], v[142:145], v[166:169], v[104:107]
	v_mfma_f32_16x16x32_bf16 v[108:111], v[150:153], v[166:169], v[108:111]
	v_mfma_f32_16x16x32_bf16 v[88:91], v[142:145], v[182:185], v[88:91]
	v_mfma_f32_16x16x32_bf16 v[92:95], v[150:153], v[182:185], v[92:95]
	v_mfma_f32_16x16x32_bf16 v[72:75], v[142:145], v[214:217], v[72:75]
	v_mfma_f32_16x16x32_bf16 v[76:79], v[150:153], v[214:217], v[76:79]
	v_mfma_f32_16x16x32_bf16 v[120:123], v[146:149], v[162:165], v[120:123]
	v_mfma_f32_16x16x32_bf16 v[124:127], v[154:157], v[162:165], v[124:127]
	v_mfma_f32_16x16x32_bf16 v[104:107], v[146:149], v[170:173], v[104:107]
	v_mfma_f32_16x16x32_bf16 v[108:111], v[154:157], v[170:173], v[108:111]
	v_mfma_f32_16x16x32_bf16 v[88:91], v[146:149], v[186:189], v[88:91]
	v_mfma_f32_16x16x32_bf16 v[92:95], v[154:157], v[186:189], v[92:95]
	v_mfma_f32_16x16x32_bf16 v[72:75], v[146:149], v[218:221], v[72:75]
	v_mfma_f32_16x16x32_bf16 v[76:79], v[154:157], v[218:221], v[76:79]
	s_barrier
	s_add_i32 s16, 0, 0x1c000
	s_add_i32 s17, s24, s58
	v_add_u32_e32 v141, s16, v139
	v_lshl_add_u64 v[136:137], v[136:137], 0, s[64:65]
	s_mov_b32 m0, s17
	ds_read_b128 v[222:225], v141
	ds_read_b128 v[226:229], v141 offset:1024
	ds_read_b128 v[230:233], v141 offset:2048
	ds_read_b128 v[234:237], v141 offset:3072
	global_load_lds_dwordx4 v[136:137], off
	v_lshl_add_u64 v[136:137], v[174:175], 0, s[64:65]
	s_add_i32 m0, s17, 0x2000
	s_nop 0
	global_load_lds_dwordx4 v[136:137], off
	s_barrier
	s_waitcnt lgkmcnt(0)
	s_waitcnt lgkmcnt(0)
	v_mfma_f32_16x16x32_bf16 v[112:115], v[222:225], v[158:161], v[112:115]
	v_mfma_f32_16x16x32_bf16 v[116:119], v[230:233], v[158:161], v[116:119]
	v_mfma_f32_16x16x32_bf16 v[96:99], v[222:225], v[166:169], v[96:99]
	v_mfma_f32_16x16x32_bf16 v[100:103], v[230:233], v[166:169], v[100:103]
	v_mfma_f32_16x16x32_bf16 v[80:83], v[222:225], v[182:185], v[80:83]
	v_mfma_f32_16x16x32_bf16 v[84:87], v[230:233], v[182:185], v[84:87]
	v_mfma_f32_16x16x32_bf16 v[64:67], v[222:225], v[214:217], v[64:67]
	v_mfma_f32_16x16x32_bf16 v[68:71], v[230:233], v[214:217], v[68:71]
	v_mfma_f32_16x16x32_bf16 v[112:115], v[226:229], v[162:165], v[112:115]
	v_mfma_f32_16x16x32_bf16 v[116:119], v[234:237], v[162:165], v[116:119]
	v_mfma_f32_16x16x32_bf16 v[96:99], v[226:229], v[170:173], v[96:99]
	v_mfma_f32_16x16x32_bf16 v[100:103], v[234:237], v[170:173], v[100:103]
	v_mfma_f32_16x16x32_bf16 v[80:83], v[226:229], v[186:189], v[80:83]
	v_mfma_f32_16x16x32_bf16 v[84:87], v[234:237], v[186:189], v[84:87]
	v_mfma_f32_16x16x32_bf16 v[64:67], v[226:229], v[218:221], v[64:67]
	v_mfma_f32_16x16x32_bf16 v[68:71], v[234:237], v[218:221], v[68:71]
	s_mov_b32 m0, s89
	v_lshl_add_u64 v[136:137], v[190:191], 0, s[64:65]
	s_barrier
	ds_read_b128 v[158:161], v140 offset:49152
	ds_read_b128 v[162:165], v140 offset:50176
	ds_read_b128 v[166:169], v140 offset:51200
	ds_read_b128 v[170:173], v140 offset:52224
	ds_read_b128 v[182:185], v140 offset:53248
	ds_read_b128 v[186:189], v140 offset:54272
	ds_read_b128 v[214:217], v140 offset:55296
	ds_read_b128 v[218:221], v140 offset:56320
	global_load_lds_dwordx4 v[136:137], off
	v_lshl_add_u64 v[136:137], v[238:239], 0, s[64:65]
	s_mov_b32 m0, s92
	s_nop 0
	global_load_lds_dwordx4 v[136:137], off
	s_barrier
; __device__ __forceinline__ u32x4 mk4(unsigned a, unsigned b, unsigned c, unsigned d) { return (u32x4){a, b, c, d}; }
; __device__ __forceinline__ float silu_f(float x) { return x * __builtin_amdgcn_rcpf(1.f + __expf(-x)); }
; #define G_STAGE(bufoff, gbase) do { _Pragma("unroll") for (int _i = 0; _i < 2; ++_i) \
;     __builtin_amdgcn_global_load_lds((const unsigned*)((const char*)(gbase) + voff[_i]), (GLAS unsigned*)(lds + (bufoff) + ldsw + _i * 8192), 16, 0, 0); } while (0)
; #define G_LDA(dst, b, h) do { _Pragma("unroll") for (int m = 0; m < 4; ++m) _Pragma("unroll") for (int k = 0; k < 2; ++k) \
;     dst[m][k] = *(const GLAS bf16x8*)(lds + G_SA(b, h) + aoff + m * 2048 + k * 1024); } while (0)
; #define G_MMA(ai, bj, At_, Bt_) do { __builtin_amdgcn_s_setprio(1); \
;     _Pragma("unroll") for (int m = 0; m < 4; ++m) _Pragma("unroll") for (int n = 0; n < 2; ++n) _Pragma("unroll") for (int k = 0; k < 2; ++k) \
;       acc[ai][bj][m][n] = __builtin_amdgcn_mfma_f32_16x16x32_bf16(Bt_[n][k], At_[m][k], acc[ai][bj][m][n], 0, 0, 0); \
;     __builtin_amdgcn_s_setprio(0); } while (0)
; #define G_WAIT_V(n) asm volatile("s_waitcnt vmcnt(" #n ")" ::: "memory")
; #define G_BAR __builtin_amdgcn_s_barrier()
; __device__ __forceinline__ void gemm_phase(const Params& p, int l, const bf16_t* __restrict__ A, const bf16_t* __restrict__ Bt, int M, int N, int K,
;                            int epi, bf16_t* __restrict__ outp, char* smem, int wvi) {
;     ...
;         G_BAR; G_WAIT_L(0); G_MMA(0, 1, At, B1); G_BAR;
;         G_LDA(At, 1, 1); G_STAGE(G_SA(1, 0), a3);
;         G_BAR; G_WAIT_L(0); G_MMA(1, 0, At, B0); G_BAR; G_SCHED;
;         G_STAGE(G_SB(1, 1), b3 + hstep);
;         G_WAIT_V(6); G_BAR; G_MMA(1, 1, At, B1); G_BAR;
;     ...
;       for (int ai = 0; ai < 2; ++ai)
; #pragma unroll
;         for (int m = 0; m < 4; ++m) {
;           bf16_t* rp = outp + (size_t)(r0 + ai * GHALF + m * 16) * DFF + pn * 128 + wc * 32 + fq * 8;
;           unsigned pk[4];
; #pragma unroll
;           for (int bj = 0; bj < 2; ++bj) {
;             const f32x4 g = acc[ai][bj][m][0], u = acc[ai][bj][m][1];
;             const float o0 = silu_f(g[0]) * u[0], o1 = silu_f(g[1]) * u[1], o2 = silu_f(g[2]) * u[2], o3 = silu_f(g[3]) * u[3];
;             pk[2 * bj] = pk2(o0, o1); pk[2 * bj + 1] = pk2(o2, o3);
;           }
;           *reinterpret_cast<u32x4*>(rp) = mk4(pk[0], pk[1], pk[2], pk[3]);
;         }
	s_waitcnt lgkmcnt(0)
	s_waitcnt lgkmcnt(0)
	v_mfma_f32_16x16x32_bf16 v[56:59], v[142:145], v[158:161], v[56:59]
	v_mfma_f32_16x16x32_bf16 v[60:63], v[150:153], v[158:161], v[60:63]
	v_mfma_f32_16x16x32_bf16 v[40:43], v[142:145], v[166:169], v[40:43]
	v_mfma_f32_16x16x32_bf16 v[44:47], v[150:153], v[166:169], v[44:47]
	v_mfma_f32_16x16x32_bf16 v[24:27], v[142:145], v[182:185], v[24:27]
	v_mfma_f32_16x16x32_bf16 v[28:31], v[150:153], v[182:185], v[28:31]
	v_mfma_f32_16x16x32_bf16 v[8:11], v[142:145], v[214:217], v[8:11]
	v_mfma_f32_16x16x32_bf16 v[12:15], v[150:153], v[214:217], v[12:15]
	v_mfma_f32_16x16x32_bf16 v[56:59], v[146:149], v[162:165], v[56:59]
	v_mfma_f32_16x16x32_bf16 v[60:63], v[154:157], v[162:165], v[60:63]
	v_mfma_f32_16x16x32_bf16 v[40:43], v[146:149], v[170:173], v[40:43]
	v_mfma_f32_16x16x32_bf16 v[44:47], v[154:157], v[170:173], v[44:47]
	v_mfma_f32_16x16x32_bf16 v[24:27], v[146:149], v[186:189], v[24:27]
	v_mfma_f32_16x16x32_bf16 v[28:31], v[154:157], v[186:189], v[28:31]
	v_mfma_f32_16x16x32_bf16 v[8:11], v[146:149], v[218:221], v[8:11]
	v_mfma_f32_16x16x32_bf16 v[12:15], v[154:157], v[218:221], v[12:15]
	s_barrier
	s_add_u32 s14, s14, 0x40080
	s_addc_u32 s15, s15, 0
	s_add_i32 s16, s16, s58
	v_lshl_add_u64 v[136:137], s[14:15], 0, v[176:177]
	s_mov_b32 m0, s16
	s_nop 0
	global_load_lds_dwordx4 v[136:137], off
	v_lshl_add_u64 v[136:137], s[14:15], 0, v[128:129]
	s_add_i32 m0, s16, 0x2000
	s_nop 0
	global_load_lds_dwordx4 v[136:137], off
	s_waitcnt vmcnt(6)
	s_barrier
	v_mfma_f32_16x16x32_bf16 v[48:51], v[222:225], v[158:161], v[48:51]
	v_mfma_f32_16x16x32_bf16 v[52:55], v[230:233], v[158:161], v[52:55]
	v_mfma_f32_16x16x32_bf16 v[32:35], v[222:225], v[166:169], v[32:35]
	v_mfma_f32_16x16x32_bf16 v[36:39], v[230:233], v[166:169], v[36:39]
	v_mfma_f32_16x16x32_bf16 v[16:19], v[222:225], v[182:185], v[16:19]
	v_mfma_f32_16x16x32_bf16 v[20:23], v[230:233], v[182:185], v[20:23]
	v_mfma_f32_16x16x32_bf16 v[0:3], v[222:225], v[214:217], v[0:3]
	v_mfma_f32_16x16x32_bf16 v[4:7], v[230:233], v[214:217], v[4:7]
	v_mfma_f32_16x16x32_bf16 v[48:51], v[226:229], v[162:165], v[48:51]
	v_mfma_f32_16x16x32_bf16 v[52:55], v[234:237], v[162:165], v[52:55]
	v_mfma_f32_16x16x32_bf16 v[32:35], v[226:229], v[170:173], v[32:35]
	v_mfma_f32_16x16x32_bf16 v[36:39], v[234:237], v[170:173], v[36:39]
	v_mfma_f32_16x16x32_bf16 v[16:19], v[226:229], v[186:189], v[16:19]
	v_mfma_f32_16x16x32_bf16 v[20:23], v[234:237], v[186:189], v[20:23]
	v_mfma_f32_16x16x32_bf16 v[0:3], v[226:229], v[218:221], v[0:3]
	v_mfma_f32_16x16x32_bf16 v[4:7], v[234:237], v[218:221], v[4:7]
	s_add_i32 s23, s23, 2
	s_add_u32 s21, s21, 0x100
	s_addc_u32 s22, s22, 0
	s_cmp_gt_u32 s23, 13
	s_mov_b64 s[16:17], s[2:3]
	s_barrier
	s_cbranch_scc0 .LBB0_1199
	v_mul_f32_e32 v142, 0xbfb8aa3b, v120
	v_mul_f32_e32 v143, 0xbfb8aa3b, v121
	v_exp_f32_e32 v142, v142
	v_exp_f32_e32 v143, v143
	v_lshl_add_u32 v141, s0, 8, v138
	s_lshl_b32 s0, s1, 7
	v_add_f32_e32 v142, 1.0, v142
	v_add_f32_e32 v143, 1.0, v143
	v_rcp_f32_e32 v142, v142
	v_rcp_f32_e32 v143, v143
	s_ashr_i32 s1, s0, 31
	v_lshl_add_u64 v[136:137], s[0:1], 1, v[130:131]
	s_movk_i32 s2, 0x1600
	v_pk_mul_f32 v[120:121], v[120:121], v[142:143]
	s_and_b64 vcc, exec, s[12:13]
	v_pk_mul_f32 v[120:121], v[124:125], v[120:121]
	v_mul_f32_e32 v124, 0xbfb8aa3b, v122
	v_mul_f32_e32 v125, 0xbfb8aa3b, v123
	v_exp_f32_e32 v124, v124
	v_exp_f32_e32 v125, v125
	v_cvt_pk_bf16_f32 v120, v120, v121
	v_add_f32_e32 v124, 1.0, v124
	v_add_f32_e32 v125, 1.0, v125
	v_rcp_f32_e32 v124, v124
	v_rcp_f32_e32 v125, v125
	s_nop 0
	v_pk_mul_f32 v[122:123], v[122:123], v[124:125]
	s_nop 0
	v_pk_mul_f32 v[122:123], v[126:127], v[122:123]
	s_nop 0
	v_cvt_pk_bf16_f32 v121, v122, v123
	v_mul_f32_e32 v122, 0xbfb8aa3b, v112
	v_mul_f32_e32 v123, 0xbfb8aa3b, v113
	v_exp_f32_e32 v122, v122
	v_exp_f32_e32 v123, v123
	v_add_f32_e32 v122, 1.0, v122
	v_add_f32_e32 v123, 1.0, v123
	v_rcp_f32_e32 v122, v122
	v_rcp_f32_e32 v123, v123
	s_nop 0
	v_pk_mul_f32 v[112:113], v[112:113], v[122:123]
	s_nop 0
	v_pk_mul_f32 v[112:113], v[116:117], v[112:113]
	v_mul_f32_e32 v116, 0xbfb8aa3b, v114
	v_mul_f32_e32 v117, 0xbfb8aa3b, v115
	v_exp_f32_e32 v116, v116
	v_exp_f32_e32 v117, v117
	v_cvt_pk_bf16_f32 v122, v112, v113
	v_mad_i64_i32 v[112:113], s[0:1], v141, s2, v[136:137]
	v_add_f32_e32 v116, 1.0, v116
	v_add_f32_e32 v117, 1.0, v117
	v_rcp_f32_e32 v116, v116
	v_rcp_f32_e32 v117, v117
	s_nop 0
	v_pk_mul_f32 v[114:115], v[114:115], v[116:117]
	s_nop 0
	v_pk_mul_f32 v[114:115], v[118:119], v[114:115]
	s_nop 0
	v_cvt_pk_bf16_f32 v123, v114, v115
	global_store_dwordx4 v[112:113], v[120:123], off
	v_mul_f32_e32 v112, 0xbfb8aa3b, v104
	v_mul_f32_e32 v113, 0xbfb8aa3b, v105
	v_exp_f32_e32 v112, v112
	v_exp_f32_e32 v113, v113
	v_or_b32_e32 v114, 16, v141
	v_add_f32_e32 v112, 1.0, v112
	v_add_f32_e32 v113, 1.0, v113
	v_rcp_f32_e32 v112, v112
	v_rcp_f32_e32 v113, v113
	s_nop 0
	v_pk_mul_f32 v[104:105], v[104:105], v[112:113]
	s_nop 0
	v_pk_mul_f32 v[104:105], v[108:109], v[104:105]
	v_mul_f32_e32 v108, 0xbfb8aa3b, v106
	v_mul_f32_e32 v109, 0xbfb8aa3b, v107
	v_exp_f32_e32 v108, v108
	v_exp_f32_e32 v109, v109
	v_cvt_pk_bf16_f32 v104, v104, v105
	v_add_f32_e32 v108, 1.0, v108
	v_add_f32_e32 v109, 1.0, v109
	v_rcp_f32_e32 v108, v108
	v_rcp_f32_e32 v109, v109
	s_nop 0
	v_pk_mul_f32 v[106:107], v[106:107], v[108:109]
	s_nop 0
	v_pk_mul_f32 v[106:107], v[110:111], v[106:107]
	s_nop 0
	v_cvt_pk_bf16_f32 v105, v106, v107
	v_mul_f32_e32 v106, 0xbfb8aa3b, v96
	v_mul_f32_e32 v107, 0xbfb8aa3b, v97
	v_exp_f32_e32 v106, v106
	v_exp_f32_e32 v107, v107
	v_add_f32_e32 v106, 1.0, v106
	v_add_f32_e32 v107, 1.0, v107
; __device__ __forceinline__ u32x4 mk4(unsigned a, unsigned b, unsigned c, unsigned d) { return (u32x4){a, b, c, d}; }
; __device__ __forceinline__ float silu_f(float x) { return x * __builtin_amdgcn_rcpf(1.f + __expf(-x)); }
; __device__ __forceinline__ void gemm_phase(const Params& p, int l, const bf16_t* __restrict__ A, const bf16_t* __restrict__ Bt, int M, int N, int K,
;                            int epi, bf16_t* __restrict__ outp, char* smem, int wvi) {
;     ...
;       for (int ai = 0; ai < 2; ++ai)
; #pragma unroll
;         for (int m = 0; m < 4; ++m) {
;           bf16_t* rp = outp + (size_t)(r0 + ai * GHALF + m * 16) * DFF + pn * 128 + wc * 32 + fq * 8;
;           unsigned pk[4];
; #pragma unroll
;           for (int bj = 0; bj < 2; ++bj) {
;             const f32x4 g = acc[ai][bj][m][0], u = acc[ai][bj][m][1];
;             const float o0 = silu_f(g[0]) * u[0], o1 = silu_f(g[1]) * u[1], o2 = silu_f(g[2]) * u[2], o3 = silu_f(g[3]) * u[3];
;             pk[2 * bj] = pk2(o0, o1); pk[2 * bj + 1] = pk2(o2, o3);
;           }
;           *reinterpret_cast<u32x4*>(rp) = mk4(pk[0], pk[1], pk[2], pk[3]);
;         }
	v_rcp_f32_e32 v106, v106
	v_rcp_f32_e32 v107, v107
	s_nop 0
	v_pk_mul_f32 v[96:97], v[96:97], v[106:107]
	s_nop 0
	v_pk_mul_f32 v[96:97], v[100:101], v[96:97]
	v_mul_f32_e32 v100, 0xbfb8aa3b, v98
	v_mul_f32_e32 v101, 0xbfb8aa3b, v99
	v_exp_f32_e32 v100, v100
	v_exp_f32_e32 v101, v101
	v_cvt_pk_bf16_f32 v106, v96, v97
	v_mad_i64_i32 v[96:97], s[0:1], v114, s2, v[136:137]
	v_add_f32_e32 v100, 1.0, v100
	v_add_f32_e32 v101, 1.0, v101
	v_rcp_f32_e32 v100, v100
	v_rcp_f32_e32 v101, v101
	s_nop 0
	v_pk_mul_f32 v[98:99], v[98:99], v[100:101]
	s_nop 0
	v_pk_mul_f32 v[98:99], v[102:103], v[98:99]
	s_nop 0
	v_cvt_pk_bf16_f32 v107, v98, v99
	global_store_dwordx4 v[96:97], v[104:107], off
	v_mul_f32_e32 v96, 0xbfb8aa3b, v88
	v_mul_f32_e32 v97, 0xbfb8aa3b, v89
	v_exp_f32_e32 v96, v96
	v_exp_f32_e32 v97, v97
	v_or_b32_e32 v98, 32, v141
	v_add_f32_e32 v96, 1.0, v96
	v_add_f32_e32 v97, 1.0, v97
	v_rcp_f32_e32 v96, v96
	v_rcp_f32_e32 v97, v97
	s_nop 0
	v_pk_mul_f32 v[88:89], v[88:89], v[96:97]
	s_nop 0
	v_pk_mul_f32 v[88:89], v[92:93], v[88:89]
	v_mul_f32_e32 v92, 0xbfb8aa3b, v90
	v_mul_f32_e32 v93, 0xbfb8aa3b, v91
	v_exp_f32_e32 v92, v92
	v_exp_f32_e32 v93, v93
	v_cvt_pk_bf16_f32 v88, v88, v89
	v_add_f32_e32 v92, 1.0, v92
	v_add_f32_e32 v93, 1.0, v93
	v_rcp_f32_e32 v92, v92
	v_rcp_f32_e32 v93, v93
	s_nop 0
	v_pk_mul_f32 v[90:91], v[90:91], v[92:93]
	s_nop 0
	v_pk_mul_f32 v[90:91], v[94:95], v[90:91]
	s_nop 0
	v_cvt_pk_bf16_f32 v89, v90, v91
	v_mul_f32_e32 v90, 0xbfb8aa3b, v80
	v_mul_f32_e32 v91, 0xbfb8aa3b, v81
	v_exp_f32_e32 v90, v90
	v_exp_f32_e32 v91, v91
	v_add_f32_e32 v90, 1.0, v90
	v_add_f32_e32 v91, 1.0, v91
	v_rcp_f32_e32 v90, v90
	v_rcp_f32_e32 v91, v91
	s_nop 0
	v_pk_mul_f32 v[80:81], v[80:81], v[90:91]
	s_nop 0
	v_pk_mul_f32 v[80:81], v[84:85], v[80:81]
	v_mul_f32_e32 v84, 0xbfb8aa3b, v82
	v_mul_f32_e32 v85, 0xbfb8aa3b, v83
	v_exp_f32_e32 v84, v84
	v_exp_f32_e32 v85, v85
	v_cvt_pk_bf16_f32 v90, v80, v81
	v_mad_i64_i32 v[80:81], s[0:1], v98, s2, v[136:137]
	v_add_f32_e32 v84, 1.0, v84
	v_add_f32_e32 v85, 1.0, v85
	v_rcp_f32_e32 v84, v84
	v_rcp_f32_e32 v85, v85
	s_nop 0
	v_pk_mul_f32 v[82:83], v[82:83], v[84:85]
	s_nop 0
	v_pk_mul_f32 v[82:83], v[86:87], v[82:83]
	s_nop 0
	v_cvt_pk_bf16_f32 v91, v82, v83
	global_store_dwordx4 v[80:81], v[88:91], off
	v_mul_f32_e32 v80, 0xbfb8aa3b, v72
	v_mul_f32_e32 v81, 0xbfb8aa3b, v73
	v_exp_f32_e32 v80, v80
	v_exp_f32_e32 v81, v81
	v_or_b32_e32 v82, 48, v141
	v_add_f32_e32 v80, 1.0, v80
	v_add_f32_e32 v81, 1.0, v81
	v_rcp_f32_e32 v80, v80
	v_rcp_f32_e32 v81, v81
	s_nop 0
	v_pk_mul_f32 v[72:73], v[72:73], v[80:81]
	s_nop 0
	v_pk_mul_f32 v[72:73], v[76:77], v[72:73]
	v_mul_f32_e32 v76, 0xbfb8aa3b, v74
	v_mul_f32_e32 v77, 0xbfb8aa3b, v75
	v_exp_f32_e32 v76, v76
	v_exp_f32_e32 v77, v77
	v_cvt_pk_bf16_f32 v72, v72, v73
	v_add_f32_e32 v76, 1.0, v76
	v_add_f32_e32 v77, 1.0, v77
	v_rcp_f32_e32 v76, v76
	v_rcp_f32_e32 v77, v77
	s_nop 0
	v_pk_mul_f32 v[74:75], v[74:75], v[76:77]
	s_nop 0
	v_pk_mul_f32 v[74:75], v[78:79], v[74:75]
	s_nop 0
	v_cvt_pk_bf16_f32 v73, v74, v75
	v_mul_f32_e32 v74, 0xbfb8aa3b, v64
	v_mul_f32_e32 v75, 0xbfb8aa3b, v65
	v_exp_f32_e32 v74, v74
	v_exp_f32_e32 v75, v75
	v_add_f32_e32 v74, 1.0, v74
	v_add_f32_e32 v75, 1.0, v75
	v_rcp_f32_e32 v74, v74
	v_rcp_f32_e32 v75, v75
	s_nop 0
	v_pk_mul_f32 v[64:65], v[64:65], v[74:75]
	s_nop 0
	v_pk_mul_f32 v[64:65], v[68:69], v[64:65]
	v_mul_f32_e32 v68, 0xbfb8aa3b, v66
	v_mul_f32_e32 v69, 0xbfb8aa3b, v67
	v_exp_f32_e32 v68, v68
	v_exp_f32_e32 v69, v69
	v_cvt_pk_bf16_f32 v74, v64, v65
	v_mad_i64_i32 v[64:65], s[0:1], v82, s2, v[136:137]
	v_add_f32_e32 v68, 1.0, v68
	v_add_f32_e32 v69, 1.0, v69
	v_rcp_f32_e32 v68, v68
	v_rcp_f32_e32 v69, v69
	s_nop 0
	v_pk_mul_f32 v[66:67], v[66:67], v[68:69]
	s_nop 0
	v_pk_mul_f32 v[66:67], v[70:71], v[66:67]
	s_nop 0
	v_cvt_pk_bf16_f32 v75, v66, v67
	global_store_dwordx4 v[64:65], v[72:75], off
	v_mul_f32_e32 v64, 0xbfb8aa3b, v56
	v_mul_f32_e32 v65, 0xbfb8aa3b, v57
	v_exp_f32_e32 v64, v64
	v_exp_f32_e32 v65, v65
	v_add_u32_e32 v66, 0x80, v141
	v_add_f32_e32 v64, 1.0, v64
	v_add_f32_e32 v65, 1.0, v65
	v_rcp_f32_e32 v64, v64
	v_rcp_f32_e32 v65, v65
	s_nop 0
	v_pk_mul_f32 v[56:57], v[56:57], v[64:65]
	s_nop 0
	v_pk_mul_f32 v[56:57], v[60:61], v[56:57]
	v_mul_f32_e32 v60, 0xbfb8aa3b, v58
	v_mul_f32_e32 v61, 0xbfb8aa3b, v59
	v_exp_f32_e32 v60, v60
	v_exp_f32_e32 v61, v61
	v_cvt_pk_bf16_f32 v56, v56, v57
	v_add_f32_e32 v60, 1.0, v60
	v_add_f32_e32 v61, 1.0, v61
	v_rcp_f32_e32 v60, v60
	v_rcp_f32_e32 v61, v61
	s_nop 0
	v_pk_mul_f32 v[58:59], v[58:59], v[60:61]
	s_nop 0
	v_pk_mul_f32 v[58:59], v[62:63], v[58:59]
	s_nop 0
	v_cvt_pk_bf16_f32 v57, v58, v59
	v_mul_f32_e32 v58, 0xbfb8aa3b, v48
	v_mul_f32_e32 v59, 0xbfb8aa3b, v49
	v_exp_f32_e32 v58, v58
	v_exp_f32_e32 v59, v59
	v_add_f32_e32 v58, 1.0, v58
	v_add_f32_e32 v59, 1.0, v59
	v_rcp_f32_e32 v58, v58
	v_rcp_f32_e32 v59, v59
	s_nop 0
	v_pk_mul_f32 v[48:49], v[48:49], v[58:59]
	s_nop 0
	v_pk_mul_f32 v[48:49], v[52:53], v[48:49]
	v_mul_f32_e32 v52, 0xbfb8aa3b, v50
	v_mul_f32_e32 v53, 0xbfb8aa3b, v51
	v_exp_f32_e32 v52, v52
	v_exp_f32_e32 v53, v53
	v_cvt_pk_bf16_f32 v58, v48, v49
	v_mad_i64_i32 v[48:49], s[0:1], v66, s2, v[136:137]
	v_add_f32_e32 v52, 1.0, v52
	v_add_f32_e32 v53, 1.0, v53
	v_rcp_f32_e32 v52, v52
	v_rcp_f32_e32 v53, v53
	s_nop 0
	v_pk_mul_f32 v[50:51], v[50:51], v[52:53]
	s_nop 0
	v_pk_mul_f32 v[50:51], v[54:55], v[50:51]
	s_nop 0
	v_cvt_pk_bf16_f32 v59, v50, v51
	global_store_dwordx4 v[48:49], v[56:59], off
	v_mul_f32_e32 v48, 0xbfb8aa3b, v40
	v_mul_f32_e32 v49, 0xbfb8aa3b, v41
	v_exp_f32_e32 v48, v48
	v_exp_f32_e32 v49, v49
	v_add_u32_e32 v50, 0x90, v141
; __device__ __forceinline__ u32x4 mk4(unsigned a, unsigned b, unsigned c, unsigned d) { return (u32x4){a, b, c, d}; }
; __device__ __forceinline__ float silu_f(float x) { return x * __builtin_amdgcn_rcpf(1.f + __expf(-x)); }
; __device__ __forceinline__ void gemm_phase(const Params& p, int l, const bf16_t* __restrict__ A, const bf16_t* __restrict__ Bt, int M, int N, int K,
;                            int epi, bf16_t* __restrict__ outp, char* smem, int wvi) {
;     ...
;       for (int ai = 0; ai < 2; ++ai)
; #pragma unroll
;         for (int m = 0; m < 4; ++m) {
;           bf16_t* rp = outp + (size_t)(r0 + ai * GHALF + m * 16) * DFF + pn * 128 + wc * 32 + fq * 8;
;           unsigned pk[4];
; #pragma unroll
;           for (int bj = 0; bj < 2; ++bj) {
;             const f32x4 g = acc[ai][bj][m][0], u = acc[ai][bj][m][1];
;             const float o0 = silu_f(g[0]) * u[0], o1 = silu_f(g[1]) * u[1], o2 = silu_f(g[2]) * u[2], o3 = silu_f(g[3]) * u[3];
;             pk[2 * bj] = pk2(o0, o1); pk[2 * bj + 1] = pk2(o2, o3);
;           }
;           *reinterpret_cast<u32x4*>(rp) = mk4(pk[0], pk[1], pk[2], pk[3]);
;         }
	v_add_f32_e32 v48, 1.0, v48
	v_add_f32_e32 v49, 1.0, v49
	v_rcp_f32_e32 v48, v48
	v_rcp_f32_e32 v49, v49
	s_nop 0
	v_pk_mul_f32 v[40:41], v[40:41], v[48:49]
	s_nop 0
	v_pk_mul_f32 v[40:41], v[44:45], v[40:41]
	v_mul_f32_e32 v44, 0xbfb8aa3b, v42
	v_mul_f32_e32 v45, 0xbfb8aa3b, v43
	v_exp_f32_e32 v44, v44
	v_exp_f32_e32 v45, v45
	v_cvt_pk_bf16_f32 v40, v40, v41
	v_add_f32_e32 v44, 1.0, v44
	v_add_f32_e32 v45, 1.0, v45
	v_rcp_f32_e32 v44, v44
	v_rcp_f32_e32 v45, v45
	s_nop 0
	v_pk_mul_f32 v[42:43], v[42:43], v[44:45]
	s_nop 0
	v_pk_mul_f32 v[42:43], v[46:47], v[42:43]
	s_nop 0
	v_cvt_pk_bf16_f32 v41, v42, v43
	v_mul_f32_e32 v42, 0xbfb8aa3b, v32
	v_mul_f32_e32 v43, 0xbfb8aa3b, v33
	v_exp_f32_e32 v42, v42
	v_exp_f32_e32 v43, v43
	v_add_f32_e32 v42, 1.0, v42
	v_add_f32_e32 v43, 1.0, v43
	v_rcp_f32_e32 v42, v42
	v_rcp_f32_e32 v43, v43
	s_nop 0
	v_pk_mul_f32 v[32:33], v[32:33], v[42:43]
	s_nop 0
	v_pk_mul_f32 v[32:33], v[36:37], v[32:33]
	v_mul_f32_e32 v36, 0xbfb8aa3b, v34
	v_mul_f32_e32 v37, 0xbfb8aa3b, v35
	v_exp_f32_e32 v36, v36
	v_exp_f32_e32 v37, v37
	v_cvt_pk_bf16_f32 v42, v32, v33
	v_mad_i64_i32 v[32:33], s[0:1], v50, s2, v[136:137]
	v_add_f32_e32 v36, 1.0, v36
	v_add_f32_e32 v37, 1.0, v37
	v_rcp_f32_e32 v36, v36
	v_rcp_f32_e32 v37, v37
	s_nop 0
	v_pk_mul_f32 v[34:35], v[34:35], v[36:37]
	s_nop 0
	v_pk_mul_f32 v[34:35], v[38:39], v[34:35]
	s_nop 0
	v_cvt_pk_bf16_f32 v43, v34, v35
	global_store_dwordx4 v[32:33], v[40:43], off
	v_mul_f32_e32 v32, 0xbfb8aa3b, v24
	v_mul_f32_e32 v33, 0xbfb8aa3b, v25
	v_exp_f32_e32 v32, v32
	v_exp_f32_e32 v33, v33
	v_add_u32_e32 v34, 0xa0, v141
	v_add_f32_e32 v32, 1.0, v32
	v_add_f32_e32 v33, 1.0, v33
	v_rcp_f32_e32 v32, v32
	v_rcp_f32_e32 v33, v33
	s_nop 0
	v_pk_mul_f32 v[24:25], v[24:25], v[32:33]
	s_nop 0
	v_pk_mul_f32 v[24:25], v[28:29], v[24:25]
	v_mul_f32_e32 v28, 0xbfb8aa3b, v26
	v_mul_f32_e32 v29, 0xbfb8aa3b, v27
	v_exp_f32_e32 v28, v28
	v_exp_f32_e32 v29, v29
	v_cvt_pk_bf16_f32 v24, v24, v25
	v_add_f32_e32 v28, 1.0, v28
	v_add_f32_e32 v29, 1.0, v29
	v_rcp_f32_e32 v28, v28
	v_rcp_f32_e32 v29, v29
	s_nop 0
	v_pk_mul_f32 v[26:27], v[26:27], v[28:29]
	s_nop 0
	v_pk_mul_f32 v[26:27], v[30:31], v[26:27]
	s_nop 0
	v_cvt_pk_bf16_f32 v25, v26, v27
	v_mul_f32_e32 v26, 0xbfb8aa3b, v16
	v_mul_f32_e32 v27, 0xbfb8aa3b, v17
	v_exp_f32_e32 v26, v26
	v_exp_f32_e32 v27, v27
	v_add_f32_e32 v26, 1.0, v26
	v_add_f32_e32 v27, 1.0, v27
	v_rcp_f32_e32 v26, v26
	v_rcp_f32_e32 v27, v27
	s_nop 0
	v_pk_mul_f32 v[16:17], v[16:17], v[26:27]
	s_nop 0
	v_pk_mul_f32 v[16:17], v[20:21], v[16:17]
	v_mul_f32_e32 v20, 0xbfb8aa3b, v18
	v_mul_f32_e32 v21, 0xbfb8aa3b, v19
	v_exp_f32_e32 v20, v20
	v_exp_f32_e32 v21, v21
	v_cvt_pk_bf16_f32 v26, v16, v17
	v_mad_i64_i32 v[16:17], s[0:1], v34, s2, v[136:137]
	v_add_f32_e32 v20, 1.0, v20
	v_add_f32_e32 v21, 1.0, v21
	v_rcp_f32_e32 v20, v20
	v_rcp_f32_e32 v21, v21
	s_nop 0
	v_pk_mul_f32 v[18:19], v[18:19], v[20:21]
	s_nop 0
	v_pk_mul_f32 v[18:19], v[22:23], v[18:19]
	s_nop 0
	v_cvt_pk_bf16_f32 v27, v18, v19
	global_store_dwordx4 v[16:17], v[24:27], off
	v_mul_f32_e32 v16, 0xbfb8aa3b, v8
	v_mul_f32_e32 v17, 0xbfb8aa3b, v9
	v_exp_f32_e32 v16, v16
	v_exp_f32_e32 v17, v17
	v_add_u32_e32 v18, 0xb0, v141
	v_add_f32_e32 v16, 1.0, v16
	v_add_f32_e32 v17, 1.0, v17
	v_rcp_f32_e32 v16, v16
	v_rcp_f32_e32 v17, v17
	s_nop 0
	v_pk_mul_f32 v[8:9], v[8:9], v[16:17]
	s_nop 0
	v_pk_mul_f32 v[8:9], v[12:13], v[8:9]
	v_mul_f32_e32 v12, 0xbfb8aa3b, v10
	v_mul_f32_e32 v13, 0xbfb8aa3b, v11
	v_exp_f32_e32 v12, v12
	v_exp_f32_e32 v13, v13
	v_cvt_pk_bf16_f32 v8, v8, v9
	v_add_f32_e32 v12, 1.0, v12
	v_add_f32_e32 v13, 1.0, v13
	v_rcp_f32_e32 v12, v12
	v_rcp_f32_e32 v13, v13
	s_nop 0
	v_pk_mul_f32 v[10:11], v[10:11], v[12:13]
	s_nop 0
	v_pk_mul_f32 v[10:11], v[14:15], v[10:11]
	s_nop 0
	v_cvt_pk_bf16_f32 v9, v10, v11
	v_mul_f32_e32 v10, 0xbfb8aa3b, v0
	v_mul_f32_e32 v11, 0xbfb8aa3b, v1
	v_exp_f32_e32 v10, v10
	v_exp_f32_e32 v11, v11
	v_add_f32_e32 v10, 1.0, v10
	v_add_f32_e32 v11, 1.0, v11
	v_rcp_f32_e32 v10, v10
	v_rcp_f32_e32 v11, v11
	s_nop 0
	v_pk_mul_f32 v[0:1], v[0:1], v[10:11]
	s_nop 0
	v_pk_mul_f32 v[0:1], v[4:5], v[0:1]
	v_mul_f32_e32 v4, 0xbfb8aa3b, v2
	v_mul_f32_e32 v5, 0xbfb8aa3b, v3
	v_exp_f32_e32 v4, v4
	v_exp_f32_e32 v5, v5
	v_cvt_pk_bf16_f32 v10, v0, v1
	v_mad_i64_i32 v[0:1], s[0:1], v18, s2, v[136:137]
	v_add_f32_e32 v4, 1.0, v4
	v_add_f32_e32 v5, 1.0, v5
	v_rcp_f32_e32 v4, v4
	v_rcp_f32_e32 v5, v5
	s_mov_b64 s[2:3], -1
	v_pk_mul_f32 v[2:3], v[2:3], v[4:5]
	s_nop 0
	v_pk_mul_f32 v[2:3], v[6:7], v[2:3]
	s_nop 0
	v_cvt_pk_bf16_f32 v11, v2, v3
	global_store_dwordx4 v[0:1], v[8:11], off
	s_cbranch_vccz .LBB0_1195
; __device__ __forceinline__ f32x4 zero4() { float z = 0.f; asm volatile("" : "+v"(z)); return (f32x4){z, z, z, z}; }
; __device__ __forceinline__ void gemm_phase(const Params& p, int l, const bf16_t* __restrict__ A, const bf16_t* __restrict__ Bt, int M, int N, int K,
;                            int epi, bf16_t* __restrict__ outp, char* smem, int wvi) {
;     ...
; #pragma unroll
;       for (int a = 0; a < 2; ++a)
; #pragma unroll
;         for (int b = 0; b < 2; ++b)
; #pragma unroll
;           for (int m = 0; m < 4; ++m)
; #pragma unroll
;             for (int n = 0; n < 2; ++n) acc[a][b][m][n] = zero4();
;       Lw = Ln; pm = npm; pn = npn; cA = nA; cB = nB;
	v_mov_b32_e32 v120, v177
	v_mov_b32_e32 v124, v177
	v_mov_b32_e32 v104, v177
	v_mov_b32_e32 v108, v177
	v_mov_b32_e32 v88, v177
	v_mov_b32_e32 v92, v177
	v_mov_b32_e32 v72, v177
	v_mov_b32_e32 v76, v177
	v_mov_b32_e32 v112, v177
	v_mov_b32_e32 v116, v177
	v_mov_b32_e32 v96, v177
	v_mov_b32_e32 v100, v177
	v_mov_b32_e32 v80, v177
	v_mov_b32_e32 v84, v177
	v_mov_b32_e32 v64, v177
	v_mov_b32_e32 v68, v177
	v_mov_b32_e32 v56, v177
	v_mov_b32_e32 v60, v177
	v_mov_b32_e32 v40, v177
	v_mov_b32_e32 v44, v177
	v_mov_b32_e32 v24, v177
	v_mov_b32_e32 v28, v177
	v_mov_b32_e32 v8, v177
	v_mov_b32_e32 v12, v177
	v_mov_b32_e32 v48, v177
	v_mov_b32_e32 v52, v177
	v_mov_b32_e32 v32, v177
	v_mov_b32_e32 v36, v177
	v_mov_b32_e32 v16, v177
	v_mov_b32_e32 v20, v177
	v_mov_b32_e32 v0, v177
	v_mov_b32_e32 v4, v177
	s_nop 0
	v_mov_b32_e32 v121, v120
	v_mov_b32_e32 v122, v120
	v_mov_b32_e32 v123, v120
	v_mov_b32_e32 v125, v124
	v_mov_b32_e32 v126, v124
	v_mov_b32_e32 v127, v124
	v_mov_b32_e32 v105, v104
	v_mov_b32_e32 v106, v104
	v_mov_b32_e32 v107, v104
	v_mov_b32_e32 v109, v108
	v_mov_b32_e32 v110, v108
	v_mov_b32_e32 v111, v108
	v_mov_b32_e32 v89, v88
	v_mov_b32_e32 v90, v88
	v_mov_b32_e32 v91, v88
	v_mov_b32_e32 v93, v92
	v_mov_b32_e32 v94, v92
	v_mov_b32_e32 v95, v92
	s_nop 0
	v_mov_b32_e32 v73, v72
	v_mov_b32_e32 v74, v72
	v_mov_b32_e32 v75, v72
	v_mov_b32_e32 v77, v76
	v_mov_b32_e32 v78, v76
	v_mov_b32_e32 v79, v76
	v_mov_b32_e32 v113, v112
	v_mov_b32_e32 v114, v112
	v_mov_b32_e32 v115, v112
	v_mov_b32_e32 v117, v116
	v_mov_b32_e32 v118, v116
	v_mov_b32_e32 v119, v116
	v_mov_b32_e32 v97, v96
	v_mov_b32_e32 v98, v96
	v_mov_b32_e32 v99, v96
	v_mov_b32_e32 v101, v100
	v_mov_b32_e32 v102, v100
	v_mov_b32_e32 v103, v100
	s_nop 0
	v_mov_b32_e32 v81, v80
	v_mov_b32_e32 v82, v80
	v_mov_b32_e32 v83, v80
	v_mov_b32_e32 v85, v84
	v_mov_b32_e32 v86, v84
	v_mov_b32_e32 v87, v84
	v_mov_b32_e32 v65, v64
	v_mov_b32_e32 v66, v64
	v_mov_b32_e32 v67, v64
	v_mov_b32_e32 v69, v68
	v_mov_b32_e32 v70, v68
	v_mov_b32_e32 v71, v68
	v_mov_b32_e32 v57, v56
	v_mov_b32_e32 v58, v56
	v_mov_b32_e32 v59, v56
	v_mov_b32_e32 v61, v60
	v_mov_b32_e32 v62, v60
	v_mov_b32_e32 v63, v60
	s_nop 0
	v_mov_b32_e32 v41, v40
	v_mov_b32_e32 v42, v40
	v_mov_b32_e32 v43, v40
	v_mov_b32_e32 v45, v44
	v_mov_b32_e32 v46, v44
	v_mov_b32_e32 v47, v44
	v_mov_b32_e32 v25, v24
	v_mov_b32_e32 v26, v24
	v_mov_b32_e32 v27, v24
	v_mov_b32_e32 v29, v28
	v_mov_b32_e32 v30, v28
	v_mov_b32_e32 v31, v28
	v_mov_b32_e32 v9, v8
	v_mov_b32_e32 v10, v8
	v_mov_b32_e32 v11, v8
	v_mov_b32_e32 v13, v12
	v_mov_b32_e32 v14, v12
	v_mov_b32_e32 v15, v12
	s_nop 0
	v_mov_b32_e32 v49, v48
	v_mov_b32_e32 v50, v48
	v_mov_b32_e32 v51, v48
	v_mov_b32_e32 v53, v52
	v_mov_b32_e32 v54, v52
	v_mov_b32_e32 v55, v52
	v_mov_b32_e32 v33, v32
	v_mov_b32_e32 v34, v32
	v_mov_b32_e32 v35, v32
	v_mov_b32_e32 v37, v36
	v_mov_b32_e32 v38, v36
	v_mov_b32_e32 v39, v36
	v_mov_b32_e32 v17, v16
	v_mov_b32_e32 v18, v16
	v_mov_b32_e32 v19, v16
	v_mov_b32_e32 v21, v20
	v_mov_b32_e32 v22, v20
	v_mov_b32_e32 v23, v20
	s_mov_b64 s[2:3], 0
	v_mov_b32_e32 v1, v0
	v_mov_b32_e32 v2, v0
	v_mov_b32_e32 v3, v0
	v_mov_b32_e32 v5, v4
	v_mov_b32_e32 v6, v4
	v_mov_b32_e32 v7, v4
	s_branch .LBB0_1195
